# v9 + closing barrier of each MFMA segment executed before its last 4 MFMAs
# baseline (speedup 1.0000x reference)
.LBB0_642:
	ds_read_b128 v[148:151], v139
	ds_read_b128 v[152:155], v139 offset:1024
	ds_read_b128 v[156:159], v139 offset:2048
	ds_read_b128 v[160:163], v139 offset:3072
	ds_read_b128 v[164:167], v140
	ds_read_b128 v[168:171], v140 offset:1024
	ds_read_b128 v[172:175], v140 offset:2048
	ds_read_b128 v[176:179], v140 offset:3072
	s_add_i32 s18, s71, 0xffe80080
	s_cmp_eq_u32 s58, s73
	s_cselect_b32 s74, s69, s18
	s_cselect_b32 s76, s70, s72
	s_or_b32 s75, s74, 0x80
	s_add_i32 s18, s71, 0xfff80000
	s_mov_b32 m0, s59
	ds_read_b128 v[180:183], v141
	ds_read_b128 v[184:187], v141 offset:1024
	ds_read_b128 v[188:191], v141 offset:2048
	ds_read_b128 v[192:195], v141 offset:3072
	ds_read_b128 v[196:199], v141 offset:4096
	ds_read_b128 v[200:203], v141 offset:5120
	ds_read_b128 v[204:207], v141 offset:6144
	ds_read_b128 v[208:211], v141 offset:7168
	buffer_load_dwordx4 v137, s[12:15], s18 offen lds
	s_mov_b32 m0, s60
	s_nop 0
	buffer_load_dwordx4 v137, s[12:15], s71 offen lds
	s_waitcnt vmcnt(8)
	s_waitcnt lgkmcnt(0)
	s_setprio 1
	v_mfma_f32_16x16x32_bf16 v[118:121], v[148:151], v[180:183], v[118:121]
	s_barrier
	v_mfma_f32_16x16x32_bf16 v[118:121], v[152:155], v[184:187], v[118:121]
	v_mfma_f32_16x16x32_bf16 v[114:117], v[156:159], v[180:183], v[114:117]
	v_mfma_f32_16x16x32_bf16 v[114:117], v[160:163], v[184:187], v[114:117]
	v_mfma_f32_16x16x32_bf16 v[110:113], v[148:151], v[188:191], v[110:113]
	v_mfma_f32_16x16x32_bf16 v[110:113], v[152:155], v[192:195], v[110:113]
	v_mfma_f32_16x16x32_bf16 v[102:105], v[156:159], v[188:191], v[102:105]
	v_mfma_f32_16x16x32_bf16 v[102:105], v[160:163], v[192:195], v[102:105]
	v_mfma_f32_16x16x32_bf16 v[94:97], v[148:151], v[196:199], v[94:97]
	v_mfma_f32_16x16x32_bf16 v[94:97], v[152:155], v[200:203], v[94:97]
	v_mfma_f32_16x16x32_bf16 v[86:89], v[156:159], v[196:199], v[86:89]
	v_mfma_f32_16x16x32_bf16 v[86:89], v[160:163], v[200:203], v[86:89]
	v_mfma_f32_16x16x32_bf16 v[78:81], v[148:151], v[204:207], v[78:81]
	v_mfma_f32_16x16x32_bf16 v[78:81], v[152:155], v[208:211], v[78:81]
	v_mfma_f32_16x16x32_bf16 v[66:69], v[156:159], v[204:207], v[66:69]
	v_mfma_f32_16x16x32_bf16 v[66:69], v[160:163], v[208:211], v[66:69]
	v_mfma_f32_16x16x32_bf16 v[126:129], v[164:167], v[180:183], v[126:129]
	v_mfma_f32_16x16x32_bf16 v[126:129], v[168:171], v[184:187], v[126:129]
	v_mfma_f32_16x16x32_bf16 v[122:125], v[172:175], v[180:183], v[122:125]
	v_mfma_f32_16x16x32_bf16 v[122:125], v[176:179], v[184:187], v[122:125]
	v_mfma_f32_16x16x32_bf16 v[106:109], v[164:167], v[188:191], v[106:109]
	v_mfma_f32_16x16x32_bf16 v[106:109], v[168:171], v[192:195], v[106:109]
	v_mfma_f32_16x16x32_bf16 v[98:101], v[172:175], v[188:191], v[98:101]
	v_mfma_f32_16x16x32_bf16 v[98:101], v[176:179], v[192:195], v[98:101]
	v_mfma_f32_16x16x32_bf16 v[90:93], v[164:167], v[196:199], v[90:93]
	v_mfma_f32_16x16x32_bf16 v[90:93], v[168:171], v[200:203], v[90:93]
	v_mfma_f32_16x16x32_bf16 v[82:85], v[172:175], v[196:199], v[82:85]
	v_mfma_f32_16x16x32_bf16 v[82:85], v[176:179], v[200:203], v[82:85]
	s_barrier
	v_mfma_f32_16x16x32_bf16 v[74:77], v[164:167], v[204:207], v[74:77]
	v_mfma_f32_16x16x32_bf16 v[74:77], v[168:171], v[208:211], v[74:77]
	v_mfma_f32_16x16x32_bf16 v[70:73], v[172:175], v[204:207], v[70:73]
	v_mfma_f32_16x16x32_bf16 v[70:73], v[176:179], v[208:211], v[70:73]
	s_setprio 0
	s_mov_b32 m0, s30
	s_mov_b32 s18, s14
	s_mov_b32 s19, s15
	ds_read_b128 v[180:183], v141 offset:16384
	ds_read_b128 v[184:187], v141 offset:17408
	ds_read_b128 v[188:191], v141 offset:18432
	ds_read_b128 v[192:195], v141 offset:19456
	ds_read_b128 v[196:199], v141 offset:20480
	ds_read_b128 v[200:203], v141 offset:21504
	ds_read_b128 v[204:207], v141 offset:22528
	ds_read_b128 v[208:211], v141 offset:23552
	buffer_load_dwordx4 v138, s[16:19], s76 offen lds
	s_add_i32 s77, s76, 0x80000
	s_mov_b32 m0, s31
	s_nop 0
	buffer_load_dwordx4 v138, s[16:19], s77 offen lds
	s_add_i32 s77, s76, 0x100000
	s_mov_b32 m0, s44
	s_nop 0
	buffer_load_dwordx4 v138, s[16:19], s77 offen lds
	s_add_i32 s77, s76, 0x180000
	s_mov_b32 m0, s45
	s_nop 0
	buffer_load_dwordx4 v138, s[16:19], s77 offen lds
	s_mov_b32 m0, s27
	s_add_i32 s77, s74, 0x80000
	buffer_load_dwordx4 v137, s[12:15], s74 offen lds
	s_mov_b32 m0, s46
	s_nop 0
	buffer_load_dwordx4 v137, s[12:15], s77 offen lds
	s_waitcnt vmcnt(8)
	s_waitcnt lgkmcnt(0)
	s_setprio 1
	v_mfma_f32_16x16x32_bf16 v[62:65], v[148:151], v[180:183], v[62:65]
	s_barrier
	v_mfma_f32_16x16x32_bf16 v[62:65], v[152:155], v[184:187], v[62:65]
	v_mfma_f32_16x16x32_bf16 v[54:57], v[156:159], v[180:183], v[54:57]
	v_mfma_f32_16x16x32_bf16 v[54:57], v[160:163], v[184:187], v[54:57]
	v_mfma_f32_16x16x32_bf16 v[46:49], v[148:151], v[188:191], v[46:49]
	v_mfma_f32_16x16x32_bf16 v[46:49], v[152:155], v[192:195], v[46:49]
	v_mfma_f32_16x16x32_bf16 v[38:41], v[156:159], v[188:191], v[38:41]
	v_mfma_f32_16x16x32_bf16 v[38:41], v[160:163], v[192:195], v[38:41]
	v_mfma_f32_16x16x32_bf16 v[30:33], v[148:151], v[196:199], v[30:33]
	v_mfma_f32_16x16x32_bf16 v[30:33], v[152:155], v[200:203], v[30:33]
	v_mfma_f32_16x16x32_bf16 v[22:25], v[156:159], v[196:199], v[22:25]
	v_mfma_f32_16x16x32_bf16 v[22:25], v[160:163], v[200:203], v[22:25]
	v_mfma_f32_16x16x32_bf16 v[14:17], v[148:151], v[204:207], v[14:17]
	v_mfma_f32_16x16x32_bf16 v[14:17], v[152:155], v[208:211], v[14:17]
	v_mfma_f32_16x16x32_bf16 v[6:9], v[156:159], v[204:207], v[6:9]
	v_mfma_f32_16x16x32_bf16 v[6:9], v[160:163], v[208:211], v[6:9]
	v_mfma_f32_16x16x32_bf16 v[58:61], v[164:167], v[180:183], v[58:61]
	v_mfma_f32_16x16x32_bf16 v[58:61], v[168:171], v[184:187], v[58:61]
	v_mfma_f32_16x16x32_bf16 v[50:53], v[172:175], v[180:183], v[50:53]
	v_mfma_f32_16x16x32_bf16 v[50:53], v[176:179], v[184:187], v[50:53]
	v_mfma_f32_16x16x32_bf16 v[42:45], v[164:167], v[188:191], v[42:45]
	v_mfma_f32_16x16x32_bf16 v[42:45], v[168:171], v[192:195], v[42:45]
	v_mfma_f32_16x16x32_bf16 v[34:37], v[172:175], v[188:191], v[34:37]
	v_mfma_f32_16x16x32_bf16 v[34:37], v[176:179], v[192:195], v[34:37]
	v_mfma_f32_16x16x32_bf16 v[26:29], v[164:167], v[196:199], v[26:29]
	v_mfma_f32_16x16x32_bf16 v[26:29], v[168:171], v[200:203], v[26:29]
	v_mfma_f32_16x16x32_bf16 v[18:21], v[172:175], v[196:199], v[18:21]
	v_mfma_f32_16x16x32_bf16 v[18:21], v[176:179], v[200:203], v[18:21]
	s_barrier
	v_mfma_f32_16x16x32_bf16 v[10:13], v[164:167], v[204:207], v[10:13]
	v_mfma_f32_16x16x32_bf16 v[10:13], v[168:171], v[208:211], v[10:13]
	v_mfma_f32_16x16x32_bf16 v[2:5], v[172:175], v[204:207], v[2:5]
	v_mfma_f32_16x16x32_bf16 v[2:5], v[176:179], v[208:211], v[2:5]
	s_setprio 0
	ds_read_b128 v[148:151], v142
	ds_read_b128 v[152:155], v142 offset:1024
	ds_read_b128 v[156:159], v142 offset:2048
	ds_read_b128 v[160:163], v142 offset:3072
	ds_read_b128 v[164:167], v143
	ds_read_b128 v[168:171], v143 offset:1024
	ds_read_b128 v[172:175], v143 offset:2048
	ds_read_b128 v[176:179], v143 offset:3072
	s_mov_b32 m0, s47
	s_add_i32 s77, s74, 0x100000
	ds_read_b128 v[180:183], v141 offset:32768
	ds_read_b128 v[184:187], v141 offset:33792
	ds_read_b128 v[188:191], v141 offset:34816
	ds_read_b128 v[192:195], v141 offset:35840
	ds_read_b128 v[196:199], v141 offset:36864
	ds_read_b128 v[200:203], v141 offset:37888
	ds_read_b128 v[204:207], v141 offset:38912
	ds_read_b128 v[208:211], v141 offset:39936
	buffer_load_dwordx4 v137, s[12:15], s77 offen lds
	s_add_i32 s77, s74, 0x180000
	s_mov_b32 m0, s48
	s_nop 0
	buffer_load_dwordx4 v137, s[12:15], s77 offen lds
	s_waitcnt vmcnt(8)
	s_waitcnt lgkmcnt(0)
	s_setprio 1
	v_mfma_f32_16x16x32_bf16 v[118:121], v[148:151], v[180:183], v[118:121]
	s_barrier
	v_mfma_f32_16x16x32_bf16 v[118:121], v[152:155], v[184:187], v[118:121]
	v_mfma_f32_16x16x32_bf16 v[114:117], v[156:159], v[180:183], v[114:117]
	v_mfma_f32_16x16x32_bf16 v[114:117], v[160:163], v[184:187], v[114:117]
	v_mfma_f32_16x16x32_bf16 v[110:113], v[148:151], v[188:191], v[110:113]
	v_mfma_f32_16x16x32_bf16 v[110:113], v[152:155], v[192:195], v[110:113]
	v_mfma_f32_16x16x32_bf16 v[102:105], v[156:159], v[188:191], v[102:105]
	v_mfma_f32_16x16x32_bf16 v[102:105], v[160:163], v[192:195], v[102:105]
	v_mfma_f32_16x16x32_bf16 v[94:97], v[148:151], v[196:199], v[94:97]
	v_mfma_f32_16x16x32_bf16 v[94:97], v[152:155], v[200:203], v[94:97]
	v_mfma_f32_16x16x32_bf16 v[86:89], v[156:159], v[196:199], v[86:89]
	v_mfma_f32_16x16x32_bf16 v[86:89], v[160:163], v[200:203], v[86:89]
	v_mfma_f32_16x16x32_bf16 v[78:81], v[148:151], v[204:207], v[78:81]
	v_mfma_f32_16x16x32_bf16 v[78:81], v[152:155], v[208:211], v[78:81]
	v_mfma_f32_16x16x32_bf16 v[66:69], v[156:159], v[204:207], v[66:69]
	v_mfma_f32_16x16x32_bf16 v[66:69], v[160:163], v[208:211], v[66:69]
	v_mfma_f32_16x16x32_bf16 v[126:129], v[164:167], v[180:183], v[126:129]
	v_mfma_f32_16x16x32_bf16 v[126:129], v[168:171], v[184:187], v[126:129]
	v_mfma_f32_16x16x32_bf16 v[122:125], v[172:175], v[180:183], v[122:125]
	v_mfma_f32_16x16x32_bf16 v[122:125], v[176:179], v[184:187], v[122:125]
	v_mfma_f32_16x16x32_bf16 v[106:109], v[164:167], v[188:191], v[106:109]
	v_mfma_f32_16x16x32_bf16 v[106:109], v[168:171], v[192:195], v[106:109]
	v_mfma_f32_16x16x32_bf16 v[98:101], v[172:175], v[188:191], v[98:101]
	v_mfma_f32_16x16x32_bf16 v[98:101], v[176:179], v[192:195], v[98:101]
	v_mfma_f32_16x16x32_bf16 v[90:93], v[164:167], v[196:199], v[90:93]
	v_mfma_f32_16x16x32_bf16 v[90:93], v[168:171], v[200:203], v[90:93]
	v_mfma_f32_16x16x32_bf16 v[82:85], v[172:175], v[196:199], v[82:85]
	v_mfma_f32_16x16x32_bf16 v[82:85], v[176:179], v[200:203], v[82:85]
	s_barrier
	v_mfma_f32_16x16x32_bf16 v[74:77], v[164:167], v[204:207], v[74:77]
	v_mfma_f32_16x16x32_bf16 v[74:77], v[168:171], v[208:211], v[74:77]
	v_mfma_f32_16x16x32_bf16 v[70:73], v[172:175], v[204:207], v[70:73]
	v_mfma_f32_16x16x32_bf16 v[70:73], v[176:179], v[208:211], v[70:73]
	s_setprio 0
	s_mov_b32 m0, s50
	s_or_b32 s77, s76, 0x80
	ds_read_b128 v[180:183], v141 offset:49152
	ds_read_b128 v[184:187], v141 offset:50176
	ds_read_b128 v[188:191], v141 offset:51200
	ds_read_b128 v[192:195], v141 offset:52224
	ds_read_b128 v[196:199], v141 offset:53248
	ds_read_b128 v[200:203], v141 offset:54272
	ds_read_b128 v[204:207], v141 offset:55296
	ds_read_b128 v[208:211], v141 offset:56320
	buffer_load_dwordx4 v138, s[16:19], s77 offen lds
	s_add_i32 s77, s76, 0x80080
	s_mov_b32 m0, s51
	s_add_i32 s74, s74, 0x80080
	buffer_load_dwordx4 v138, s[16:19], s77 offen lds
	s_add_i32 s77, s76, 0x100080
	s_mov_b32 m0, s54
	s_add_i32 s76, s76, 0x180080
	buffer_load_dwordx4 v138, s[16:19], s77 offen lds
	s_mov_b32 m0, s55
	s_nop 0
	buffer_load_dwordx4 v138, s[16:19], s76 offen lds
	s_mov_b32 m0, s52
	s_nop 0
	buffer_load_dwordx4 v137, s[12:15], s75 offen lds
	s_mov_b32 m0, s53
	s_nop 0
	buffer_load_dwordx4 v137, s[12:15], s74 offen lds
	s_waitcnt vmcnt(8)
	s_waitcnt lgkmcnt(0)
	s_setprio 1
	v_mfma_f32_16x16x32_bf16 v[62:65], v[148:151], v[180:183], v[62:65]
	s_barrier
	v_mfma_f32_16x16x32_bf16 v[62:65], v[152:155], v[184:187], v[62:65]
	v_mfma_f32_16x16x32_bf16 v[54:57], v[156:159], v[180:183], v[54:57]
	v_mfma_f32_16x16x32_bf16 v[54:57], v[160:163], v[184:187], v[54:57]
	v_mfma_f32_16x16x32_bf16 v[46:49], v[148:151], v[188:191], v[46:49]
	v_mfma_f32_16x16x32_bf16 v[46:49], v[152:155], v[192:195], v[46:49]
	v_mfma_f32_16x16x32_bf16 v[38:41], v[156:159], v[188:191], v[38:41]
	v_mfma_f32_16x16x32_bf16 v[38:41], v[160:163], v[192:195], v[38:41]
	v_mfma_f32_16x16x32_bf16 v[30:33], v[148:151], v[196:199], v[30:33]
	v_mfma_f32_16x16x32_bf16 v[30:33], v[152:155], v[200:203], v[30:33]
	v_mfma_f32_16x16x32_bf16 v[22:25], v[156:159], v[196:199], v[22:25]
	v_mfma_f32_16x16x32_bf16 v[22:25], v[160:163], v[200:203], v[22:25]
	v_mfma_f32_16x16x32_bf16 v[14:17], v[148:151], v[204:207], v[14:17]
	v_mfma_f32_16x16x32_bf16 v[14:17], v[152:155], v[208:211], v[14:17]
	v_mfma_f32_16x16x32_bf16 v[6:9], v[156:159], v[204:207], v[6:9]
	v_mfma_f32_16x16x32_bf16 v[6:9], v[160:163], v[208:211], v[6:9]
	v_mfma_f32_16x16x32_bf16 v[58:61], v[164:167], v[180:183], v[58:61]
	v_mfma_f32_16x16x32_bf16 v[58:61], v[168:171], v[184:187], v[58:61]
	v_mfma_f32_16x16x32_bf16 v[50:53], v[172:175], v[180:183], v[50:53]
	v_mfma_f32_16x16x32_bf16 v[50:53], v[176:179], v[184:187], v[50:53]
	v_mfma_f32_16x16x32_bf16 v[42:45], v[164:167], v[188:191], v[42:45]
	v_mfma_f32_16x16x32_bf16 v[42:45], v[168:171], v[192:195], v[42:45]
	v_mfma_f32_16x16x32_bf16 v[34:37], v[172:175], v[188:191], v[34:37]
	v_mfma_f32_16x16x32_bf16 v[34:37], v[176:179], v[192:195], v[34:37]
	v_mfma_f32_16x16x32_bf16 v[26:29], v[164:167], v[196:199], v[26:29]
	v_mfma_f32_16x16x32_bf16 v[26:29], v[168:171], v[200:203], v[26:29]
	v_mfma_f32_16x16x32_bf16 v[18:21], v[172:175], v[196:199], v[18:21]
	v_mfma_f32_16x16x32_bf16 v[18:21], v[176:179], v[200:203], v[18:21]
	s_barrier
	v_mfma_f32_16x16x32_bf16 v[10:13], v[164:167], v[204:207], v[10:13]
	v_mfma_f32_16x16x32_bf16 v[10:13], v[168:171], v[208:211], v[10:13]
	v_mfma_f32_16x16x32_bf16 v[2:5], v[172:175], v[204:207], v[2:5]
	v_mfma_f32_16x16x32_bf16 v[2:5], v[176:179], v[208:211], v[2:5]
	s_setprio 0
	s_add_i32 s73, s73, 2
	s_addk_i32 s71, 0x100
	s_addk_i32 s72, 0x100
	s_cmp_ge_i32 s73, s3
	s_cbranch_scc0 .LBB0_642
	s_and_b64 vcc, exec, s[42:43]
	s_cbranch_vccz .LBB0_645

.LBB0_799:
	ds_read_b128 v[134:137], v210
	ds_read_b128 v[138:141], v210 offset:1024
	ds_read_b128 v[142:145], v210 offset:2048
	ds_read_b128 v[148:151], v210 offset:3072
	ds_read_b128 v[152:155], v211
	ds_read_b128 v[156:159], v211 offset:1024
	ds_read_b128 v[160:163], v211 offset:2048
	ds_read_b128 v[164:167], v211 offset:3072
	s_add_i32 s18, s77, 0xffbf8080
	s_cmp_eq_u32 s62, s79
	s_cselect_b32 s80, s6, s18
	s_cselect_b32 s82, s7, s78
	s_or_b32 s81, s80, 0x80
	s_add_i32 s18, s77, 0xffea8000
	s_mov_b32 m0, s63
	ds_read_b128 v[168:171], v212
	ds_read_b128 v[172:175], v212 offset:1024
	ds_read_b128 v[176:179], v212 offset:2048
	ds_read_b128 v[180:183], v212 offset:3072
	ds_read_b128 v[184:187], v212 offset:4096
	ds_read_b128 v[188:191], v212 offset:5120
	ds_read_b128 v[192:195], v212 offset:6144
	ds_read_b128 v[196:199], v212 offset:7168
	buffer_load_dwordx4 v208, s[12:15], s18 offen lds
	s_mov_b32 m0, s66
	s_nop 0
	buffer_load_dwordx4 v208, s[12:15], s77 offen lds
	s_waitcnt vmcnt(8)
	s_waitcnt lgkmcnt(0)
	s_setprio 1
	v_mfma_f32_16x16x32_bf16 v[126:129], v[134:137], v[168:171], v[126:129]
	s_barrier
	v_mfma_f32_16x16x32_bf16 v[126:129], v[138:141], v[172:175], v[126:129]
	v_mfma_f32_16x16x32_bf16 v[122:125], v[142:145], v[168:171], v[122:125]
	v_mfma_f32_16x16x32_bf16 v[122:125], v[148:151], v[172:175], v[122:125]
	v_mfma_f32_16x16x32_bf16 v[118:121], v[134:137], v[176:179], v[118:121]
	v_mfma_f32_16x16x32_bf16 v[118:121], v[138:141], v[180:183], v[118:121]
	v_mfma_f32_16x16x32_bf16 v[114:117], v[142:145], v[176:179], v[114:117]
	v_mfma_f32_16x16x32_bf16 v[114:117], v[148:151], v[180:183], v[114:117]
	v_mfma_f32_16x16x32_bf16 v[106:109], v[134:137], v[184:187], v[106:109]
	v_mfma_f32_16x16x32_bf16 v[106:109], v[138:141], v[188:191], v[106:109]
	v_mfma_f32_16x16x32_bf16 v[98:101], v[142:145], v[184:187], v[98:101]
	v_mfma_f32_16x16x32_bf16 v[98:101], v[148:151], v[188:191], v[98:101]
	v_mfma_f32_16x16x32_bf16 v[90:93], v[134:137], v[192:195], v[90:93]
	v_mfma_f32_16x16x32_bf16 v[90:93], v[138:141], v[196:199], v[90:93]
	v_mfma_f32_16x16x32_bf16 v[82:85], v[142:145], v[192:195], v[82:85]
	v_mfma_f32_16x16x32_bf16 v[82:85], v[148:151], v[196:199], v[82:85]
	v_mfma_f32_16x16x32_bf16 v[110:113], v[152:155], v[168:171], v[110:113]
	v_mfma_f32_16x16x32_bf16 v[110:113], v[156:159], v[172:175], v[110:113]
	v_mfma_f32_16x16x32_bf16 v[102:105], v[160:163], v[168:171], v[102:105]
	v_mfma_f32_16x16x32_bf16 v[102:105], v[164:167], v[172:175], v[102:105]
	v_mfma_f32_16x16x32_bf16 v[94:97], v[152:155], v[176:179], v[94:97]
	v_mfma_f32_16x16x32_bf16 v[94:97], v[156:159], v[180:183], v[94:97]
	v_mfma_f32_16x16x32_bf16 v[86:89], v[160:163], v[176:179], v[86:89]
	v_mfma_f32_16x16x32_bf16 v[86:89], v[164:167], v[180:183], v[86:89]
	v_mfma_f32_16x16x32_bf16 v[78:81], v[152:155], v[184:187], v[78:81]
	v_mfma_f32_16x16x32_bf16 v[78:81], v[156:159], v[188:191], v[78:81]
	v_mfma_f32_16x16x32_bf16 v[74:77], v[160:163], v[184:187], v[74:77]
	v_mfma_f32_16x16x32_bf16 v[74:77], v[164:167], v[188:191], v[74:77]
	s_barrier
	v_mfma_f32_16x16x32_bf16 v[70:73], v[152:155], v[192:195], v[70:73]
	v_mfma_f32_16x16x32_bf16 v[70:73], v[156:159], v[196:199], v[70:73]
	v_mfma_f32_16x16x32_bf16 v[66:69], v[160:163], v[192:195], v[66:69]
	v_mfma_f32_16x16x32_bf16 v[66:69], v[164:167], v[196:199], v[66:69]
	s_setprio 0
	s_mov_b32 m0, s25
	s_mov_b32 s18, s14
	s_mov_b32 s19, s15
	ds_read_b128 v[168:171], v212 offset:16384
	ds_read_b128 v[172:175], v212 offset:17408
	ds_read_b128 v[176:179], v212 offset:18432
	ds_read_b128 v[180:183], v212 offset:19456
	ds_read_b128 v[184:187], v212 offset:20480
	ds_read_b128 v[188:191], v212 offset:21504
	ds_read_b128 v[192:195], v212 offset:22528
	ds_read_b128 v[196:199], v212 offset:23552
	buffer_load_dwordx4 v209, s[16:19], s82 offen lds
	s_add_i32 s83, s82, 0x158000
	s_mov_b32 m0, s27
	s_nop 0
	buffer_load_dwordx4 v209, s[16:19], s83 offen lds
	s_add_i32 s83, s82, 0x2b0000
	s_mov_b32 m0, s30
	s_nop 0
	buffer_load_dwordx4 v209, s[16:19], s83 offen lds
	s_add_i32 s83, s82, 0x408000
	s_mov_b32 m0, s31
	s_nop 0
	buffer_load_dwordx4 v209, s[16:19], s83 offen lds
	s_mov_b32 m0, s21
	s_add_i32 s83, s80, 0x158000
	buffer_load_dwordx4 v208, s[12:15], s80 offen lds
	s_mov_b32 m0, s48
	s_nop 0
	buffer_load_dwordx4 v208, s[12:15], s83 offen lds
	s_waitcnt vmcnt(8)
	s_waitcnt lgkmcnt(0)
	s_setprio 1
	v_mfma_f32_16x16x32_bf16 v[62:65], v[134:137], v[168:171], v[62:65]
	s_barrier
	v_mfma_f32_16x16x32_bf16 v[62:65], v[138:141], v[172:175], v[62:65]
	v_mfma_f32_16x16x32_bf16 v[58:61], v[142:145], v[168:171], v[58:61]
	v_mfma_f32_16x16x32_bf16 v[58:61], v[148:151], v[172:175], v[58:61]
	v_mfma_f32_16x16x32_bf16 v[54:57], v[134:137], v[176:179], v[54:57]
	v_mfma_f32_16x16x32_bf16 v[54:57], v[138:141], v[180:183], v[54:57]
	v_mfma_f32_16x16x32_bf16 v[50:53], v[142:145], v[176:179], v[50:53]
	v_mfma_f32_16x16x32_bf16 v[50:53], v[148:151], v[180:183], v[50:53]
	v_mfma_f32_16x16x32_bf16 v[42:45], v[134:137], v[184:187], v[42:45]
	v_mfma_f32_16x16x32_bf16 v[42:45], v[138:141], v[188:191], v[42:45]
	v_mfma_f32_16x16x32_bf16 v[34:37], v[142:145], v[184:187], v[34:37]
	v_mfma_f32_16x16x32_bf16 v[34:37], v[148:151], v[188:191], v[34:37]
	v_mfma_f32_16x16x32_bf16 v[26:29], v[134:137], v[192:195], v[26:29]
	v_mfma_f32_16x16x32_bf16 v[26:29], v[138:141], v[196:199], v[26:29]
	v_mfma_f32_16x16x32_bf16 v[18:21], v[142:145], v[192:195], v[18:21]
	v_mfma_f32_16x16x32_bf16 v[18:21], v[148:151], v[196:199], v[18:21]
	v_mfma_f32_16x16x32_bf16 v[46:49], v[152:155], v[168:171], v[46:49]
	v_mfma_f32_16x16x32_bf16 v[46:49], v[156:159], v[172:175], v[46:49]
	v_mfma_f32_16x16x32_bf16 v[38:41], v[160:163], v[168:171], v[38:41]
	v_mfma_f32_16x16x32_bf16 v[38:41], v[164:167], v[172:175], v[38:41]
	v_mfma_f32_16x16x32_bf16 v[30:33], v[152:155], v[176:179], v[30:33]
	v_mfma_f32_16x16x32_bf16 v[30:33], v[156:159], v[180:183], v[30:33]
	v_mfma_f32_16x16x32_bf16 v[22:25], v[160:163], v[176:179], v[22:25]
	v_mfma_f32_16x16x32_bf16 v[22:25], v[164:167], v[180:183], v[22:25]
	v_mfma_f32_16x16x32_bf16 v[14:17], v[152:155], v[184:187], v[14:17]
	v_mfma_f32_16x16x32_bf16 v[14:17], v[156:159], v[188:191], v[14:17]
	v_mfma_f32_16x16x32_bf16 v[10:13], v[160:163], v[184:187], v[10:13]
	v_mfma_f32_16x16x32_bf16 v[10:13], v[164:167], v[188:191], v[10:13]
	s_barrier
	v_mfma_f32_16x16x32_bf16 v[6:9], v[152:155], v[192:195], v[6:9]
	v_mfma_f32_16x16x32_bf16 v[6:9], v[156:159], v[196:199], v[6:9]
	v_mfma_f32_16x16x32_bf16 v[2:5], v[160:163], v[192:195], v[2:5]
	v_mfma_f32_16x16x32_bf16 v[2:5], v[164:167], v[196:199], v[2:5]
	s_setprio 0
	ds_read_b128 v[134:137], v213
	ds_read_b128 v[138:141], v213 offset:1024
	ds_read_b128 v[142:145], v213 offset:2048
	ds_read_b128 v[148:151], v213 offset:3072
	ds_read_b128 v[152:155], v214
	ds_read_b128 v[156:159], v214 offset:1024
	ds_read_b128 v[160:163], v214 offset:2048
	ds_read_b128 v[164:167], v214 offset:3072
	s_mov_b32 m0, s49
	s_add_i32 s83, s80, 0x2b0000
	ds_read_b128 v[168:171], v212 offset:32768
	ds_read_b128 v[172:175], v212 offset:33792
	ds_read_b128 v[176:179], v212 offset:34816
	ds_read_b128 v[180:183], v212 offset:35840
	ds_read_b128 v[184:187], v212 offset:36864
	ds_read_b128 v[188:191], v212 offset:37888
	ds_read_b128 v[192:195], v212 offset:38912
	ds_read_b128 v[196:199], v212 offset:39936
	buffer_load_dwordx4 v208, s[12:15], s83 offen lds
	s_add_i32 s83, s80, 0x408000
	s_mov_b32 m0, s50
	s_nop 0
	buffer_load_dwordx4 v208, s[12:15], s83 offen lds
	s_waitcnt vmcnt(8)
	s_waitcnt lgkmcnt(0)
	s_setprio 1
	v_mfma_f32_16x16x32_bf16 v[126:129], v[134:137], v[168:171], v[126:129]
	s_barrier
	v_mfma_f32_16x16x32_bf16 v[126:129], v[138:141], v[172:175], v[126:129]
	v_mfma_f32_16x16x32_bf16 v[122:125], v[142:145], v[168:171], v[122:125]
	v_mfma_f32_16x16x32_bf16 v[122:125], v[148:151], v[172:175], v[122:125]
	v_mfma_f32_16x16x32_bf16 v[118:121], v[134:137], v[176:179], v[118:121]
	v_mfma_f32_16x16x32_bf16 v[118:121], v[138:141], v[180:183], v[118:121]
	v_mfma_f32_16x16x32_bf16 v[114:117], v[142:145], v[176:179], v[114:117]
	v_mfma_f32_16x16x32_bf16 v[114:117], v[148:151], v[180:183], v[114:117]
	v_mfma_f32_16x16x32_bf16 v[106:109], v[134:137], v[184:187], v[106:109]
	v_mfma_f32_16x16x32_bf16 v[106:109], v[138:141], v[188:191], v[106:109]
	v_mfma_f32_16x16x32_bf16 v[98:101], v[142:145], v[184:187], v[98:101]
	v_mfma_f32_16x16x32_bf16 v[98:101], v[148:151], v[188:191], v[98:101]
	v_mfma_f32_16x16x32_bf16 v[90:93], v[134:137], v[192:195], v[90:93]
	v_mfma_f32_16x16x32_bf16 v[90:93], v[138:141], v[196:199], v[90:93]
	v_mfma_f32_16x16x32_bf16 v[82:85], v[142:145], v[192:195], v[82:85]
	v_mfma_f32_16x16x32_bf16 v[82:85], v[148:151], v[196:199], v[82:85]
	v_mfma_f32_16x16x32_bf16 v[110:113], v[152:155], v[168:171], v[110:113]
	v_mfma_f32_16x16x32_bf16 v[110:113], v[156:159], v[172:175], v[110:113]
	v_mfma_f32_16x16x32_bf16 v[102:105], v[160:163], v[168:171], v[102:105]
	v_mfma_f32_16x16x32_bf16 v[102:105], v[164:167], v[172:175], v[102:105]
	v_mfma_f32_16x16x32_bf16 v[94:97], v[152:155], v[176:179], v[94:97]
	v_mfma_f32_16x16x32_bf16 v[94:97], v[156:159], v[180:183], v[94:97]
	v_mfma_f32_16x16x32_bf16 v[86:89], v[160:163], v[176:179], v[86:89]
	v_mfma_f32_16x16x32_bf16 v[86:89], v[164:167], v[180:183], v[86:89]
	v_mfma_f32_16x16x32_bf16 v[78:81], v[152:155], v[184:187], v[78:81]
	v_mfma_f32_16x16x32_bf16 v[78:81], v[156:159], v[188:191], v[78:81]
	v_mfma_f32_16x16x32_bf16 v[74:77], v[160:163], v[184:187], v[74:77]
	v_mfma_f32_16x16x32_bf16 v[74:77], v[164:167], v[188:191], v[74:77]
	s_barrier
	v_mfma_f32_16x16x32_bf16 v[70:73], v[152:155], v[192:195], v[70:73]
	v_mfma_f32_16x16x32_bf16 v[70:73], v[156:159], v[196:199], v[70:73]
	v_mfma_f32_16x16x32_bf16 v[66:69], v[160:163], v[192:195], v[66:69]
	v_mfma_f32_16x16x32_bf16 v[66:69], v[164:167], v[196:199], v[66:69]
	s_setprio 0
	s_mov_b32 m0, s54
	s_or_b32 s83, s82, 0x80
	ds_read_b128 v[168:171], v212 offset:49152
	ds_read_b128 v[172:175], v212 offset:50176
	ds_read_b128 v[176:179], v212 offset:51200
	ds_read_b128 v[180:183], v212 offset:52224
	ds_read_b128 v[184:187], v212 offset:53248
	ds_read_b128 v[188:191], v212 offset:54272
	ds_read_b128 v[192:195], v212 offset:55296
	ds_read_b128 v[196:199], v212 offset:56320
	buffer_load_dwordx4 v209, s[16:19], s83 offen lds
	s_add_i32 s83, s82, 0x158080
	s_mov_b32 m0, s55
	s_add_i32 s80, s80, 0x158080
	buffer_load_dwordx4 v209, s[16:19], s83 offen lds
	s_add_i32 s83, s82, 0x2b0080
	s_mov_b32 m0, s58
	s_add_i32 s82, s82, 0x408080
	buffer_load_dwordx4 v209, s[16:19], s83 offen lds
	s_mov_b32 m0, s59
	s_nop 0
	buffer_load_dwordx4 v209, s[16:19], s82 offen lds
	s_mov_b32 m0, s56
	s_nop 0
	buffer_load_dwordx4 v208, s[12:15], s81 offen lds
	s_mov_b32 m0, s57
	s_nop 0
	buffer_load_dwordx4 v208, s[12:15], s80 offen lds
	s_waitcnt vmcnt(8)
	s_waitcnt lgkmcnt(0)
	s_setprio 1
	v_mfma_f32_16x16x32_bf16 v[62:65], v[134:137], v[168:171], v[62:65]
	s_barrier
	v_mfma_f32_16x16x32_bf16 v[62:65], v[138:141], v[172:175], v[62:65]
	v_mfma_f32_16x16x32_bf16 v[58:61], v[142:145], v[168:171], v[58:61]
	v_mfma_f32_16x16x32_bf16 v[58:61], v[148:151], v[172:175], v[58:61]
	v_mfma_f32_16x16x32_bf16 v[54:57], v[134:137], v[176:179], v[54:57]
	v_mfma_f32_16x16x32_bf16 v[54:57], v[138:141], v[180:183], v[54:57]
	v_mfma_f32_16x16x32_bf16 v[50:53], v[142:145], v[176:179], v[50:53]
	v_mfma_f32_16x16x32_bf16 v[50:53], v[148:151], v[180:183], v[50:53]
	v_mfma_f32_16x16x32_bf16 v[42:45], v[134:137], v[184:187], v[42:45]
	v_mfma_f32_16x16x32_bf16 v[42:45], v[138:141], v[188:191], v[42:45]
	v_mfma_f32_16x16x32_bf16 v[34:37], v[142:145], v[184:187], v[34:37]
	v_mfma_f32_16x16x32_bf16 v[34:37], v[148:151], v[188:191], v[34:37]
	v_mfma_f32_16x16x32_bf16 v[26:29], v[134:137], v[192:195], v[26:29]
	v_mfma_f32_16x16x32_bf16 v[26:29], v[138:141], v[196:199], v[26:29]
	v_mfma_f32_16x16x32_bf16 v[18:21], v[142:145], v[192:195], v[18:21]
	v_mfma_f32_16x16x32_bf16 v[18:21], v[148:151], v[196:199], v[18:21]
	v_mfma_f32_16x16x32_bf16 v[46:49], v[152:155], v[168:171], v[46:49]
	v_mfma_f32_16x16x32_bf16 v[46:49], v[156:159], v[172:175], v[46:49]
	v_mfma_f32_16x16x32_bf16 v[38:41], v[160:163], v[168:171], v[38:41]
	v_mfma_f32_16x16x32_bf16 v[38:41], v[164:167], v[172:175], v[38:41]
	v_mfma_f32_16x16x32_bf16 v[30:33], v[152:155], v[176:179], v[30:33]
	v_mfma_f32_16x16x32_bf16 v[30:33], v[156:159], v[180:183], v[30:33]
	v_mfma_f32_16x16x32_bf16 v[22:25], v[160:163], v[176:179], v[22:25]
	v_mfma_f32_16x16x32_bf16 v[22:25], v[164:167], v[180:183], v[22:25]
	v_mfma_f32_16x16x32_bf16 v[14:17], v[152:155], v[184:187], v[14:17]
	v_mfma_f32_16x16x32_bf16 v[14:17], v[156:159], v[188:191], v[14:17]
	v_mfma_f32_16x16x32_bf16 v[10:13], v[160:163], v[184:187], v[10:13]
	v_mfma_f32_16x16x32_bf16 v[10:13], v[164:167], v[188:191], v[10:13]
	s_barrier
	v_mfma_f32_16x16x32_bf16 v[6:9], v[152:155], v[192:195], v[6:9]
	v_mfma_f32_16x16x32_bf16 v[6:9], v[156:159], v[196:199], v[6:9]
	v_mfma_f32_16x16x32_bf16 v[2:5], v[160:163], v[192:195], v[2:5]
	v_mfma_f32_16x16x32_bf16 v[2:5], v[164:167], v[196:199], v[2:5]
	s_setprio 0
	s_add_i32 s79, s79, 2
	s_addk_i32 s77, 0x100
	s_addk_i32 s78, 0x100
	s_cmp_ge_i32 s79, s3
	s_cbranch_scc0 .LBB0_799
	v_pk_mul_f32 v[184:185], v[128:129], 0.5 op_sel_hi:[1,0]
	v_pk_mul_f32 v[186:187], v[126:127], 0.5 op_sel_hi:[1,0]
	v_pk_mul_f32 v[188:189], v[124:125], 0.5 op_sel_hi:[1,0]
	v_pk_mul_f32 v[190:191], v[122:123], 0.5 op_sel_hi:[1,0]
	v_pk_mul_f32 v[198:199], v[112:113], 0.5 op_sel_hi:[1,0]
	v_pk_mul_f32 v[196:197], v[110:111], 0.5 op_sel_hi:[1,0]
	v_pk_mul_f32 v[194:195], v[104:105], 0.5 op_sel_hi:[1,0]
	v_pk_mul_f32 v[192:193], v[102:103], 0.5 op_sel_hi:[1,0]
	v_pk_mul_f32 v[182:183], v[120:121], 0.5 op_sel_hi:[1,0]
	v_pk_mul_f32 v[180:181], v[118:119], 0.5 op_sel_hi:[1,0]
	v_pk_mul_f32 v[178:179], v[116:117], 0.5 op_sel_hi:[1,0]
	v_pk_mul_f32 v[176:177], v[114:115], 0.5 op_sel_hi:[1,0]
	v_pk_mul_f32 v[172:173], v[96:97], 0.5 op_sel_hi:[1,0]
	v_pk_mul_f32 v[170:171], v[94:95], 0.5 op_sel_hi:[1,0]
	v_pk_mul_f32 v[168:169], v[88:89], 0.5 op_sel_hi:[1,0]
	v_pk_mul_f32 v[166:167], v[86:87], 0.5 op_sel_hi:[1,0]
	v_pk_mul_f32 v[164:165], v[108:109], 0.5 op_sel_hi:[1,0]
	v_pk_mul_f32 v[162:163], v[106:107], 0.5 op_sel_hi:[1,0]
	v_pk_mul_f32 v[160:161], v[100:101], 0.5 op_sel_hi:[1,0]
	v_pk_mul_f32 v[158:159], v[98:99], 0.5 op_sel_hi:[1,0]
	v_pk_mul_f32 v[156:157], v[80:81], 0.5 op_sel_hi:[1,0]
	v_pk_mul_f32 v[154:155], v[78:79], 0.5 op_sel_hi:[1,0]
	v_pk_mul_f32 v[152:153], v[76:77], 0.5 op_sel_hi:[1,0]
	v_pk_mul_f32 v[150:151], v[74:75], 0.5 op_sel_hi:[1,0]
	v_pk_mul_f32 v[144:145], v[92:93], 0.5 op_sel_hi:[1,0]
	v_pk_mul_f32 v[142:143], v[90:91], 0.5 op_sel_hi:[1,0]
	v_pk_mul_f32 v[140:141], v[84:85], 0.5 op_sel_hi:[1,0]
	v_pk_mul_f32 v[138:139], v[82:83], 0.5 op_sel_hi:[1,0]
	v_pk_mul_f32 v[136:137], v[72:73], 0.5 op_sel_hi:[1,0]
	v_pk_mul_f32 v[134:135], v[70:71], 0.5 op_sel_hi:[1,0]
	v_pk_mul_f32 v[128:129], v[68:69], 0.5 op_sel_hi:[1,0]
	v_pk_mul_f32 v[126:127], v[66:67], 0.5 op_sel_hi:[1,0]
	v_pk_mul_f32 v[122:123], v[64:65], 0.5 op_sel_hi:[1,0]
	v_pk_mul_f32 v[120:121], v[62:63], 0.5 op_sel_hi:[1,0]
	v_pk_mul_f32 v[118:119], v[60:61], 0.5 op_sel_hi:[1,0]
	v_pk_mul_f32 v[116:117], v[58:59], 0.5 op_sel_hi:[1,0]
	v_pk_mul_f32 v[112:113], v[48:49], 0.5 op_sel_hi:[1,0]
	v_pk_mul_f32 v[110:111], v[46:47], 0.5 op_sel_hi:[1,0]
	v_pk_mul_f32 v[108:109], v[40:41], 0.5 op_sel_hi:[1,0]
	v_pk_mul_f32 v[106:107], v[38:39], 0.5 op_sel_hi:[1,0]
	v_pk_mul_f32 v[104:105], v[56:57], 0.5 op_sel_hi:[1,0]
	v_pk_mul_f32 v[102:103], v[54:55], 0.5 op_sel_hi:[1,0]
	v_pk_mul_f32 v[100:101], v[52:53], 0.5 op_sel_hi:[1,0]
	v_pk_mul_f32 v[98:99], v[50:51], 0.5 op_sel_hi:[1,0]
	v_pk_mul_f32 v[96:97], v[32:33], 0.5 op_sel_hi:[1,0]
	v_pk_mul_f32 v[94:95], v[30:31], 0.5 op_sel_hi:[1,0]
	v_pk_mul_f32 v[92:93], v[24:25], 0.5 op_sel_hi:[1,0]
	v_pk_mul_f32 v[90:91], v[22:23], 0.5 op_sel_hi:[1,0]
	v_pk_mul_f32 v[88:89], v[44:45], 0.5 op_sel_hi:[1,0]
	v_pk_mul_f32 v[86:87], v[42:43], 0.5 op_sel_hi:[1,0]
	v_pk_mul_f32 v[84:85], v[36:37], 0.5 op_sel_hi:[1,0]
	v_pk_mul_f32 v[82:83], v[34:35], 0.5 op_sel_hi:[1,0]
	v_pk_mul_f32 v[80:81], v[16:17], 0.5 op_sel_hi:[1,0]
	v_pk_mul_f32 v[78:79], v[14:15], 0.5 op_sel_hi:[1,0]
	v_pk_mul_f32 v[76:77], v[12:13], 0.5 op_sel_hi:[1,0]
	v_pk_mul_f32 v[74:75], v[10:11], 0.5 op_sel_hi:[1,0]
	v_pk_mul_f32 v[72:73], v[28:29], 0.5 op_sel_hi:[1,0]
	v_pk_mul_f32 v[70:71], v[26:27], 0.5 op_sel_hi:[1,0]
	v_pk_mul_f32 v[68:69], v[20:21], 0.5 op_sel_hi:[1,0]
	v_pk_mul_f32 v[66:67], v[18:19], 0.5 op_sel_hi:[1,0]
	v_pk_mul_f32 v[64:65], v[8:9], 0.5 op_sel_hi:[1,0]
	v_pk_mul_f32 v[62:63], v[6:7], 0.5 op_sel_hi:[1,0]
	v_pk_mul_f32 v[60:61], v[4:5], 0.5 op_sel_hi:[1,0]
	v_pk_mul_f32 v[58:59], v[2:3], 0.5 op_sel_hi:[1,0]
	s_and_b64 vcc, exec, s[38:39]
	s_cbranch_vccz .LBB0_802

.LBB0_892:
	ds_read_b128 v[130:133], v172
	ds_read_b128 v[134:137], v172 offset:1024
	ds_read_b128 v[148:151], v172 offset:2048
	ds_read_b128 v[152:155], v172 offset:3072
	ds_read_b128 v[156:159], v173
	ds_read_b128 v[160:163], v173 offset:1024
	ds_read_b128 v[164:167], v173 offset:2048
	ds_read_b128 v[180:183], v173 offset:3072
	s_add_i32 s18, s8, 0xffe80080
	s_cmp_eq_u32 s77, s52
	s_cselect_b32 s53, s6, s18
	s_cselect_b32 s58, s7, s9
	s_or_b32 s57, s53, 0x80
	s_add_i32 s18, s8, 0xfff80000
	s_mov_b32 m0, s78
	ds_read_b128 v[184:187], v174
	ds_read_b128 v[188:191], v174 offset:1024
	ds_read_b128 v[192:195], v174 offset:2048
	ds_read_b128 v[196:199], v174 offset:3072
	ds_read_b128 v[200:203], v174 offset:4096
	ds_read_b128 v[204:207], v174 offset:5120
	ds_read_b128 v[208:211], v174 offset:6144
	ds_read_b128 v[212:215], v174 offset:7168
	buffer_load_dwordx4 v170, s[12:15], s18 offen lds
	s_mov_b32 m0, s79
	s_nop 0
	buffer_load_dwordx4 v170, s[12:15], s8 offen lds
	s_waitcnt vmcnt(8)
	s_waitcnt lgkmcnt(0)
	s_setprio 1
	v_mfma_f32_16x16x32_bf16 v[126:129], v[130:133], v[184:187], v[126:129]
	s_barrier
	v_mfma_f32_16x16x32_bf16 v[126:129], v[134:137], v[188:191], v[126:129]
	v_mfma_f32_16x16x32_bf16 v[118:121], v[148:151], v[184:187], v[118:121]
	v_mfma_f32_16x16x32_bf16 v[118:121], v[152:155], v[188:191], v[118:121]
	v_mfma_f32_16x16x32_bf16 v[110:113], v[130:133], v[192:195], v[110:113]
	v_mfma_f32_16x16x32_bf16 v[110:113], v[134:137], v[196:199], v[110:113]
	v_mfma_f32_16x16x32_bf16 v[102:105], v[148:151], v[192:195], v[102:105]
	v_mfma_f32_16x16x32_bf16 v[102:105], v[152:155], v[196:199], v[102:105]
	v_mfma_f32_16x16x32_bf16 v[94:97], v[130:133], v[200:203], v[94:97]
	v_mfma_f32_16x16x32_bf16 v[94:97], v[134:137], v[204:207], v[94:97]
	v_mfma_f32_16x16x32_bf16 v[90:93], v[148:151], v[200:203], v[90:93]
	v_mfma_f32_16x16x32_bf16 v[90:93], v[152:155], v[204:207], v[90:93]
	v_mfma_f32_16x16x32_bf16 v[78:81], v[130:133], v[208:211], v[78:81]
	v_mfma_f32_16x16x32_bf16 v[78:81], v[134:137], v[212:215], v[78:81]
	v_mfma_f32_16x16x32_bf16 v[70:73], v[148:151], v[208:211], v[70:73]
	v_mfma_f32_16x16x32_bf16 v[70:73], v[152:155], v[212:215], v[70:73]
	v_mfma_f32_16x16x32_bf16 v[122:125], v[156:159], v[184:187], v[122:125]
	v_mfma_f32_16x16x32_bf16 v[122:125], v[160:163], v[188:191], v[122:125]
	v_mfma_f32_16x16x32_bf16 v[114:117], v[164:167], v[184:187], v[114:117]
	v_mfma_f32_16x16x32_bf16 v[114:117], v[180:183], v[188:191], v[114:117]
	v_mfma_f32_16x16x32_bf16 v[106:109], v[156:159], v[192:195], v[106:109]
	v_mfma_f32_16x16x32_bf16 v[106:109], v[160:163], v[196:199], v[106:109]
	v_mfma_f32_16x16x32_bf16 v[98:101], v[164:167], v[192:195], v[98:101]
	v_mfma_f32_16x16x32_bf16 v[98:101], v[180:183], v[196:199], v[98:101]
	v_mfma_f32_16x16x32_bf16 v[86:89], v[156:159], v[200:203], v[86:89]
	v_mfma_f32_16x16x32_bf16 v[86:89], v[160:163], v[204:207], v[86:89]
	v_mfma_f32_16x16x32_bf16 v[82:85], v[164:167], v[200:203], v[82:85]
	v_mfma_f32_16x16x32_bf16 v[82:85], v[180:183], v[204:207], v[82:85]
	s_barrier
	v_mfma_f32_16x16x32_bf16 v[74:77], v[156:159], v[208:211], v[74:77]
	v_mfma_f32_16x16x32_bf16 v[74:77], v[160:163], v[212:215], v[74:77]
	v_mfma_f32_16x16x32_bf16 v[66:69], v[164:167], v[208:211], v[66:69]
	v_mfma_f32_16x16x32_bf16 v[66:69], v[180:183], v[212:215], v[66:69]
	s_setprio 0
	s_mov_b32 m0, s27
	s_mov_b32 s18, s14
	s_mov_b32 s19, s15
	ds_read_b128 v[184:187], v174 offset:16384
	ds_read_b128 v[188:191], v174 offset:17408
	ds_read_b128 v[192:195], v174 offset:18432
	ds_read_b128 v[196:199], v174 offset:19456
	ds_read_b128 v[200:203], v174 offset:20480
	ds_read_b128 v[204:207], v174 offset:21504
	ds_read_b128 v[208:211], v174 offset:22528
	ds_read_b128 v[212:215], v174 offset:23552
	buffer_load_dwordx4 v171, s[16:19], s58 offen lds
	s_add_i32 s59, s58, 0x80000
	s_mov_b32 m0, s60
	s_nop 0
	buffer_load_dwordx4 v171, s[16:19], s59 offen lds
	s_add_i32 s59, s58, 0x100000
	s_mov_b32 m0, s61
	s_nop 0
	buffer_load_dwordx4 v171, s[16:19], s59 offen lds
	s_add_i32 s59, s58, 0x180000
	s_mov_b32 m0, s62
	s_nop 0
	buffer_load_dwordx4 v171, s[16:19], s59 offen lds
	s_mov_b32 m0, s25
	s_add_i32 s59, s53, 0x80000
	buffer_load_dwordx4 v170, s[12:15], s53 offen lds
	s_mov_b32 m0, s63
	s_nop 0
	buffer_load_dwordx4 v170, s[12:15], s59 offen lds
	s_waitcnt vmcnt(8)
	s_waitcnt lgkmcnt(0)
	s_setprio 1
	v_mfma_f32_16x16x32_bf16 v[62:65], v[130:133], v[184:187], v[62:65]
	s_barrier
	v_mfma_f32_16x16x32_bf16 v[62:65], v[134:137], v[188:191], v[62:65]
	v_mfma_f32_16x16x32_bf16 v[54:57], v[148:151], v[184:187], v[54:57]
	v_mfma_f32_16x16x32_bf16 v[54:57], v[152:155], v[188:191], v[54:57]
	v_mfma_f32_16x16x32_bf16 v[46:49], v[130:133], v[192:195], v[46:49]
	v_mfma_f32_16x16x32_bf16 v[46:49], v[134:137], v[196:199], v[46:49]
	v_mfma_f32_16x16x32_bf16 v[38:41], v[148:151], v[192:195], v[38:41]
	v_mfma_f32_16x16x32_bf16 v[38:41], v[152:155], v[196:199], v[38:41]
	v_mfma_f32_16x16x32_bf16 v[30:33], v[130:133], v[200:203], v[30:33]
	v_mfma_f32_16x16x32_bf16 v[30:33], v[134:137], v[204:207], v[30:33]
	v_mfma_f32_16x16x32_bf16 v[22:25], v[148:151], v[200:203], v[22:25]
	v_mfma_f32_16x16x32_bf16 v[22:25], v[152:155], v[204:207], v[22:25]
	v_mfma_f32_16x16x32_bf16 v[14:17], v[130:133], v[208:211], v[14:17]
	v_mfma_f32_16x16x32_bf16 v[14:17], v[134:137], v[212:215], v[14:17]
	v_mfma_f32_16x16x32_bf16 v[6:9], v[148:151], v[208:211], v[6:9]
	v_mfma_f32_16x16x32_bf16 v[6:9], v[152:155], v[212:215], v[6:9]
	v_mfma_f32_16x16x32_bf16 v[58:61], v[156:159], v[184:187], v[58:61]
	v_mfma_f32_16x16x32_bf16 v[58:61], v[160:163], v[188:191], v[58:61]
	v_mfma_f32_16x16x32_bf16 v[50:53], v[164:167], v[184:187], v[50:53]
	v_mfma_f32_16x16x32_bf16 v[50:53], v[180:183], v[188:191], v[50:53]
	v_mfma_f32_16x16x32_bf16 v[42:45], v[156:159], v[192:195], v[42:45]
	v_mfma_f32_16x16x32_bf16 v[42:45], v[160:163], v[196:199], v[42:45]
	v_mfma_f32_16x16x32_bf16 v[34:37], v[164:167], v[192:195], v[34:37]
	v_mfma_f32_16x16x32_bf16 v[34:37], v[180:183], v[196:199], v[34:37]
	v_mfma_f32_16x16x32_bf16 v[26:29], v[156:159], v[200:203], v[26:29]
	v_mfma_f32_16x16x32_bf16 v[26:29], v[160:163], v[204:207], v[26:29]
	v_mfma_f32_16x16x32_bf16 v[18:21], v[164:167], v[200:203], v[18:21]
	v_mfma_f32_16x16x32_bf16 v[18:21], v[180:183], v[204:207], v[18:21]
	s_barrier
	v_mfma_f32_16x16x32_bf16 v[10:13], v[156:159], v[208:211], v[10:13]
	v_mfma_f32_16x16x32_bf16 v[10:13], v[160:163], v[212:215], v[10:13]
	v_mfma_f32_16x16x32_bf16 v[2:5], v[164:167], v[208:211], v[2:5]
	v_mfma_f32_16x16x32_bf16 v[2:5], v[180:183], v[212:215], v[2:5]
	s_setprio 0
	ds_read_b128 v[130:133], v175
	ds_read_b128 v[134:137], v175 offset:1024
	ds_read_b128 v[148:151], v175 offset:2048
	ds_read_b128 v[152:155], v175 offset:3072
	ds_read_b128 v[156:159], v176
	ds_read_b128 v[160:163], v176 offset:1024
	ds_read_b128 v[164:167], v176 offset:2048
	ds_read_b128 v[180:183], v176 offset:3072
	s_mov_b32 m0, s64
	s_add_i32 s59, s53, 0x100000
	ds_read_b128 v[184:187], v174 offset:32768
	ds_read_b128 v[188:191], v174 offset:33792
	ds_read_b128 v[192:195], v174 offset:34816
	ds_read_b128 v[196:199], v174 offset:35840
	ds_read_b128 v[200:203], v174 offset:36864
	ds_read_b128 v[204:207], v174 offset:37888
	ds_read_b128 v[208:211], v174 offset:38912
	ds_read_b128 v[212:215], v174 offset:39936
	buffer_load_dwordx4 v170, s[12:15], s59 offen lds
	s_add_i32 s59, s53, 0x180000
	s_mov_b32 m0, s65
	s_nop 0
	buffer_load_dwordx4 v170, s[12:15], s59 offen lds
	s_waitcnt vmcnt(8)
	s_waitcnt lgkmcnt(0)
	s_setprio 1
	v_mfma_f32_16x16x32_bf16 v[126:129], v[130:133], v[184:187], v[126:129]
	s_barrier
	v_mfma_f32_16x16x32_bf16 v[126:129], v[134:137], v[188:191], v[126:129]
	v_mfma_f32_16x16x32_bf16 v[118:121], v[148:151], v[184:187], v[118:121]
	v_mfma_f32_16x16x32_bf16 v[118:121], v[152:155], v[188:191], v[118:121]
	v_mfma_f32_16x16x32_bf16 v[110:113], v[130:133], v[192:195], v[110:113]
	v_mfma_f32_16x16x32_bf16 v[110:113], v[134:137], v[196:199], v[110:113]
	v_mfma_f32_16x16x32_bf16 v[102:105], v[148:151], v[192:195], v[102:105]
	v_mfma_f32_16x16x32_bf16 v[102:105], v[152:155], v[196:199], v[102:105]
	v_mfma_f32_16x16x32_bf16 v[94:97], v[130:133], v[200:203], v[94:97]
	v_mfma_f32_16x16x32_bf16 v[94:97], v[134:137], v[204:207], v[94:97]
	v_mfma_f32_16x16x32_bf16 v[90:93], v[148:151], v[200:203], v[90:93]
	v_mfma_f32_16x16x32_bf16 v[90:93], v[152:155], v[204:207], v[90:93]
	v_mfma_f32_16x16x32_bf16 v[78:81], v[130:133], v[208:211], v[78:81]
	v_mfma_f32_16x16x32_bf16 v[78:81], v[134:137], v[212:215], v[78:81]
	v_mfma_f32_16x16x32_bf16 v[70:73], v[148:151], v[208:211], v[70:73]
	v_mfma_f32_16x16x32_bf16 v[70:73], v[152:155], v[212:215], v[70:73]
	v_mfma_f32_16x16x32_bf16 v[122:125], v[156:159], v[184:187], v[122:125]
	v_mfma_f32_16x16x32_bf16 v[122:125], v[160:163], v[188:191], v[122:125]
	v_mfma_f32_16x16x32_bf16 v[114:117], v[164:167], v[184:187], v[114:117]
	v_mfma_f32_16x16x32_bf16 v[114:117], v[180:183], v[188:191], v[114:117]
	v_mfma_f32_16x16x32_bf16 v[106:109], v[156:159], v[192:195], v[106:109]
	v_mfma_f32_16x16x32_bf16 v[106:109], v[160:163], v[196:199], v[106:109]
	v_mfma_f32_16x16x32_bf16 v[98:101], v[164:167], v[192:195], v[98:101]
	v_mfma_f32_16x16x32_bf16 v[98:101], v[180:183], v[196:199], v[98:101]
	v_mfma_f32_16x16x32_bf16 v[86:89], v[156:159], v[200:203], v[86:89]
	v_mfma_f32_16x16x32_bf16 v[86:89], v[160:163], v[204:207], v[86:89]
	v_mfma_f32_16x16x32_bf16 v[82:85], v[164:167], v[200:203], v[82:85]
	v_mfma_f32_16x16x32_bf16 v[82:85], v[180:183], v[204:207], v[82:85]
	s_barrier
	v_mfma_f32_16x16x32_bf16 v[74:77], v[156:159], v[208:211], v[74:77]
	v_mfma_f32_16x16x32_bf16 v[74:77], v[160:163], v[212:215], v[74:77]
	v_mfma_f32_16x16x32_bf16 v[66:69], v[164:167], v[208:211], v[66:69]
	v_mfma_f32_16x16x32_bf16 v[66:69], v[180:183], v[212:215], v[66:69]
	s_setprio 0
	s_mov_b32 m0, s70
	s_or_b32 s59, s58, 0x80
	ds_read_b128 v[184:187], v174 offset:49152
	ds_read_b128 v[188:191], v174 offset:50176
	ds_read_b128 v[192:195], v174 offset:51200
	ds_read_b128 v[196:199], v174 offset:52224
	ds_read_b128 v[200:203], v174 offset:53248
	ds_read_b128 v[204:207], v174 offset:54272
	ds_read_b128 v[208:211], v174 offset:55296
	ds_read_b128 v[212:215], v174 offset:56320
	buffer_load_dwordx4 v171, s[16:19], s59 offen lds
	s_add_i32 s59, s58, 0x80080
	s_mov_b32 m0, s71
	s_add_i32 s53, s53, 0x80080
	buffer_load_dwordx4 v171, s[16:19], s59 offen lds
	s_add_i32 s59, s58, 0x100080
	s_mov_b32 m0, s74
	s_add_i32 s58, s58, 0x180080
	buffer_load_dwordx4 v171, s[16:19], s59 offen lds
	s_mov_b32 m0, s75
	s_nop 0
	buffer_load_dwordx4 v171, s[16:19], s58 offen lds
	s_mov_b32 m0, s72
	s_nop 0
	buffer_load_dwordx4 v170, s[12:15], s57 offen lds
	s_mov_b32 m0, s73
	s_nop 0
	buffer_load_dwordx4 v170, s[12:15], s53 offen lds
	s_waitcnt vmcnt(8)
	s_waitcnt lgkmcnt(0)
	s_setprio 1
	v_mfma_f32_16x16x32_bf16 v[62:65], v[130:133], v[184:187], v[62:65]
	s_barrier
	v_mfma_f32_16x16x32_bf16 v[62:65], v[134:137], v[188:191], v[62:65]
	v_mfma_f32_16x16x32_bf16 v[54:57], v[148:151], v[184:187], v[54:57]
	v_mfma_f32_16x16x32_bf16 v[54:57], v[152:155], v[188:191], v[54:57]
	v_mfma_f32_16x16x32_bf16 v[46:49], v[130:133], v[192:195], v[46:49]
	v_mfma_f32_16x16x32_bf16 v[46:49], v[134:137], v[196:199], v[46:49]
	v_mfma_f32_16x16x32_bf16 v[38:41], v[148:151], v[192:195], v[38:41]
	v_mfma_f32_16x16x32_bf16 v[38:41], v[152:155], v[196:199], v[38:41]
	v_mfma_f32_16x16x32_bf16 v[30:33], v[130:133], v[200:203], v[30:33]
	v_mfma_f32_16x16x32_bf16 v[30:33], v[134:137], v[204:207], v[30:33]
	v_mfma_f32_16x16x32_bf16 v[22:25], v[148:151], v[200:203], v[22:25]
	v_mfma_f32_16x16x32_bf16 v[22:25], v[152:155], v[204:207], v[22:25]
	v_mfma_f32_16x16x32_bf16 v[14:17], v[130:133], v[208:211], v[14:17]
	v_mfma_f32_16x16x32_bf16 v[14:17], v[134:137], v[212:215], v[14:17]
	v_mfma_f32_16x16x32_bf16 v[6:9], v[148:151], v[208:211], v[6:9]
	v_mfma_f32_16x16x32_bf16 v[6:9], v[152:155], v[212:215], v[6:9]
	v_mfma_f32_16x16x32_bf16 v[58:61], v[156:159], v[184:187], v[58:61]
	v_mfma_f32_16x16x32_bf16 v[58:61], v[160:163], v[188:191], v[58:61]
	v_mfma_f32_16x16x32_bf16 v[50:53], v[164:167], v[184:187], v[50:53]
	v_mfma_f32_16x16x32_bf16 v[50:53], v[180:183], v[188:191], v[50:53]
	v_mfma_f32_16x16x32_bf16 v[42:45], v[156:159], v[192:195], v[42:45]
	v_mfma_f32_16x16x32_bf16 v[42:45], v[160:163], v[196:199], v[42:45]
	v_mfma_f32_16x16x32_bf16 v[34:37], v[164:167], v[192:195], v[34:37]
	v_mfma_f32_16x16x32_bf16 v[34:37], v[180:183], v[196:199], v[34:37]
	v_mfma_f32_16x16x32_bf16 v[26:29], v[156:159], v[200:203], v[26:29]
	v_mfma_f32_16x16x32_bf16 v[26:29], v[160:163], v[204:207], v[26:29]
	v_mfma_f32_16x16x32_bf16 v[18:21], v[164:167], v[200:203], v[18:21]
	v_mfma_f32_16x16x32_bf16 v[18:21], v[180:183], v[204:207], v[18:21]
	s_barrier
	v_mfma_f32_16x16x32_bf16 v[10:13], v[156:159], v[208:211], v[10:13]
	v_mfma_f32_16x16x32_bf16 v[10:13], v[160:163], v[212:215], v[10:13]
	v_mfma_f32_16x16x32_bf16 v[2:5], v[164:167], v[208:211], v[2:5]
	v_mfma_f32_16x16x32_bf16 v[2:5], v[180:183], v[212:215], v[2:5]
	s_setprio 0
	s_add_i32 s52, s52, 2
	s_addk_i32 s8, 0x100
	s_addk_i32 s9, 0x100
	s_cmp_ge_i32 s52, s21
	s_cbranch_scc0 .LBB0_892
	s_and_b64 vcc, exec, s[48:49]
	s_cbranch_vccz .LBB0_895

.LBB0_1020:
	v_add_u32_e32 v142, 0x10000, v162
	v_add_u32_e32 v150, 0x14000, v162
	ds_read_b128 v[130:133], v142
	ds_read_b128 v[134:137], v142 offset:1024
	ds_read_b128 v[138:141], v142 offset:2048
	ds_read_b128 v[142:145], v142 offset:3072
	ds_read_b128 v[154:157], v150
	ds_read_b128 v[164:167], v150 offset:1024
	ds_read_b128 v[168:171], v150 offset:2048
	ds_read_b128 v[172:175], v150 offset:3072
	s_add_i32 s90, s6, 0x100
	s_add_i32 s7, s88, s6
	s_cmp_eq_u32 s81, s89
	s_cselect_b32 s91, 0, s90
	s_cselect_b32 s93, s87, s7
	s_add_i32 s91, s91, s70
	s_or_b32 s92, s91, 0x80
	s_add_i32 s6, s3, s6
	s_mov_b32 m0, s82
	s_add_i32 s7, s6, 0x20080
	ds_read_b128 v[176:179], v163
	ds_read_b128 v[180:183], v163 offset:1024
	ds_read_b128 v[184:187], v163 offset:2048
	ds_read_b128 v[188:191], v163 offset:3072
	ds_read_b128 v[192:195], v163 offset:4096
	ds_read_b128 v[196:199], v163 offset:5120
	ds_read_b128 v[200:203], v163 offset:6144
	ds_read_b128 v[204:207], v163 offset:7168
	buffer_load_dwordx4 v161, s[12:15], s7 offen lds
	s_add_i32 s6, s6, 0x30080
	s_mov_b32 m0, s83
	s_nop 0
	buffer_load_dwordx4 v161, s[12:15], s6 offen lds
	s_waitcnt vmcnt(8)
	s_waitcnt lgkmcnt(0)
	s_setprio 1
	v_mfma_f32_16x16x32_bf16 v[126:129], v[130:133], v[176:179], v[126:129]
	s_barrier
	v_mfma_f32_16x16x32_bf16 v[126:129], v[134:137], v[180:183], v[126:129]
	v_mfma_f32_16x16x32_bf16 v[122:125], v[138:141], v[176:179], v[122:125]
	v_mfma_f32_16x16x32_bf16 v[122:125], v[142:145], v[180:183], v[122:125]
	v_mfma_f32_16x16x32_bf16 v[110:113], v[130:133], v[184:187], v[110:113]
	v_mfma_f32_16x16x32_bf16 v[110:113], v[134:137], v[188:191], v[110:113]
	v_mfma_f32_16x16x32_bf16 v[106:109], v[138:141], v[184:187], v[106:109]
	v_mfma_f32_16x16x32_bf16 v[106:109], v[142:145], v[188:191], v[106:109]
	v_mfma_f32_16x16x32_bf16 v[94:97], v[130:133], v[192:195], v[94:97]
	v_mfma_f32_16x16x32_bf16 v[94:97], v[134:137], v[196:199], v[94:97]
	v_mfma_f32_16x16x32_bf16 v[90:93], v[138:141], v[192:195], v[90:93]
	v_mfma_f32_16x16x32_bf16 v[90:93], v[142:145], v[196:199], v[90:93]
	v_mfma_f32_16x16x32_bf16 v[78:81], v[130:133], v[200:203], v[78:81]
	v_mfma_f32_16x16x32_bf16 v[78:81], v[134:137], v[204:207], v[78:81]
	v_mfma_f32_16x16x32_bf16 v[74:77], v[138:141], v[200:203], v[74:77]
	v_mfma_f32_16x16x32_bf16 v[74:77], v[142:145], v[204:207], v[74:77]
	v_mfma_f32_16x16x32_bf16 v[118:121], v[154:157], v[176:179], v[118:121]
	v_mfma_f32_16x16x32_bf16 v[118:121], v[164:167], v[180:183], v[118:121]
	v_mfma_f32_16x16x32_bf16 v[114:117], v[168:171], v[176:179], v[114:117]
	v_mfma_f32_16x16x32_bf16 v[114:117], v[172:175], v[180:183], v[114:117]
	v_mfma_f32_16x16x32_bf16 v[102:105], v[154:157], v[184:187], v[102:105]
	v_mfma_f32_16x16x32_bf16 v[102:105], v[164:167], v[188:191], v[102:105]
	v_mfma_f32_16x16x32_bf16 v[98:101], v[168:171], v[184:187], v[98:101]
	v_mfma_f32_16x16x32_bf16 v[98:101], v[172:175], v[188:191], v[98:101]
	v_mfma_f32_16x16x32_bf16 v[86:89], v[154:157], v[192:195], v[86:89]
	v_mfma_f32_16x16x32_bf16 v[86:89], v[164:167], v[196:199], v[86:89]
	v_mfma_f32_16x16x32_bf16 v[82:85], v[168:171], v[192:195], v[82:85]
	v_mfma_f32_16x16x32_bf16 v[82:85], v[172:175], v[196:199], v[82:85]
	s_barrier
	v_mfma_f32_16x16x32_bf16 v[70:73], v[154:157], v[200:203], v[70:73]
	v_mfma_f32_16x16x32_bf16 v[70:73], v[164:167], v[204:207], v[70:73]
	v_mfma_f32_16x16x32_bf16 v[66:69], v[168:171], v[200:203], v[66:69]
	v_mfma_f32_16x16x32_bf16 v[66:69], v[172:175], v[204:207], v[66:69]
	s_setprio 0
	s_mov_b32 m0, s66
	s_mov_b32 s6, s14
	s_mov_b32 s7, s15
	ds_read_b128 v[176:179], v163 offset:16384
	ds_read_b128 v[180:183], v163 offset:17408
	ds_read_b128 v[184:187], v163 offset:18432
	ds_read_b128 v[188:191], v163 offset:19456
	ds_read_b128 v[192:195], v163 offset:20480
	ds_read_b128 v[196:199], v163 offset:21504
	ds_read_b128 v[200:203], v163 offset:22528
	ds_read_b128 v[204:207], v163 offset:23552
	buffer_load_dwordx4 v160, s[4:7], s93 offen lds
	s_add_i32 s94, s93, 0x10000
	s_mov_b32 m0, s67
	s_nop 0
	buffer_load_dwordx4 v160, s[4:7], s94 offen lds
	s_add_i32 s94, s93, 0x20000
	s_mov_b32 m0, s68
	s_nop 0
	buffer_load_dwordx4 v160, s[4:7], s94 offen lds
	s_add_i32 s94, s93, 0x30000
	s_mov_b32 m0, s69
	s_nop 0
	buffer_load_dwordx4 v160, s[4:7], s94 offen lds
	s_mov_b32 m0, s65
	s_add_i32 s94, s91, 0x10000
	buffer_load_dwordx4 v161, s[12:15], s91 offen lds
	s_mov_b32 m0, s71
	s_nop 0
	buffer_load_dwordx4 v161, s[12:15], s94 offen lds
	s_waitcnt vmcnt(8)
	s_waitcnt lgkmcnt(0)
	s_setprio 1
	v_mfma_f32_16x16x32_bf16 v[62:65], v[130:133], v[176:179], v[62:65]
	s_barrier
	v_mfma_f32_16x16x32_bf16 v[62:65], v[134:137], v[180:183], v[62:65]
	v_mfma_f32_16x16x32_bf16 v[58:61], v[138:141], v[176:179], v[58:61]
	v_mfma_f32_16x16x32_bf16 v[58:61], v[142:145], v[180:183], v[58:61]
	v_mfma_f32_16x16x32_bf16 v[46:49], v[130:133], v[184:187], v[46:49]
	v_mfma_f32_16x16x32_bf16 v[46:49], v[134:137], v[188:191], v[46:49]
	v_mfma_f32_16x16x32_bf16 v[42:45], v[138:141], v[184:187], v[42:45]
	v_mfma_f32_16x16x32_bf16 v[42:45], v[142:145], v[188:191], v[42:45]
	v_mfma_f32_16x16x32_bf16 v[30:33], v[130:133], v[192:195], v[30:33]
	v_mfma_f32_16x16x32_bf16 v[30:33], v[134:137], v[196:199], v[30:33]
	v_mfma_f32_16x16x32_bf16 v[26:29], v[138:141], v[192:195], v[26:29]
	v_mfma_f32_16x16x32_bf16 v[26:29], v[142:145], v[196:199], v[26:29]
	v_mfma_f32_16x16x32_bf16 v[14:17], v[130:133], v[200:203], v[14:17]
	v_mfma_f32_16x16x32_bf16 v[14:17], v[134:137], v[204:207], v[14:17]
	v_mfma_f32_16x16x32_bf16 v[10:13], v[138:141], v[200:203], v[10:13]
	v_mfma_f32_16x16x32_bf16 v[10:13], v[142:145], v[204:207], v[10:13]
	v_mfma_f32_16x16x32_bf16 v[54:57], v[154:157], v[176:179], v[54:57]
	v_mfma_f32_16x16x32_bf16 v[54:57], v[164:167], v[180:183], v[54:57]
	v_mfma_f32_16x16x32_bf16 v[50:53], v[168:171], v[176:179], v[50:53]
	v_mfma_f32_16x16x32_bf16 v[50:53], v[172:175], v[180:183], v[50:53]
	v_mfma_f32_16x16x32_bf16 v[38:41], v[154:157], v[184:187], v[38:41]
	v_mfma_f32_16x16x32_bf16 v[38:41], v[164:167], v[188:191], v[38:41]
	v_mfma_f32_16x16x32_bf16 v[34:37], v[168:171], v[184:187], v[34:37]
	v_mfma_f32_16x16x32_bf16 v[34:37], v[172:175], v[188:191], v[34:37]
	v_mfma_f32_16x16x32_bf16 v[22:25], v[154:157], v[192:195], v[22:25]
	v_mfma_f32_16x16x32_bf16 v[22:25], v[164:167], v[196:199], v[22:25]
	v_mfma_f32_16x16x32_bf16 v[18:21], v[168:171], v[192:195], v[18:21]
	v_mfma_f32_16x16x32_bf16 v[18:21], v[172:175], v[196:199], v[18:21]
	s_barrier
	v_mfma_f32_16x16x32_bf16 v[6:9], v[154:157], v[200:203], v[6:9]
	v_mfma_f32_16x16x32_bf16 v[6:9], v[164:167], v[204:207], v[6:9]
	v_mfma_f32_16x16x32_bf16 v[2:5], v[168:171], v[200:203], v[2:5]
	v_mfma_f32_16x16x32_bf16 v[2:5], v[172:175], v[204:207], v[2:5]
	s_setprio 0
	v_add_u32_e32 v142, 0x18000, v162
	v_add_u32_e32 v150, 0x1c000, v162
	ds_read_b128 v[130:133], v142
	ds_read_b128 v[134:137], v142 offset:1024
	ds_read_b128 v[138:141], v142 offset:2048
	ds_read_b128 v[142:145], v142 offset:3072
	ds_read_b128 v[154:157], v150
	ds_read_b128 v[164:167], v150 offset:1024
	ds_read_b128 v[168:171], v150 offset:2048
	ds_read_b128 v[172:175], v150 offset:3072
	s_mov_b32 m0, s72
	s_add_i32 s94, s91, 0x20000
	ds_read_b128 v[176:179], v163 offset:32768
	ds_read_b128 v[180:183], v163 offset:33792
	ds_read_b128 v[184:187], v163 offset:34816
	ds_read_b128 v[188:191], v163 offset:35840
	ds_read_b128 v[192:195], v163 offset:36864
	ds_read_b128 v[196:199], v163 offset:37888
	ds_read_b128 v[200:203], v163 offset:38912
	ds_read_b128 v[204:207], v163 offset:39936
	buffer_load_dwordx4 v161, s[12:15], s94 offen lds
	s_add_i32 s94, s91, 0x30000
	s_mov_b32 m0, s73
	s_nop 0
	buffer_load_dwordx4 v161, s[12:15], s94 offen lds
	s_waitcnt vmcnt(8)
	s_waitcnt lgkmcnt(0)
	s_setprio 1
	v_mfma_f32_16x16x32_bf16 v[126:129], v[130:133], v[176:179], v[126:129]
	s_barrier
	v_mfma_f32_16x16x32_bf16 v[126:129], v[134:137], v[180:183], v[126:129]
	v_mfma_f32_16x16x32_bf16 v[122:125], v[138:141], v[176:179], v[122:125]
	v_mfma_f32_16x16x32_bf16 v[122:125], v[142:145], v[180:183], v[122:125]
	v_mfma_f32_16x16x32_bf16 v[110:113], v[130:133], v[184:187], v[110:113]
	v_mfma_f32_16x16x32_bf16 v[110:113], v[134:137], v[188:191], v[110:113]
	v_mfma_f32_16x16x32_bf16 v[106:109], v[138:141], v[184:187], v[106:109]
	v_mfma_f32_16x16x32_bf16 v[106:109], v[142:145], v[188:191], v[106:109]
	v_mfma_f32_16x16x32_bf16 v[94:97], v[130:133], v[192:195], v[94:97]
	v_mfma_f32_16x16x32_bf16 v[94:97], v[134:137], v[196:199], v[94:97]
	v_mfma_f32_16x16x32_bf16 v[90:93], v[138:141], v[192:195], v[90:93]
	v_mfma_f32_16x16x32_bf16 v[90:93], v[142:145], v[196:199], v[90:93]
	v_mfma_f32_16x16x32_bf16 v[78:81], v[130:133], v[200:203], v[78:81]
	v_mfma_f32_16x16x32_bf16 v[78:81], v[134:137], v[204:207], v[78:81]
	v_mfma_f32_16x16x32_bf16 v[74:77], v[138:141], v[200:203], v[74:77]
	v_mfma_f32_16x16x32_bf16 v[74:77], v[142:145], v[204:207], v[74:77]
	v_mfma_f32_16x16x32_bf16 v[118:121], v[154:157], v[176:179], v[118:121]
	v_mfma_f32_16x16x32_bf16 v[118:121], v[164:167], v[180:183], v[118:121]
	v_mfma_f32_16x16x32_bf16 v[114:117], v[168:171], v[176:179], v[114:117]
	v_mfma_f32_16x16x32_bf16 v[114:117], v[172:175], v[180:183], v[114:117]
	v_mfma_f32_16x16x32_bf16 v[102:105], v[154:157], v[184:187], v[102:105]
	v_mfma_f32_16x16x32_bf16 v[102:105], v[164:167], v[188:191], v[102:105]
	v_mfma_f32_16x16x32_bf16 v[98:101], v[168:171], v[184:187], v[98:101]
	v_mfma_f32_16x16x32_bf16 v[98:101], v[172:175], v[188:191], v[98:101]
	v_mfma_f32_16x16x32_bf16 v[86:89], v[154:157], v[192:195], v[86:89]
	v_mfma_f32_16x16x32_bf16 v[86:89], v[164:167], v[196:199], v[86:89]
	v_mfma_f32_16x16x32_bf16 v[82:85], v[168:171], v[192:195], v[82:85]
	v_mfma_f32_16x16x32_bf16 v[82:85], v[172:175], v[196:199], v[82:85]
	s_barrier
	v_mfma_f32_16x16x32_bf16 v[70:73], v[154:157], v[200:203], v[70:73]
	v_mfma_f32_16x16x32_bf16 v[70:73], v[164:167], v[204:207], v[70:73]
	v_mfma_f32_16x16x32_bf16 v[66:69], v[168:171], v[200:203], v[66:69]
	v_mfma_f32_16x16x32_bf16 v[66:69], v[172:175], v[204:207], v[66:69]
	s_setprio 0
	s_mov_b32 m0, s74
	s_or_b32 s94, s93, 0x80
	ds_read_b128 v[176:179], v163 offset:49152
	ds_read_b128 v[180:183], v163 offset:50176
	ds_read_b128 v[184:187], v163 offset:51200
	ds_read_b128 v[188:191], v163 offset:52224
	ds_read_b128 v[192:195], v163 offset:53248
	ds_read_b128 v[196:199], v163 offset:54272
	ds_read_b128 v[200:203], v163 offset:55296
	ds_read_b128 v[204:207], v163 offset:56320
	buffer_load_dwordx4 v160, s[4:7], s94 offen lds
	s_add_i32 s94, s93, 0x10080
	s_mov_b32 m0, s75
	s_add_i32 s91, s91, 0x10080
	buffer_load_dwordx4 v160, s[4:7], s94 offen lds
	s_add_i32 s94, s93, 0x20080
	s_mov_b32 m0, s78
	s_add_i32 s93, s93, 0x30080
	buffer_load_dwordx4 v160, s[4:7], s94 offen lds
	s_mov_b32 m0, s79
	s_nop 0
	buffer_load_dwordx4 v160, s[4:7], s93 offen lds
	s_mov_b32 m0, s76
	s_nop 0
	buffer_load_dwordx4 v161, s[12:15], s92 offen lds
	s_mov_b32 m0, s77
	s_nop 0
	buffer_load_dwordx4 v161, s[12:15], s91 offen lds
	s_waitcnt vmcnt(8)
	s_waitcnt lgkmcnt(0)
	s_setprio 1
	v_mfma_f32_16x16x32_bf16 v[62:65], v[130:133], v[176:179], v[62:65]
	s_barrier
	v_mfma_f32_16x16x32_bf16 v[62:65], v[134:137], v[180:183], v[62:65]
	v_mfma_f32_16x16x32_bf16 v[58:61], v[138:141], v[176:179], v[58:61]
	v_mfma_f32_16x16x32_bf16 v[58:61], v[142:145], v[180:183], v[58:61]
	v_mfma_f32_16x16x32_bf16 v[46:49], v[130:133], v[184:187], v[46:49]
	v_mfma_f32_16x16x32_bf16 v[46:49], v[134:137], v[188:191], v[46:49]
	v_mfma_f32_16x16x32_bf16 v[42:45], v[138:141], v[184:187], v[42:45]
	v_mfma_f32_16x16x32_bf16 v[42:45], v[142:145], v[188:191], v[42:45]
	v_mfma_f32_16x16x32_bf16 v[30:33], v[130:133], v[192:195], v[30:33]
	v_mfma_f32_16x16x32_bf16 v[30:33], v[134:137], v[196:199], v[30:33]
	v_mfma_f32_16x16x32_bf16 v[26:29], v[138:141], v[192:195], v[26:29]
	v_mfma_f32_16x16x32_bf16 v[26:29], v[142:145], v[196:199], v[26:29]
	v_mfma_f32_16x16x32_bf16 v[14:17], v[130:133], v[200:203], v[14:17]
	v_mfma_f32_16x16x32_bf16 v[14:17], v[134:137], v[204:207], v[14:17]
	v_mfma_f32_16x16x32_bf16 v[10:13], v[138:141], v[200:203], v[10:13]
	v_mfma_f32_16x16x32_bf16 v[10:13], v[142:145], v[204:207], v[10:13]
	v_mfma_f32_16x16x32_bf16 v[54:57], v[154:157], v[176:179], v[54:57]
	v_mfma_f32_16x16x32_bf16 v[54:57], v[164:167], v[180:183], v[54:57]
	v_mfma_f32_16x16x32_bf16 v[50:53], v[168:171], v[176:179], v[50:53]
	v_mfma_f32_16x16x32_bf16 v[50:53], v[172:175], v[180:183], v[50:53]
	v_mfma_f32_16x16x32_bf16 v[38:41], v[154:157], v[184:187], v[38:41]
	v_mfma_f32_16x16x32_bf16 v[38:41], v[164:167], v[188:191], v[38:41]
	v_mfma_f32_16x16x32_bf16 v[34:37], v[168:171], v[184:187], v[34:37]
	v_mfma_f32_16x16x32_bf16 v[34:37], v[172:175], v[188:191], v[34:37]
	v_mfma_f32_16x16x32_bf16 v[22:25], v[154:157], v[192:195], v[22:25]
	v_mfma_f32_16x16x32_bf16 v[22:25], v[164:167], v[196:199], v[22:25]
	v_mfma_f32_16x16x32_bf16 v[18:21], v[168:171], v[192:195], v[18:21]
	v_mfma_f32_16x16x32_bf16 v[18:21], v[172:175], v[196:199], v[18:21]
	s_barrier
	v_mfma_f32_16x16x32_bf16 v[6:9], v[154:157], v[200:203], v[6:9]
	v_mfma_f32_16x16x32_bf16 v[6:9], v[164:167], v[204:207], v[6:9]
	v_mfma_f32_16x16x32_bf16 v[2:5], v[168:171], v[200:203], v[2:5]
	v_mfma_f32_16x16x32_bf16 v[2:5], v[172:175], v[204:207], v[2:5]
	s_setprio 0
	s_add_i32 s89, s89, 2
	s_cmp_ge_i32 s89, s63
	s_mov_b32 s6, s90
	s_cbranch_scc0 .LBB0_1020
	s_and_b64 vcc, exec, s[54:55]
	s_cbranch_vccz .LBB0_1023

.LBB0_1035:
	ds_read_b128 v[140:143], v134
	ds_read_b128 v[148:151], v134 offset:1024
	ds_read_b128 v[152:155], v134 offset:2048
	ds_read_b128 v[156:159], v134 offset:3072
	ds_read_b128 v[160:163], v135
	ds_read_b128 v[164:167], v135 offset:1024
	ds_read_b128 v[168:171], v135 offset:2048
	ds_read_b128 v[172:175], v135 offset:3072
	s_add_i32 s73, s70, 0xfffb8080
	s_cmp_eq_u32 s53, s72
	s_cselect_b32 s73, s68, s73
	s_cselect_b32 s75, s69, s71
	s_add_i32 s74, s73, 0x80
	s_add_i32 s76, s70, 0xfffe8000
	s_mov_b32 m0, s54
	ds_read_b128 v[176:179], v136
	ds_read_b128 v[180:183], v136 offset:1024
	ds_read_b128 v[184:187], v136 offset:2048
	ds_read_b128 v[188:191], v136 offset:3072
	ds_read_b128 v[192:195], v136 offset:4096
	ds_read_b128 v[196:199], v136 offset:5120
	ds_read_b128 v[200:203], v136 offset:6144
	ds_read_b128 v[204:207], v136 offset:7168
	buffer_load_dwordx4 v132, s[12:15], s76 offen lds
	s_mov_b32 m0, s55
	s_nop 0
	buffer_load_dwordx4 v132, s[12:15], s70 offen lds
	s_waitcnt vmcnt(8)
	s_waitcnt lgkmcnt(0)
	s_setprio 1
	v_mfma_f32_16x16x32_bf16 v[126:129], v[140:143], v[176:179], v[126:129]
	s_barrier
	v_mfma_f32_16x16x32_bf16 v[126:129], v[148:151], v[180:183], v[126:129]
	v_mfma_f32_16x16x32_bf16 v[122:125], v[152:155], v[176:179], v[122:125]
	v_mfma_f32_16x16x32_bf16 v[122:125], v[156:159], v[180:183], v[122:125]
	v_mfma_f32_16x16x32_bf16 v[110:113], v[140:143], v[184:187], v[110:113]
	v_mfma_f32_16x16x32_bf16 v[110:113], v[148:151], v[188:191], v[110:113]
	v_mfma_f32_16x16x32_bf16 v[106:109], v[152:155], v[184:187], v[106:109]
	v_mfma_f32_16x16x32_bf16 v[106:109], v[156:159], v[188:191], v[106:109]
	v_mfma_f32_16x16x32_bf16 v[94:97], v[140:143], v[192:195], v[94:97]
	v_mfma_f32_16x16x32_bf16 v[94:97], v[148:151], v[196:199], v[94:97]
	v_mfma_f32_16x16x32_bf16 v[90:93], v[152:155], v[192:195], v[90:93]
	v_mfma_f32_16x16x32_bf16 v[90:93], v[156:159], v[196:199], v[90:93]
	v_mfma_f32_16x16x32_bf16 v[78:81], v[140:143], v[200:203], v[78:81]
	v_mfma_f32_16x16x32_bf16 v[78:81], v[148:151], v[204:207], v[78:81]
	v_mfma_f32_16x16x32_bf16 v[74:77], v[152:155], v[200:203], v[74:77]
	v_mfma_f32_16x16x32_bf16 v[74:77], v[156:159], v[204:207], v[74:77]
	v_mfma_f32_16x16x32_bf16 v[118:121], v[160:163], v[176:179], v[118:121]
	v_mfma_f32_16x16x32_bf16 v[118:121], v[164:167], v[180:183], v[118:121]
	v_mfma_f32_16x16x32_bf16 v[114:117], v[168:171], v[176:179], v[114:117]
	v_mfma_f32_16x16x32_bf16 v[114:117], v[172:175], v[180:183], v[114:117]
	v_mfma_f32_16x16x32_bf16 v[102:105], v[160:163], v[184:187], v[102:105]
	v_mfma_f32_16x16x32_bf16 v[102:105], v[164:167], v[188:191], v[102:105]
	v_mfma_f32_16x16x32_bf16 v[98:101], v[168:171], v[184:187], v[98:101]
	v_mfma_f32_16x16x32_bf16 v[98:101], v[172:175], v[188:191], v[98:101]
	v_mfma_f32_16x16x32_bf16 v[86:89], v[160:163], v[192:195], v[86:89]
	v_mfma_f32_16x16x32_bf16 v[86:89], v[164:167], v[196:199], v[86:89]
	v_mfma_f32_16x16x32_bf16 v[82:85], v[168:171], v[192:195], v[82:85]
	v_mfma_f32_16x16x32_bf16 v[82:85], v[172:175], v[196:199], v[82:85]
	s_barrier
	v_mfma_f32_16x16x32_bf16 v[70:73], v[160:163], v[200:203], v[70:73]
	v_mfma_f32_16x16x32_bf16 v[70:73], v[164:167], v[204:207], v[70:73]
	v_mfma_f32_16x16x32_bf16 v[66:69], v[168:171], v[200:203], v[66:69]
	v_mfma_f32_16x16x32_bf16 v[66:69], v[172:175], v[204:207], v[66:69]
	s_setprio 0
	s_mov_b32 m0, s30
	ds_read_b128 v[176:179], v136 offset:16384
	ds_read_b128 v[180:183], v136 offset:17408
	ds_read_b128 v[184:187], v136 offset:18432
	ds_read_b128 v[188:191], v136 offset:19456
	ds_read_b128 v[192:195], v136 offset:20480
	ds_read_b128 v[196:199], v136 offset:21504
	ds_read_b128 v[200:203], v136 offset:22528
	ds_read_b128 v[204:207], v136 offset:23552
	buffer_load_dwordx4 v133, s[16:19], s75 offen lds
	s_add_i32 s76, s75, 0x200000
	s_mov_b32 m0, s31
	s_nop 0
	buffer_load_dwordx4 v133, s[16:19], s76 offen lds
	s_add_i32 s76, s75, 0x400000
	s_mov_b32 m0, s35
	s_nop 0
	buffer_load_dwordx4 v133, s[16:19], s76 offen lds
	s_add_i32 s76, s75, 0x600000
	s_mov_b32 m0, s42
	s_nop 0
	buffer_load_dwordx4 v133, s[16:19], s76 offen lds
	s_mov_b32 m0, s27
	s_add_i32 s76, s73, 0x18000
	buffer_load_dwordx4 v132, s[12:15], s73 offen lds
	s_mov_b32 m0, s43
	s_nop 0
	buffer_load_dwordx4 v132, s[12:15], s76 offen lds
	s_waitcnt vmcnt(8)
	s_waitcnt lgkmcnt(0)
	s_setprio 1
	v_mfma_f32_16x16x32_bf16 v[62:65], v[140:143], v[176:179], v[62:65]
	s_barrier
	v_mfma_f32_16x16x32_bf16 v[62:65], v[148:151], v[180:183], v[62:65]
	v_mfma_f32_16x16x32_bf16 v[58:61], v[152:155], v[176:179], v[58:61]
	v_mfma_f32_16x16x32_bf16 v[58:61], v[156:159], v[180:183], v[58:61]
	v_mfma_f32_16x16x32_bf16 v[46:49], v[140:143], v[184:187], v[46:49]
	v_mfma_f32_16x16x32_bf16 v[46:49], v[148:151], v[188:191], v[46:49]
	v_mfma_f32_16x16x32_bf16 v[42:45], v[152:155], v[184:187], v[42:45]
	v_mfma_f32_16x16x32_bf16 v[42:45], v[156:159], v[188:191], v[42:45]
	v_mfma_f32_16x16x32_bf16 v[30:33], v[140:143], v[192:195], v[30:33]
	v_mfma_f32_16x16x32_bf16 v[30:33], v[148:151], v[196:199], v[30:33]
	v_mfma_f32_16x16x32_bf16 v[26:29], v[152:155], v[192:195], v[26:29]
	v_mfma_f32_16x16x32_bf16 v[26:29], v[156:159], v[196:199], v[26:29]
	v_mfma_f32_16x16x32_bf16 v[14:17], v[140:143], v[200:203], v[14:17]
	v_mfma_f32_16x16x32_bf16 v[14:17], v[148:151], v[204:207], v[14:17]
	v_mfma_f32_16x16x32_bf16 v[10:13], v[152:155], v[200:203], v[10:13]
	v_mfma_f32_16x16x32_bf16 v[10:13], v[156:159], v[204:207], v[10:13]
	v_mfma_f32_16x16x32_bf16 v[54:57], v[160:163], v[176:179], v[54:57]
	v_mfma_f32_16x16x32_bf16 v[54:57], v[164:167], v[180:183], v[54:57]
	v_mfma_f32_16x16x32_bf16 v[50:53], v[168:171], v[176:179], v[50:53]
	v_mfma_f32_16x16x32_bf16 v[50:53], v[172:175], v[180:183], v[50:53]
	v_mfma_f32_16x16x32_bf16 v[38:41], v[160:163], v[184:187], v[38:41]
	v_mfma_f32_16x16x32_bf16 v[38:41], v[164:167], v[188:191], v[38:41]
	v_mfma_f32_16x16x32_bf16 v[34:37], v[168:171], v[184:187], v[34:37]
	v_mfma_f32_16x16x32_bf16 v[34:37], v[172:175], v[188:191], v[34:37]
	v_mfma_f32_16x16x32_bf16 v[22:25], v[160:163], v[192:195], v[22:25]
	v_mfma_f32_16x16x32_bf16 v[22:25], v[164:167], v[196:199], v[22:25]
	v_mfma_f32_16x16x32_bf16 v[18:21], v[168:171], v[192:195], v[18:21]
	v_mfma_f32_16x16x32_bf16 v[18:21], v[172:175], v[196:199], v[18:21]
	s_barrier
	v_mfma_f32_16x16x32_bf16 v[6:9], v[160:163], v[200:203], v[6:9]
	v_mfma_f32_16x16x32_bf16 v[6:9], v[164:167], v[204:207], v[6:9]
	v_mfma_f32_16x16x32_bf16 v[2:5], v[168:171], v[200:203], v[2:5]
	v_mfma_f32_16x16x32_bf16 v[2:5], v[172:175], v[204:207], v[2:5]
	s_setprio 0
	ds_read_b128 v[140:143], v137
	ds_read_b128 v[148:151], v137 offset:1024
	ds_read_b128 v[152:155], v137 offset:2048
	ds_read_b128 v[156:159], v137 offset:3072
	ds_read_b128 v[160:163], v138
	ds_read_b128 v[164:167], v138 offset:1024
	ds_read_b128 v[168:171], v138 offset:2048
	ds_read_b128 v[172:175], v138 offset:3072
	s_mov_b32 m0, s44
	s_add_i32 s76, s73, 0x30000
	ds_read_b128 v[176:179], v136 offset:32768
	ds_read_b128 v[180:183], v136 offset:33792
	ds_read_b128 v[184:187], v136 offset:34816
	ds_read_b128 v[188:191], v136 offset:35840
	ds_read_b128 v[192:195], v136 offset:36864
	ds_read_b128 v[196:199], v136 offset:37888
	ds_read_b128 v[200:203], v136 offset:38912
	ds_read_b128 v[204:207], v136 offset:39936
	buffer_load_dwordx4 v132, s[12:15], s76 offen lds
	s_add_i32 s76, s73, 0x48000
	s_mov_b32 m0, s45
	s_nop 0
	buffer_load_dwordx4 v132, s[12:15], s76 offen lds
	s_waitcnt vmcnt(8)
	s_waitcnt lgkmcnt(0)
	s_setprio 1
	v_mfma_f32_16x16x32_bf16 v[126:129], v[140:143], v[176:179], v[126:129]
	s_barrier
	v_mfma_f32_16x16x32_bf16 v[126:129], v[148:151], v[180:183], v[126:129]
	v_mfma_f32_16x16x32_bf16 v[122:125], v[152:155], v[176:179], v[122:125]
	v_mfma_f32_16x16x32_bf16 v[122:125], v[156:159], v[180:183], v[122:125]
	v_mfma_f32_16x16x32_bf16 v[110:113], v[140:143], v[184:187], v[110:113]
	v_mfma_f32_16x16x32_bf16 v[110:113], v[148:151], v[188:191], v[110:113]
	v_mfma_f32_16x16x32_bf16 v[106:109], v[152:155], v[184:187], v[106:109]
	v_mfma_f32_16x16x32_bf16 v[106:109], v[156:159], v[188:191], v[106:109]
	v_mfma_f32_16x16x32_bf16 v[94:97], v[140:143], v[192:195], v[94:97]
	v_mfma_f32_16x16x32_bf16 v[94:97], v[148:151], v[196:199], v[94:97]
	v_mfma_f32_16x16x32_bf16 v[90:93], v[152:155], v[192:195], v[90:93]
	v_mfma_f32_16x16x32_bf16 v[90:93], v[156:159], v[196:199], v[90:93]
	v_mfma_f32_16x16x32_bf16 v[78:81], v[140:143], v[200:203], v[78:81]
	v_mfma_f32_16x16x32_bf16 v[78:81], v[148:151], v[204:207], v[78:81]
	v_mfma_f32_16x16x32_bf16 v[74:77], v[152:155], v[200:203], v[74:77]
	v_mfma_f32_16x16x32_bf16 v[74:77], v[156:159], v[204:207], v[74:77]
	v_mfma_f32_16x16x32_bf16 v[118:121], v[160:163], v[176:179], v[118:121]
	v_mfma_f32_16x16x32_bf16 v[118:121], v[164:167], v[180:183], v[118:121]
	v_mfma_f32_16x16x32_bf16 v[114:117], v[168:171], v[176:179], v[114:117]
	v_mfma_f32_16x16x32_bf16 v[114:117], v[172:175], v[180:183], v[114:117]
	v_mfma_f32_16x16x32_bf16 v[102:105], v[160:163], v[184:187], v[102:105]
	v_mfma_f32_16x16x32_bf16 v[102:105], v[164:167], v[188:191], v[102:105]
	v_mfma_f32_16x16x32_bf16 v[98:101], v[168:171], v[184:187], v[98:101]
	v_mfma_f32_16x16x32_bf16 v[98:101], v[172:175], v[188:191], v[98:101]
	v_mfma_f32_16x16x32_bf16 v[86:89], v[160:163], v[192:195], v[86:89]
	v_mfma_f32_16x16x32_bf16 v[86:89], v[164:167], v[196:199], v[86:89]
	v_mfma_f32_16x16x32_bf16 v[82:85], v[168:171], v[192:195], v[82:85]
	v_mfma_f32_16x16x32_bf16 v[82:85], v[172:175], v[196:199], v[82:85]
	s_barrier
	v_mfma_f32_16x16x32_bf16 v[70:73], v[160:163], v[200:203], v[70:73]
	v_mfma_f32_16x16x32_bf16 v[70:73], v[164:167], v[204:207], v[70:73]
	v_mfma_f32_16x16x32_bf16 v[66:69], v[168:171], v[200:203], v[66:69]
	v_mfma_f32_16x16x32_bf16 v[66:69], v[172:175], v[204:207], v[66:69]
	s_setprio 0
	s_mov_b32 m0, s46
	s_add_i32 s76, s75, 0x80
	ds_read_b128 v[176:179], v136 offset:49152
	ds_read_b128 v[180:183], v136 offset:50176
	ds_read_b128 v[184:187], v136 offset:51200
	ds_read_b128 v[188:191], v136 offset:52224
	ds_read_b128 v[192:195], v136 offset:53248
	ds_read_b128 v[196:199], v136 offset:54272
	ds_read_b128 v[200:203], v136 offset:55296
	ds_read_b128 v[204:207], v136 offset:56320
	buffer_load_dwordx4 v133, s[16:19], s76 offen lds
	s_add_i32 s76, s75, 0x200080
	s_mov_b32 m0, s47
	s_add_i32 s73, s73, 0x18080
	buffer_load_dwordx4 v133, s[16:19], s76 offen lds
	s_add_i32 s76, s75, 0x400080
	s_mov_b32 m0, s50
	s_add_i32 s75, s75, 0x600080
	buffer_load_dwordx4 v133, s[16:19], s76 offen lds
	s_mov_b32 m0, s51
	s_nop 0
	buffer_load_dwordx4 v133, s[16:19], s75 offen lds
	s_mov_b32 m0, s48
	s_nop 0
	buffer_load_dwordx4 v132, s[12:15], s74 offen lds
	s_mov_b32 m0, s49
	s_nop 0
	buffer_load_dwordx4 v132, s[12:15], s73 offen lds
	s_waitcnt vmcnt(8)
	s_waitcnt lgkmcnt(0)
	s_setprio 1
	v_mfma_f32_16x16x32_bf16 v[62:65], v[140:143], v[176:179], v[62:65]
	s_barrier
	v_mfma_f32_16x16x32_bf16 v[62:65], v[148:151], v[180:183], v[62:65]
	v_mfma_f32_16x16x32_bf16 v[58:61], v[152:155], v[176:179], v[58:61]
	v_mfma_f32_16x16x32_bf16 v[58:61], v[156:159], v[180:183], v[58:61]
	v_mfma_f32_16x16x32_bf16 v[46:49], v[140:143], v[184:187], v[46:49]
	v_mfma_f32_16x16x32_bf16 v[46:49], v[148:151], v[188:191], v[46:49]
	v_mfma_f32_16x16x32_bf16 v[42:45], v[152:155], v[184:187], v[42:45]
	v_mfma_f32_16x16x32_bf16 v[42:45], v[156:159], v[188:191], v[42:45]
	v_mfma_f32_16x16x32_bf16 v[30:33], v[140:143], v[192:195], v[30:33]
	v_mfma_f32_16x16x32_bf16 v[30:33], v[148:151], v[196:199], v[30:33]
	v_mfma_f32_16x16x32_bf16 v[26:29], v[152:155], v[192:195], v[26:29]
	v_mfma_f32_16x16x32_bf16 v[26:29], v[156:159], v[196:199], v[26:29]
	v_mfma_f32_16x16x32_bf16 v[14:17], v[140:143], v[200:203], v[14:17]
	v_mfma_f32_16x16x32_bf16 v[14:17], v[148:151], v[204:207], v[14:17]
	v_mfma_f32_16x16x32_bf16 v[10:13], v[152:155], v[200:203], v[10:13]
	v_mfma_f32_16x16x32_bf16 v[10:13], v[156:159], v[204:207], v[10:13]
	v_mfma_f32_16x16x32_bf16 v[54:57], v[160:163], v[176:179], v[54:57]
	v_mfma_f32_16x16x32_bf16 v[54:57], v[164:167], v[180:183], v[54:57]
	v_mfma_f32_16x16x32_bf16 v[50:53], v[168:171], v[176:179], v[50:53]
	v_mfma_f32_16x16x32_bf16 v[50:53], v[172:175], v[180:183], v[50:53]
	v_mfma_f32_16x16x32_bf16 v[38:41], v[160:163], v[184:187], v[38:41]
	v_mfma_f32_16x16x32_bf16 v[38:41], v[164:167], v[188:191], v[38:41]
	v_mfma_f32_16x16x32_bf16 v[34:37], v[168:171], v[184:187], v[34:37]
	v_mfma_f32_16x16x32_bf16 v[34:37], v[172:175], v[188:191], v[34:37]
	v_mfma_f32_16x16x32_bf16 v[22:25], v[160:163], v[192:195], v[22:25]
	v_mfma_f32_16x16x32_bf16 v[22:25], v[164:167], v[196:199], v[22:25]
	v_mfma_f32_16x16x32_bf16 v[18:21], v[168:171], v[192:195], v[18:21]
	v_mfma_f32_16x16x32_bf16 v[18:21], v[172:175], v[196:199], v[18:21]
	s_barrier
	v_mfma_f32_16x16x32_bf16 v[6:9], v[160:163], v[200:203], v[6:9]
	v_mfma_f32_16x16x32_bf16 v[6:9], v[164:167], v[204:207], v[6:9]
	v_mfma_f32_16x16x32_bf16 v[2:5], v[168:171], v[200:203], v[2:5]
	v_mfma_f32_16x16x32_bf16 v[2:5], v[172:175], v[204:207], v[2:5]
	s_setprio 0
	s_add_i32 s72, s72, 2
	s_addk_i32 s70, 0x100
	s_addk_i32 s71, 0x100
	s_cmp_ge_i32 s72, s21
	s_cbranch_scc0 .LBB0_1035

.LBB0_1050:
	ds_read_b128 v[132:135], v142
	ds_read_b128 v[136:139], v142 offset:1024
	ds_read_b128 v[148:151], v142 offset:2048
	ds_read_b128 v[152:155], v142 offset:3072
	ds_read_b128 v[156:159], v143
	ds_read_b128 v[160:163], v143 offset:1024
	ds_read_b128 v[164:167], v143 offset:2048
	ds_read_b128 v[168:171], v143 offset:3072
	s_add_i32 s18, s61, 0xfff40080
	s_cmp_eq_u32 s54, s62
	s_cselect_b32 s64, s35, s18
	s_add_i32 s63, s64, 0x80
	s_add_i32 s18, s61, 0xfffc0000
	s_mov_b32 m0, s55
	ds_read_b128 v[172:175], v144
	ds_read_b128 v[176:179], v144 offset:1024
	ds_read_b128 v[180:183], v144 offset:2048
	ds_read_b128 v[184:187], v144 offset:3072
	ds_read_b128 v[188:191], v144 offset:4096
	ds_read_b128 v[192:195], v144 offset:5120
	ds_read_b128 v[196:199], v144 offset:6144
	ds_read_b128 v[200:203], v144 offset:7168
	buffer_load_dwordx4 v140, s[12:15], s18 offen lds
	s_mov_b32 m0, s56
	s_nop 0
	buffer_load_dwordx4 v140, s[12:15], s61 offen lds
	s_waitcnt vmcnt(8)
	s_waitcnt lgkmcnt(0)
	s_setprio 1
	v_mfma_f32_16x16x32_bf16 v[126:129], v[132:135], v[172:175], v[126:129]
	s_barrier
	v_mfma_f32_16x16x32_bf16 v[126:129], v[136:139], v[176:179], v[126:129]
	v_mfma_f32_16x16x32_bf16 v[122:125], v[148:151], v[172:175], v[122:125]
	v_mfma_f32_16x16x32_bf16 v[122:125], v[152:155], v[176:179], v[122:125]
	v_mfma_f32_16x16x32_bf16 v[110:113], v[132:135], v[180:183], v[110:113]
	v_mfma_f32_16x16x32_bf16 v[110:113], v[136:139], v[184:187], v[110:113]
	v_mfma_f32_16x16x32_bf16 v[106:109], v[148:151], v[180:183], v[106:109]
	v_mfma_f32_16x16x32_bf16 v[106:109], v[152:155], v[184:187], v[106:109]
	v_mfma_f32_16x16x32_bf16 v[94:97], v[132:135], v[188:191], v[94:97]
	v_mfma_f32_16x16x32_bf16 v[94:97], v[136:139], v[192:195], v[94:97]
	v_mfma_f32_16x16x32_bf16 v[90:93], v[148:151], v[188:191], v[90:93]
	v_mfma_f32_16x16x32_bf16 v[90:93], v[152:155], v[192:195], v[90:93]
	v_mfma_f32_16x16x32_bf16 v[78:81], v[132:135], v[196:199], v[78:81]
	v_mfma_f32_16x16x32_bf16 v[78:81], v[136:139], v[200:203], v[78:81]
	v_mfma_f32_16x16x32_bf16 v[74:77], v[148:151], v[196:199], v[74:77]
	v_mfma_f32_16x16x32_bf16 v[74:77], v[152:155], v[200:203], v[74:77]
	v_mfma_f32_16x16x32_bf16 v[118:121], v[156:159], v[172:175], v[118:121]
	v_mfma_f32_16x16x32_bf16 v[118:121], v[160:163], v[176:179], v[118:121]
	v_mfma_f32_16x16x32_bf16 v[114:117], v[164:167], v[172:175], v[114:117]
	v_mfma_f32_16x16x32_bf16 v[114:117], v[168:171], v[176:179], v[114:117]
	v_mfma_f32_16x16x32_bf16 v[102:105], v[156:159], v[180:183], v[102:105]
	v_mfma_f32_16x16x32_bf16 v[102:105], v[160:163], v[184:187], v[102:105]
	v_mfma_f32_16x16x32_bf16 v[98:101], v[164:167], v[180:183], v[98:101]
	v_mfma_f32_16x16x32_bf16 v[98:101], v[168:171], v[184:187], v[98:101]
	v_mfma_f32_16x16x32_bf16 v[86:89], v[156:159], v[188:191], v[86:89]
	v_mfma_f32_16x16x32_bf16 v[86:89], v[160:163], v[192:195], v[86:89]
	v_mfma_f32_16x16x32_bf16 v[82:85], v[164:167], v[188:191], v[82:85]
	v_mfma_f32_16x16x32_bf16 v[82:85], v[168:171], v[192:195], v[82:85]
	s_barrier
	v_mfma_f32_16x16x32_bf16 v[70:73], v[156:159], v[196:199], v[70:73]
	v_mfma_f32_16x16x32_bf16 v[70:73], v[160:163], v[200:203], v[70:73]
	v_mfma_f32_16x16x32_bf16 v[66:69], v[164:167], v[196:199], v[66:69]
	v_mfma_f32_16x16x32_bf16 v[66:69], v[168:171], v[200:203], v[66:69]
	s_setprio 0
	s_mov_b32 m0, s25
	s_mov_b32 s18, s14
	s_mov_b32 s19, s15
	ds_read_b128 v[172:175], v144 offset:16384
	ds_read_b128 v[176:179], v144 offset:17408
	ds_read_b128 v[180:183], v144 offset:18432
	ds_read_b128 v[184:187], v144 offset:19456
	ds_read_b128 v[188:191], v144 offset:20480
	ds_read_b128 v[192:195], v144 offset:21504
	ds_read_b128 v[196:199], v144 offset:22528
	ds_read_b128 v[200:203], v144 offset:23552
	buffer_load_dwordx4 v141, s[16:19], s64 offen lds
	s_add_i32 s65, s64, 0x40000
	s_mov_b32 m0, s27
	s_add_i32 s66, s64, 0x80000
	buffer_load_dwordx4 v141, s[16:19], s65 offen lds
	s_mov_b32 m0, s30
	s_add_i32 s67, s64, 0xc0000
	buffer_load_dwordx4 v141, s[16:19], s66 offen lds
	s_mov_b32 m0, s31
	s_nop 0
	buffer_load_dwordx4 v141, s[16:19], s67 offen lds
	s_mov_b32 m0, s21
	s_nop 0
	buffer_load_dwordx4 v140, s[12:15], s64 offen lds
	s_mov_b32 m0, s38
	s_nop 0
	buffer_load_dwordx4 v140, s[12:15], s65 offen lds
	s_waitcnt vmcnt(8)
	s_waitcnt lgkmcnt(0)
	s_setprio 1
	v_mfma_f32_16x16x32_bf16 v[62:65], v[132:135], v[172:175], v[62:65]
	s_barrier
	v_mfma_f32_16x16x32_bf16 v[62:65], v[136:139], v[176:179], v[62:65]
	v_mfma_f32_16x16x32_bf16 v[58:61], v[148:151], v[172:175], v[58:61]
	v_mfma_f32_16x16x32_bf16 v[58:61], v[152:155], v[176:179], v[58:61]
	v_mfma_f32_16x16x32_bf16 v[46:49], v[132:135], v[180:183], v[46:49]
	v_mfma_f32_16x16x32_bf16 v[46:49], v[136:139], v[184:187], v[46:49]
	v_mfma_f32_16x16x32_bf16 v[42:45], v[148:151], v[180:183], v[42:45]
	v_mfma_f32_16x16x32_bf16 v[42:45], v[152:155], v[184:187], v[42:45]
	v_mfma_f32_16x16x32_bf16 v[30:33], v[132:135], v[188:191], v[30:33]
	v_mfma_f32_16x16x32_bf16 v[30:33], v[136:139], v[192:195], v[30:33]
	v_mfma_f32_16x16x32_bf16 v[26:29], v[148:151], v[188:191], v[26:29]
	v_mfma_f32_16x16x32_bf16 v[26:29], v[152:155], v[192:195], v[26:29]
	v_mfma_f32_16x16x32_bf16 v[14:17], v[132:135], v[196:199], v[14:17]
	v_mfma_f32_16x16x32_bf16 v[14:17], v[136:139], v[200:203], v[14:17]
	v_mfma_f32_16x16x32_bf16 v[10:13], v[148:151], v[196:199], v[10:13]
	v_mfma_f32_16x16x32_bf16 v[10:13], v[152:155], v[200:203], v[10:13]
	v_mfma_f32_16x16x32_bf16 v[54:57], v[156:159], v[172:175], v[54:57]
	v_mfma_f32_16x16x32_bf16 v[54:57], v[160:163], v[176:179], v[54:57]
	v_mfma_f32_16x16x32_bf16 v[50:53], v[164:167], v[172:175], v[50:53]
	v_mfma_f32_16x16x32_bf16 v[50:53], v[168:171], v[176:179], v[50:53]
	v_mfma_f32_16x16x32_bf16 v[38:41], v[156:159], v[180:183], v[38:41]
	v_mfma_f32_16x16x32_bf16 v[38:41], v[160:163], v[184:187], v[38:41]
	v_mfma_f32_16x16x32_bf16 v[34:37], v[164:167], v[180:183], v[34:37]
	v_mfma_f32_16x16x32_bf16 v[34:37], v[168:171], v[184:187], v[34:37]
	v_mfma_f32_16x16x32_bf16 v[22:25], v[156:159], v[188:191], v[22:25]
	v_mfma_f32_16x16x32_bf16 v[22:25], v[160:163], v[192:195], v[22:25]
	v_mfma_f32_16x16x32_bf16 v[18:21], v[164:167], v[188:191], v[18:21]
	v_mfma_f32_16x16x32_bf16 v[18:21], v[168:171], v[192:195], v[18:21]
	s_barrier
	v_mfma_f32_16x16x32_bf16 v[6:9], v[156:159], v[196:199], v[6:9]
	v_mfma_f32_16x16x32_bf16 v[6:9], v[160:163], v[200:203], v[6:9]
	v_mfma_f32_16x16x32_bf16 v[2:5], v[164:167], v[196:199], v[2:5]
	v_mfma_f32_16x16x32_bf16 v[2:5], v[168:171], v[200:203], v[2:5]
	s_setprio 0
	ds_read_b128 v[132:135], v145
	ds_read_b128 v[136:139], v145 offset:1024
	ds_read_b128 v[148:151], v145 offset:2048
	ds_read_b128 v[152:155], v145 offset:3072
	ds_read_b128 v[156:159], v147
	ds_read_b128 v[160:163], v147 offset:1024
	ds_read_b128 v[164:167], v147 offset:2048
	ds_read_b128 v[168:171], v147 offset:3072
	s_mov_b32 m0, s39
	ds_read_b128 v[172:175], v144 offset:32768
	ds_read_b128 v[176:179], v144 offset:33792
	ds_read_b128 v[180:183], v144 offset:34816
	ds_read_b128 v[184:187], v144 offset:35840
	ds_read_b128 v[188:191], v144 offset:36864
	ds_read_b128 v[192:195], v144 offset:37888
	ds_read_b128 v[196:199], v144 offset:38912
	ds_read_b128 v[200:203], v144 offset:39936
	buffer_load_dwordx4 v140, s[12:15], s66 offen lds
	s_mov_b32 m0, s40
	s_nop 0
	buffer_load_dwordx4 v140, s[12:15], s67 offen lds
	s_waitcnt vmcnt(8)
	s_waitcnt lgkmcnt(0)
	s_setprio 1
	v_mfma_f32_16x16x32_bf16 v[126:129], v[132:135], v[172:175], v[126:129]
	s_barrier
	v_mfma_f32_16x16x32_bf16 v[126:129], v[136:139], v[176:179], v[126:129]
	v_mfma_f32_16x16x32_bf16 v[122:125], v[148:151], v[172:175], v[122:125]
	v_mfma_f32_16x16x32_bf16 v[122:125], v[152:155], v[176:179], v[122:125]
	v_mfma_f32_16x16x32_bf16 v[110:113], v[132:135], v[180:183], v[110:113]
	v_mfma_f32_16x16x32_bf16 v[110:113], v[136:139], v[184:187], v[110:113]
	v_mfma_f32_16x16x32_bf16 v[106:109], v[148:151], v[180:183], v[106:109]
	v_mfma_f32_16x16x32_bf16 v[106:109], v[152:155], v[184:187], v[106:109]
	v_mfma_f32_16x16x32_bf16 v[94:97], v[132:135], v[188:191], v[94:97]
	v_mfma_f32_16x16x32_bf16 v[94:97], v[136:139], v[192:195], v[94:97]
	v_mfma_f32_16x16x32_bf16 v[90:93], v[148:151], v[188:191], v[90:93]
	v_mfma_f32_16x16x32_bf16 v[90:93], v[152:155], v[192:195], v[90:93]
	v_mfma_f32_16x16x32_bf16 v[78:81], v[132:135], v[196:199], v[78:81]
	v_mfma_f32_16x16x32_bf16 v[78:81], v[136:139], v[200:203], v[78:81]
	v_mfma_f32_16x16x32_bf16 v[74:77], v[148:151], v[196:199], v[74:77]
	v_mfma_f32_16x16x32_bf16 v[74:77], v[152:155], v[200:203], v[74:77]
	v_mfma_f32_16x16x32_bf16 v[118:121], v[156:159], v[172:175], v[118:121]
	v_mfma_f32_16x16x32_bf16 v[118:121], v[160:163], v[176:179], v[118:121]
	v_mfma_f32_16x16x32_bf16 v[114:117], v[164:167], v[172:175], v[114:117]
	v_mfma_f32_16x16x32_bf16 v[114:117], v[168:171], v[176:179], v[114:117]
	v_mfma_f32_16x16x32_bf16 v[102:105], v[156:159], v[180:183], v[102:105]
	v_mfma_f32_16x16x32_bf16 v[102:105], v[160:163], v[184:187], v[102:105]
	v_mfma_f32_16x16x32_bf16 v[98:101], v[164:167], v[180:183], v[98:101]
	v_mfma_f32_16x16x32_bf16 v[98:101], v[168:171], v[184:187], v[98:101]
	v_mfma_f32_16x16x32_bf16 v[86:89], v[156:159], v[188:191], v[86:89]
	v_mfma_f32_16x16x32_bf16 v[86:89], v[160:163], v[192:195], v[86:89]
	v_mfma_f32_16x16x32_bf16 v[82:85], v[164:167], v[188:191], v[82:85]
	v_mfma_f32_16x16x32_bf16 v[82:85], v[168:171], v[192:195], v[82:85]
	s_barrier
	v_mfma_f32_16x16x32_bf16 v[70:73], v[156:159], v[196:199], v[70:73]
	v_mfma_f32_16x16x32_bf16 v[70:73], v[160:163], v[200:203], v[70:73]
	v_mfma_f32_16x16x32_bf16 v[66:69], v[164:167], v[196:199], v[66:69]
	v_mfma_f32_16x16x32_bf16 v[66:69], v[168:171], v[200:203], v[66:69]
	s_setprio 0
	s_mov_b32 m0, s48
	ds_read_b128 v[172:175], v144 offset:49152
	ds_read_b128 v[176:179], v144 offset:50176
	ds_read_b128 v[180:183], v144 offset:51200
	ds_read_b128 v[184:187], v144 offset:52224
	ds_read_b128 v[188:191], v144 offset:53248
	ds_read_b128 v[192:195], v144 offset:54272
	ds_read_b128 v[196:199], v144 offset:55296
	ds_read_b128 v[200:203], v144 offset:56320
	buffer_load_dwordx4 v141, s[16:19], s63 offen lds
	s_add_i32 s65, s64, 0x40080
	s_mov_b32 m0, s49
	s_add_i32 s66, s64, 0x80080
	buffer_load_dwordx4 v141, s[16:19], s65 offen lds
	s_mov_b32 m0, s52
	s_add_i32 s64, s64, 0xc0080
	buffer_load_dwordx4 v141, s[16:19], s66 offen lds
	s_mov_b32 m0, s53
	s_nop 0
	buffer_load_dwordx4 v141, s[16:19], s64 offen lds
	s_mov_b32 m0, s50
	s_nop 0
	buffer_load_dwordx4 v140, s[12:15], s63 offen lds
	s_mov_b32 m0, s51
	s_nop 0
	buffer_load_dwordx4 v140, s[12:15], s65 offen lds
	s_waitcnt vmcnt(8)
	s_waitcnt lgkmcnt(0)
	s_setprio 1
	v_mfma_f32_16x16x32_bf16 v[62:65], v[132:135], v[172:175], v[62:65]
	s_barrier
	v_mfma_f32_16x16x32_bf16 v[62:65], v[136:139], v[176:179], v[62:65]
	v_mfma_f32_16x16x32_bf16 v[58:61], v[148:151], v[172:175], v[58:61]
	v_mfma_f32_16x16x32_bf16 v[58:61], v[152:155], v[176:179], v[58:61]
	v_mfma_f32_16x16x32_bf16 v[46:49], v[132:135], v[180:183], v[46:49]
	v_mfma_f32_16x16x32_bf16 v[46:49], v[136:139], v[184:187], v[46:49]
	v_mfma_f32_16x16x32_bf16 v[42:45], v[148:151], v[180:183], v[42:45]
	v_mfma_f32_16x16x32_bf16 v[42:45], v[152:155], v[184:187], v[42:45]
	v_mfma_f32_16x16x32_bf16 v[30:33], v[132:135], v[188:191], v[30:33]
	v_mfma_f32_16x16x32_bf16 v[30:33], v[136:139], v[192:195], v[30:33]
	v_mfma_f32_16x16x32_bf16 v[26:29], v[148:151], v[188:191], v[26:29]
	v_mfma_f32_16x16x32_bf16 v[26:29], v[152:155], v[192:195], v[26:29]
	v_mfma_f32_16x16x32_bf16 v[14:17], v[132:135], v[196:199], v[14:17]
	v_mfma_f32_16x16x32_bf16 v[14:17], v[136:139], v[200:203], v[14:17]
	v_mfma_f32_16x16x32_bf16 v[10:13], v[148:151], v[196:199], v[10:13]
	v_mfma_f32_16x16x32_bf16 v[10:13], v[152:155], v[200:203], v[10:13]
	v_mfma_f32_16x16x32_bf16 v[54:57], v[156:159], v[172:175], v[54:57]
	v_mfma_f32_16x16x32_bf16 v[54:57], v[160:163], v[176:179], v[54:57]
	v_mfma_f32_16x16x32_bf16 v[50:53], v[164:167], v[172:175], v[50:53]
	v_mfma_f32_16x16x32_bf16 v[50:53], v[168:171], v[176:179], v[50:53]
	v_mfma_f32_16x16x32_bf16 v[38:41], v[156:159], v[180:183], v[38:41]
	v_mfma_f32_16x16x32_bf16 v[38:41], v[160:163], v[184:187], v[38:41]
	v_mfma_f32_16x16x32_bf16 v[34:37], v[164:167], v[180:183], v[34:37]
	v_mfma_f32_16x16x32_bf16 v[34:37], v[168:171], v[184:187], v[34:37]
	v_mfma_f32_16x16x32_bf16 v[22:25], v[156:159], v[188:191], v[22:25]
	v_mfma_f32_16x16x32_bf16 v[22:25], v[160:163], v[192:195], v[22:25]
	v_mfma_f32_16x16x32_bf16 v[18:21], v[164:167], v[188:191], v[18:21]
	v_mfma_f32_16x16x32_bf16 v[18:21], v[168:171], v[192:195], v[18:21]
	s_barrier
	v_mfma_f32_16x16x32_bf16 v[6:9], v[156:159], v[196:199], v[6:9]
	v_mfma_f32_16x16x32_bf16 v[6:9], v[160:163], v[200:203], v[6:9]
	v_mfma_f32_16x16x32_bf16 v[2:5], v[164:167], v[196:199], v[2:5]
	v_mfma_f32_16x16x32_bf16 v[2:5], v[168:171], v[200:203], v[2:5]
	s_setprio 0
	s_add_i32 s62, s62, 2
	s_addk_i32 s61, 0x100
	s_cmp_ge_i32 s62, s3
	s_cbranch_scc0 .LBB0_1050

.LBB0_1181:
	v_add_u32_e32 v2, 0x10000, v232
	ds_read_b128 v[134:137], v2
	ds_read_b128 v[138:141], v2 offset:1024
	ds_read_b128 v[142:145], v2 offset:2048
	ds_read_b128 v[146:149], v2 offset:3072
	v_add_u32_e32 v2, 0x14000, v232
	ds_read_b128 v[150:153], v2
	ds_read_b128 v[154:157], v2 offset:1024
	ds_read_b128 v[158:161], v2 offset:2048
	ds_read_b128 v[162:165], v2 offset:3072
	s_add_i32 s50, s47, s90
	s_and_b64 s[18:19], exec, s[18:19]
	s_cselect_b32 s51, s88, s50
	s_add_i32 s50, s92, 0x80
	s_or_b32 s52, s51, 0x80
	s_add_i32 s18, s89, s93
	s_add_i32 s94, s94, 0x1bfffc80
	s_cmp_lt_u32 s91, 8
	s_cselect_b32 s18, s18, s94
	s_mov_b32 m0, s74
	s_add_i32 s19, s18, 0x80000
	ds_read_b128 v[166:169], v233
	ds_read_b128 v[170:173], v233 offset:1024
	ds_read_b128 v[174:177], v233 offset:2048
	ds_read_b128 v[178:181], v233 offset:3072
	ds_read_b128 v[182:185], v233 offset:4096
	ds_read_b128 v[186:189], v233 offset:5120
	ds_read_b128 v[190:193], v233 offset:6144
	ds_read_b128 v[194:197], v233 offset:7168
	buffer_load_dwordx4 v230, s[12:15], s19 offen lds
	s_add_i32 s18, s18, 0xc0000
	s_mov_b32 m0, s75
	s_nop 0
	buffer_load_dwordx4 v230, s[12:15], s18 offen lds
	s_waitcnt vmcnt(8)
	s_waitcnt lgkmcnt(0)
	s_setprio 1
	v_mfma_f32_16x16x32_bf16 v[130:133], v[134:137], v[166:169], v[130:133]
	s_barrier
	v_mfma_f32_16x16x32_bf16 v[130:133], v[138:141], v[170:173], v[130:133]
	v_mfma_f32_16x16x32_bf16 v[126:129], v[142:145], v[166:169], v[126:129]
	v_mfma_f32_16x16x32_bf16 v[126:129], v[146:149], v[170:173], v[126:129]
	v_mfma_f32_16x16x32_bf16 v[114:117], v[134:137], v[174:177], v[114:117]
	v_mfma_f32_16x16x32_bf16 v[114:117], v[138:141], v[178:181], v[114:117]
	v_mfma_f32_16x16x32_bf16 v[110:113], v[142:145], v[174:177], v[110:113]
	v_mfma_f32_16x16x32_bf16 v[110:113], v[146:149], v[178:181], v[110:113]
	v_mfma_f32_16x16x32_bf16 v[98:101], v[134:137], v[182:185], v[98:101]
	v_mfma_f32_16x16x32_bf16 v[98:101], v[138:141], v[186:189], v[98:101]
	v_mfma_f32_16x16x32_bf16 v[94:97], v[142:145], v[182:185], v[94:97]
	v_mfma_f32_16x16x32_bf16 v[94:97], v[146:149], v[186:189], v[94:97]
	v_mfma_f32_16x16x32_bf16 v[82:85], v[134:137], v[190:193], v[82:85]
	v_mfma_f32_16x16x32_bf16 v[82:85], v[138:141], v[194:197], v[82:85]
	v_mfma_f32_16x16x32_bf16 v[78:81], v[142:145], v[190:193], v[78:81]
	v_mfma_f32_16x16x32_bf16 v[78:81], v[146:149], v[194:197], v[78:81]
	v_mfma_f32_16x16x32_bf16 v[122:125], v[150:153], v[166:169], v[122:125]
	v_mfma_f32_16x16x32_bf16 v[122:125], v[154:157], v[170:173], v[122:125]
	v_mfma_f32_16x16x32_bf16 v[118:121], v[158:161], v[166:169], v[118:121]
	v_mfma_f32_16x16x32_bf16 v[118:121], v[162:165], v[170:173], v[118:121]
	v_mfma_f32_16x16x32_bf16 v[106:109], v[150:153], v[174:177], v[106:109]
	v_mfma_f32_16x16x32_bf16 v[106:109], v[154:157], v[178:181], v[106:109]
	v_mfma_f32_16x16x32_bf16 v[102:105], v[158:161], v[174:177], v[102:105]
	v_mfma_f32_16x16x32_bf16 v[102:105], v[162:165], v[178:181], v[102:105]
	v_mfma_f32_16x16x32_bf16 v[90:93], v[150:153], v[182:185], v[90:93]
	v_mfma_f32_16x16x32_bf16 v[90:93], v[154:157], v[186:189], v[90:93]
	v_mfma_f32_16x16x32_bf16 v[86:89], v[158:161], v[182:185], v[86:89]
	v_mfma_f32_16x16x32_bf16 v[86:89], v[162:165], v[186:189], v[86:89]
	s_barrier
	v_mfma_f32_16x16x32_bf16 v[74:77], v[150:153], v[190:193], v[74:77]
	v_mfma_f32_16x16x32_bf16 v[74:77], v[154:157], v[194:197], v[74:77]
	v_mfma_f32_16x16x32_bf16 v[70:73], v[158:161], v[190:193], v[70:73]
	v_mfma_f32_16x16x32_bf16 v[70:73], v[162:165], v[194:197], v[70:73]
	s_setprio 0
	s_mov_b32 m0, s27
	s_mov_b32 s18, s14
	s_mov_b32 s19, s15
	ds_read_b128 v[166:169], v233 offset:16384
	ds_read_b128 v[170:173], v233 offset:17408
	ds_read_b128 v[174:177], v233 offset:18432
	ds_read_b128 v[178:181], v233 offset:19456
	ds_read_b128 v[182:185], v233 offset:20480
	ds_read_b128 v[186:189], v233 offset:21504
	ds_read_b128 v[190:193], v233 offset:22528
	ds_read_b128 v[194:197], v233 offset:23552
	buffer_load_dwordx4 v231, s[16:19], s51 offen lds
	s_add_i32 s53, s51, 0x18000
	s_mov_b32 m0, s30
	s_nop 0
	buffer_load_dwordx4 v231, s[16:19], s53 offen lds
	s_add_i32 s53, s51, 0x30000
	s_mov_b32 m0, s31
	s_nop 0
	buffer_load_dwordx4 v231, s[16:19], s53 offen lds
	s_add_i32 s53, s51, 0x48000
	s_mov_b32 m0, s54
	s_nop 0
	buffer_load_dwordx4 v231, s[16:19], s53 offen lds
	s_mov_b32 m0, s25
	s_add_i32 s53, s92, 0x40000
	buffer_load_dwordx4 v230, s[12:15], s92 offen lds
	s_mov_b32 m0, s55
	s_nop 0
	buffer_load_dwordx4 v230, s[12:15], s53 offen lds
	s_waitcnt vmcnt(8)
	s_waitcnt lgkmcnt(0)
	s_setprio 1
	v_mfma_f32_16x16x32_bf16 v[66:69], v[134:137], v[166:169], v[66:69]
	s_barrier
	v_mfma_f32_16x16x32_bf16 v[62:65], v[142:145], v[166:169], v[62:65]
	v_mfma_f32_16x16x32_bf16 v[50:53], v[134:137], v[174:177], v[50:53]
	v_mfma_f32_16x16x32_bf16 v[46:49], v[142:145], v[174:177], v[46:49]
	v_mfma_f32_16x16x32_bf16 v[34:37], v[134:137], v[182:185], v[34:37]
	v_mfma_f32_16x16x32_bf16 v[30:33], v[142:145], v[182:185], v[30:33]
	v_mfma_f32_16x16x32_bf16 v[18:21], v[134:137], v[190:193], v[18:21]
	v_mfma_f32_16x16x32_bf16 v[14:17], v[142:145], v[190:193], v[14:17]
	v_mfma_f32_16x16x32_bf16 v[58:61], v[150:153], v[166:169], v[58:61]
	v_mfma_f32_16x16x32_bf16 v[54:57], v[158:161], v[166:169], v[54:57]
	v_mfma_f32_16x16x32_bf16 v[42:45], v[150:153], v[174:177], v[42:45]
	v_mfma_f32_16x16x32_bf16 v[38:41], v[158:161], v[174:177], v[38:41]
	v_mfma_f32_16x16x32_bf16 v[26:29], v[150:153], v[182:185], v[26:29]
	v_mfma_f32_16x16x32_bf16 v[22:25], v[158:161], v[182:185], v[22:25]
	v_mfma_f32_16x16x32_bf16 v[10:13], v[150:153], v[190:193], v[10:13]
	v_mfma_f32_16x16x32_bf16 v[4:7], v[158:161], v[190:193], v[6:9]
	v_mfma_f32_16x16x32_bf16 v[66:69], v[138:141], v[170:173], v[66:69]
	v_mfma_f32_16x16x32_bf16 v[62:65], v[146:149], v[170:173], v[62:65]
	v_mfma_f32_16x16x32_bf16 v[50:53], v[138:141], v[178:181], v[50:53]
	v_mfma_f32_16x16x32_bf16 v[46:49], v[146:149], v[178:181], v[46:49]
	v_mfma_f32_16x16x32_bf16 v[34:37], v[138:141], v[186:189], v[34:37]
	v_mfma_f32_16x16x32_bf16 v[30:33], v[146:149], v[186:189], v[30:33]
	v_mfma_f32_16x16x32_bf16 v[18:21], v[138:141], v[194:197], v[18:21]
	v_mfma_f32_16x16x32_bf16 v[14:17], v[146:149], v[194:197], v[14:17]
	v_mfma_f32_16x16x32_bf16 v[58:61], v[154:157], v[170:173], v[58:61]
	v_mfma_f32_16x16x32_bf16 v[54:57], v[162:165], v[170:173], v[54:57]
	v_mfma_f32_16x16x32_bf16 v[42:45], v[154:157], v[178:181], v[42:45]
	v_mfma_f32_16x16x32_bf16 v[38:41], v[162:165], v[178:181], v[38:41]
	s_barrier
	v_mfma_f32_16x16x32_bf16 v[26:29], v[154:157], v[186:189], v[26:29]
	v_mfma_f32_16x16x32_bf16 v[22:25], v[162:165], v[186:189], v[22:25]
	v_mfma_f32_16x16x32_bf16 v[10:13], v[154:157], v[194:197], v[10:13]
	v_mfma_f32_16x16x32_bf16 v[4:7], v[162:165], v[194:197], v[4:7]
	s_setprio 0
	v_add_u32_e32 v2, 0x18000, v232
	ds_read_b128 v[134:137], v2
	ds_read_b128 v[138:141], v2 offset:1024
	ds_read_b128 v[142:145], v2 offset:2048
	ds_read_b128 v[146:149], v2 offset:3072
	v_add_u32_e32 v2, 0x1c000, v232
	ds_read_b128 v[150:153], v2
	ds_read_b128 v[154:157], v2 offset:1024
	ds_read_b128 v[158:161], v2 offset:2048
	ds_read_b128 v[162:165], v2 offset:3072
	s_mov_b32 m0, s56
	s_add_i32 s53, s92, 0x80000
	ds_read_b128 v[166:169], v233 offset:32768
	ds_read_b128 v[170:173], v233 offset:33792
	ds_read_b128 v[174:177], v233 offset:34816
	ds_read_b128 v[178:181], v233 offset:35840
	ds_read_b128 v[182:185], v233 offset:36864
	ds_read_b128 v[186:189], v233 offset:37888
	ds_read_b128 v[190:193], v233 offset:38912
	ds_read_b128 v[194:197], v233 offset:39936
	buffer_load_dwordx4 v230, s[12:15], s53 offen lds
	s_add_i32 s53, s92, 0xc0000
	s_mov_b32 m0, s57
	s_nop 0
	buffer_load_dwordx4 v230, s[12:15], s53 offen lds
	s_waitcnt vmcnt(8)
	s_waitcnt lgkmcnt(0)
	s_setprio 1
	v_mfma_f32_16x16x32_bf16 v[130:133], v[134:137], v[166:169], v[130:133]
	s_barrier
	v_mfma_f32_16x16x32_bf16 v[130:133], v[138:141], v[170:173], v[130:133]
	v_mfma_f32_16x16x32_bf16 v[126:129], v[142:145], v[166:169], v[126:129]
	v_mfma_f32_16x16x32_bf16 v[126:129], v[146:149], v[170:173], v[126:129]
	v_mfma_f32_16x16x32_bf16 v[114:117], v[134:137], v[174:177], v[114:117]
	v_mfma_f32_16x16x32_bf16 v[114:117], v[138:141], v[178:181], v[114:117]
	v_mfma_f32_16x16x32_bf16 v[110:113], v[142:145], v[174:177], v[110:113]
	v_mfma_f32_16x16x32_bf16 v[110:113], v[146:149], v[178:181], v[110:113]
	v_mfma_f32_16x16x32_bf16 v[98:101], v[134:137], v[182:185], v[98:101]
	v_mfma_f32_16x16x32_bf16 v[98:101], v[138:141], v[186:189], v[98:101]
	v_mfma_f32_16x16x32_bf16 v[94:97], v[142:145], v[182:185], v[94:97]
	v_mfma_f32_16x16x32_bf16 v[94:97], v[146:149], v[186:189], v[94:97]
	v_mfma_f32_16x16x32_bf16 v[82:85], v[134:137], v[190:193], v[82:85]
	v_mfma_f32_16x16x32_bf16 v[82:85], v[138:141], v[194:197], v[82:85]
	v_mfma_f32_16x16x32_bf16 v[78:81], v[142:145], v[190:193], v[78:81]
	v_mfma_f32_16x16x32_bf16 v[78:81], v[146:149], v[194:197], v[78:81]
	v_mfma_f32_16x16x32_bf16 v[122:125], v[150:153], v[166:169], v[122:125]
	v_mfma_f32_16x16x32_bf16 v[122:125], v[154:157], v[170:173], v[122:125]
	v_mfma_f32_16x16x32_bf16 v[118:121], v[158:161], v[166:169], v[118:121]
	v_mfma_f32_16x16x32_bf16 v[118:121], v[162:165], v[170:173], v[118:121]
	v_mfma_f32_16x16x32_bf16 v[106:109], v[150:153], v[174:177], v[106:109]
	v_mfma_f32_16x16x32_bf16 v[106:109], v[154:157], v[178:181], v[106:109]
	v_mfma_f32_16x16x32_bf16 v[102:105], v[158:161], v[174:177], v[102:105]
	v_mfma_f32_16x16x32_bf16 v[102:105], v[162:165], v[178:181], v[102:105]
	v_mfma_f32_16x16x32_bf16 v[90:93], v[150:153], v[182:185], v[90:93]
	v_mfma_f32_16x16x32_bf16 v[90:93], v[154:157], v[186:189], v[90:93]
	v_mfma_f32_16x16x32_bf16 v[86:89], v[158:161], v[182:185], v[86:89]
	v_mfma_f32_16x16x32_bf16 v[86:89], v[162:165], v[186:189], v[86:89]
	s_barrier
	v_mfma_f32_16x16x32_bf16 v[74:77], v[150:153], v[190:193], v[74:77]
	v_mfma_f32_16x16x32_bf16 v[74:77], v[154:157], v[194:197], v[74:77]
	v_mfma_f32_16x16x32_bf16 v[70:73], v[158:161], v[190:193], v[70:73]
	v_mfma_f32_16x16x32_bf16 v[70:73], v[162:165], v[194:197], v[70:73]
	s_setprio 0
	s_mov_b32 m0, s64
	ds_read_b128 v[166:169], v233 offset:49152
	ds_read_b128 v[170:173], v233 offset:50176
	ds_read_b128 v[174:177], v233 offset:51200
	ds_read_b128 v[178:181], v233 offset:52224
	ds_read_b128 v[182:185], v233 offset:53248
	ds_read_b128 v[186:189], v233 offset:54272
	ds_read_b128 v[190:193], v233 offset:55296
	ds_read_b128 v[194:197], v233 offset:56320
	buffer_load_dwordx4 v231, s[16:19], s52 offen lds
	s_add_i32 s52, s51, 0x18080
	s_mov_b32 m0, s65
	s_nop 0
	buffer_load_dwordx4 v231, s[16:19], s52 offen lds
	s_add_i32 s52, s51, 0x30080
	s_mov_b32 m0, s68
	s_add_i32 s51, s51, 0x48080
	buffer_load_dwordx4 v231, s[16:19], s52 offen lds
	s_mov_b32 m0, s69
	s_nop 0
	buffer_load_dwordx4 v231, s[16:19], s51 offen lds
	s_mov_b32 m0, s66
	s_add_i32 s18, s92, 0x40080
	buffer_load_dwordx4 v230, s[12:15], s50 offen lds
	s_mov_b32 m0, s67
	s_nop 0
	buffer_load_dwordx4 v230, s[12:15], s18 offen lds
	s_waitcnt vmcnt(8)
	s_waitcnt lgkmcnt(0)
	s_setprio 1
	v_mfma_f32_16x16x32_bf16 v[66:69], v[134:137], v[166:169], v[66:69]
	s_barrier
	v_mfma_f32_16x16x32_bf16 v[62:65], v[142:145], v[166:169], v[62:65]
	v_mfma_f32_16x16x32_bf16 v[50:53], v[134:137], v[174:177], v[50:53]
	v_mfma_f32_16x16x32_bf16 v[46:49], v[142:145], v[174:177], v[46:49]
	v_mfma_f32_16x16x32_bf16 v[34:37], v[134:137], v[182:185], v[34:37]
	v_mfma_f32_16x16x32_bf16 v[30:33], v[142:145], v[182:185], v[30:33]
	v_mfma_f32_16x16x32_bf16 v[18:21], v[134:137], v[190:193], v[18:21]
	v_mfma_f32_16x16x32_bf16 v[14:17], v[142:145], v[190:193], v[14:17]
	v_mfma_f32_16x16x32_bf16 v[58:61], v[150:153], v[166:169], v[58:61]
	v_mfma_f32_16x16x32_bf16 v[54:57], v[158:161], v[166:169], v[54:57]
	v_mfma_f32_16x16x32_bf16 v[42:45], v[150:153], v[174:177], v[42:45]
	v_mfma_f32_16x16x32_bf16 v[38:41], v[158:161], v[174:177], v[38:41]
	v_mfma_f32_16x16x32_bf16 v[26:29], v[150:153], v[182:185], v[26:29]
	v_mfma_f32_16x16x32_bf16 v[22:25], v[158:161], v[182:185], v[22:25]
	v_mfma_f32_16x16x32_bf16 v[8:11], v[150:153], v[190:193], v[10:13]
	v_mfma_f32_16x16x32_bf16 v[4:7], v[158:161], v[190:193], v[4:7]
	v_mfma_f32_16x16x32_bf16 v[66:69], v[138:141], v[170:173], v[66:69]
	v_mfma_f32_16x16x32_bf16 v[62:65], v[146:149], v[170:173], v[62:65]
	v_mfma_f32_16x16x32_bf16 v[50:53], v[138:141], v[178:181], v[50:53]
	v_mfma_f32_16x16x32_bf16 v[46:49], v[146:149], v[178:181], v[46:49]
	v_mfma_f32_16x16x32_bf16 v[34:37], v[138:141], v[186:189], v[34:37]
	v_mfma_f32_16x16x32_bf16 v[30:33], v[146:149], v[186:189], v[30:33]
	v_mfma_f32_16x16x32_bf16 v[18:21], v[138:141], v[194:197], v[18:21]
	v_mfma_f32_16x16x32_bf16 v[14:17], v[146:149], v[194:197], v[14:17]
	v_mfma_f32_16x16x32_bf16 v[58:61], v[154:157], v[170:173], v[58:61]
	v_mfma_f32_16x16x32_bf16 v[54:57], v[162:165], v[170:173], v[54:57]
	v_mfma_f32_16x16x32_bf16 v[42:45], v[154:157], v[178:181], v[42:45]
	v_mfma_f32_16x16x32_bf16 v[38:41], v[162:165], v[178:181], v[38:41]
	s_barrier
	v_mfma_f32_16x16x32_bf16 v[26:29], v[154:157], v[186:189], v[26:29]
	v_mfma_f32_16x16x32_bf16 v[22:25], v[162:165], v[186:189], v[22:25]
	v_mfma_f32_16x16x32_bf16 v[10:13], v[154:157], v[194:197], v[8:11]
	v_mfma_f32_16x16x32_bf16 v[6:9], v[162:165], v[194:197], v[4:7]
	s_setprio 0
	s_add_i32 s91, s91, 2
	s_addk_i32 s90, 0x100
	s_cmp_ge_i32 s91, s3
	s_cbranch_scc1 .LBB0_1193

.LBB0_1290:
	ds_read_b128 v[106:109], v224
	ds_read_b128 v[118:121], v224 offset:1024
	ds_read_b128 v[130:133], v224 offset:2048
	ds_read_b128 v[138:141], v224 offset:3072
	ds_read_b128 v[146:149], v225
	ds_read_b128 v[150:153], v225 offset:1024
	ds_read_b128 v[154:157], v225 offset:2048
	ds_read_b128 v[158:161], v225 offset:3072
	s_add_i32 s18, s72, 0xffe80080
	s_cmp_eq_u32 s56, s74
	s_cselect_b32 s75, s6, s18
	s_cselect_b32 s77, s7, s73
	s_or_b32 s76, s75, 0x80
	s_add_i32 s18, s72, 0xfff80000
	s_mov_b32 m0, s57
	ds_read_b128 v[162:165], v226
	ds_read_b128 v[166:169], v226 offset:1024
	ds_read_b128 v[170:173], v226 offset:2048
	ds_read_b128 v[174:177], v226 offset:3072
	ds_read_b128 v[178:181], v226 offset:4096
	ds_read_b128 v[182:185], v226 offset:5120
	ds_read_b128 v[190:193], v226 offset:6144
	ds_read_b128 v[194:197], v226 offset:7168
	buffer_load_dwordx4 v222, s[12:15], s18 offen lds
	s_mov_b32 m0, s60
	s_nop 0
	buffer_load_dwordx4 v222, s[12:15], s72 offen lds
	s_waitcnt vmcnt(8)
	s_waitcnt lgkmcnt(0)
	s_setprio 1
	v_mfma_f32_16x16x32_bf16 v[142:145], v[106:109], v[162:165], v[142:145]
	s_barrier
	v_mfma_f32_16x16x32_bf16 v[142:145], v[118:121], v[166:169], v[142:145]
	v_mfma_f32_16x16x32_bf16 v[134:137], v[130:133], v[162:165], v[134:137]
	v_mfma_f32_16x16x32_bf16 v[134:137], v[138:141], v[166:169], v[134:137]
	v_mfma_f32_16x16x32_bf16 v[114:117], v[106:109], v[170:173], v[114:117]
	v_mfma_f32_16x16x32_bf16 v[114:117], v[118:121], v[174:177], v[114:117]
	v_mfma_f32_16x16x32_bf16 v[110:113], v[130:133], v[170:173], v[110:113]
	v_mfma_f32_16x16x32_bf16 v[110:113], v[138:141], v[174:177], v[110:113]
	v_mfma_f32_16x16x32_bf16 v[94:97], v[106:109], v[178:181], v[94:97]
	v_mfma_f32_16x16x32_bf16 v[94:97], v[118:121], v[182:185], v[94:97]
	v_mfma_f32_16x16x32_bf16 v[90:93], v[130:133], v[178:181], v[90:93]
	v_mfma_f32_16x16x32_bf16 v[90:93], v[138:141], v[182:185], v[90:93]
	v_mfma_f32_16x16x32_bf16 v[78:81], v[106:109], v[190:193], v[78:81]
	v_mfma_f32_16x16x32_bf16 v[78:81], v[118:121], v[194:197], v[78:81]
	v_mfma_f32_16x16x32_bf16 v[74:77], v[130:133], v[190:193], v[74:77]
	v_mfma_f32_16x16x32_bf16 v[74:77], v[138:141], v[194:197], v[74:77]
	v_mfma_f32_16x16x32_bf16 v[126:129], v[146:149], v[162:165], v[126:129]
	v_mfma_f32_16x16x32_bf16 v[126:129], v[150:153], v[166:169], v[126:129]
	v_mfma_f32_16x16x32_bf16 v[122:125], v[154:157], v[162:165], v[122:125]
	v_mfma_f32_16x16x32_bf16 v[122:125], v[158:161], v[166:169], v[122:125]
	v_mfma_f32_16x16x32_bf16 v[102:105], v[146:149], v[170:173], v[102:105]
	v_mfma_f32_16x16x32_bf16 v[102:105], v[150:153], v[174:177], v[102:105]
	v_mfma_f32_16x16x32_bf16 v[98:101], v[154:157], v[170:173], v[98:101]
	v_mfma_f32_16x16x32_bf16 v[98:101], v[158:161], v[174:177], v[98:101]
	v_mfma_f32_16x16x32_bf16 v[86:89], v[146:149], v[178:181], v[86:89]
	v_mfma_f32_16x16x32_bf16 v[86:89], v[150:153], v[182:185], v[86:89]
	v_mfma_f32_16x16x32_bf16 v[82:85], v[154:157], v[178:181], v[82:85]
	v_mfma_f32_16x16x32_bf16 v[82:85], v[158:161], v[182:185], v[82:85]
	s_barrier
	v_mfma_f32_16x16x32_bf16 v[70:73], v[146:149], v[190:193], v[70:73]
	v_mfma_f32_16x16x32_bf16 v[70:73], v[150:153], v[194:197], v[70:73]
	v_mfma_f32_16x16x32_bf16 v[66:69], v[154:157], v[190:193], v[66:69]
	v_mfma_f32_16x16x32_bf16 v[66:69], v[158:161], v[194:197], v[66:69]
	s_setprio 0
	s_mov_b32 m0, s27
	s_mov_b32 s18, s14
	s_mov_b32 s19, s15
	ds_read_b128 v[162:165], v226 offset:16384
	ds_read_b128 v[166:169], v226 offset:17408
	ds_read_b128 v[170:173], v226 offset:18432
	ds_read_b128 v[174:177], v226 offset:19456
	ds_read_b128 v[178:181], v226 offset:20480
	ds_read_b128 v[182:185], v226 offset:21504
	ds_read_b128 v[190:193], v226 offset:22528
	ds_read_b128 v[194:197], v226 offset:23552
	buffer_load_dwordx4 v223, s[16:19], s77 offen lds
	s_add_i32 s78, s77, 0x80000
	s_mov_b32 m0, s30
	s_nop 0
	buffer_load_dwordx4 v223, s[16:19], s78 offen lds
	s_add_i32 s78, s77, 0x100000
	s_mov_b32 m0, s31
	s_nop 0
	buffer_load_dwordx4 v223, s[16:19], s78 offen lds
	s_add_i32 s78, s77, 0x180000
	s_mov_b32 m0, s41
	s_nop 0
	buffer_load_dwordx4 v223, s[16:19], s78 offen lds
	s_mov_b32 m0, s25
	s_add_i32 s78, s75, 0x80000
	buffer_load_dwordx4 v222, s[12:15], s75 offen lds
	s_mov_b32 m0, s42
	s_nop 0
	buffer_load_dwordx4 v222, s[12:15], s78 offen lds
	s_waitcnt vmcnt(8)
	s_waitcnt lgkmcnt(0)
	s_setprio 1
	v_mfma_f32_16x16x32_bf16 v[62:65], v[106:109], v[162:165], v[62:65]
	s_barrier
	v_mfma_f32_16x16x32_bf16 v[62:65], v[118:121], v[166:169], v[62:65]
	v_mfma_f32_16x16x32_bf16 v[58:61], v[130:133], v[162:165], v[58:61]
	v_mfma_f32_16x16x32_bf16 v[58:61], v[138:141], v[166:169], v[58:61]
	v_mfma_f32_16x16x32_bf16 v[46:49], v[106:109], v[170:173], v[46:49]
	v_mfma_f32_16x16x32_bf16 v[46:49], v[118:121], v[174:177], v[46:49]
	v_mfma_f32_16x16x32_bf16 v[42:45], v[130:133], v[170:173], v[42:45]
	v_mfma_f32_16x16x32_bf16 v[42:45], v[138:141], v[174:177], v[42:45]
	v_mfma_f32_16x16x32_bf16 v[30:33], v[106:109], v[178:181], v[30:33]
	v_mfma_f32_16x16x32_bf16 v[30:33], v[118:121], v[182:185], v[30:33]
	v_mfma_f32_16x16x32_bf16 v[26:29], v[130:133], v[178:181], v[26:29]
	v_mfma_f32_16x16x32_bf16 v[26:29], v[138:141], v[182:185], v[26:29]
	v_mfma_f32_16x16x32_bf16 v[14:17], v[106:109], v[190:193], v[14:17]
	v_mfma_f32_16x16x32_bf16 v[14:17], v[118:121], v[194:197], v[14:17]
	v_mfma_f32_16x16x32_bf16 v[10:13], v[130:133], v[190:193], v[10:13]
	v_mfma_f32_16x16x32_bf16 v[10:13], v[138:141], v[194:197], v[10:13]
	v_mfma_f32_16x16x32_bf16 v[54:57], v[146:149], v[162:165], v[54:57]
	v_mfma_f32_16x16x32_bf16 v[54:57], v[150:153], v[166:169], v[54:57]
	v_mfma_f32_16x16x32_bf16 v[50:53], v[154:157], v[162:165], v[50:53]
	v_mfma_f32_16x16x32_bf16 v[50:53], v[158:161], v[166:169], v[50:53]
	v_mfma_f32_16x16x32_bf16 v[38:41], v[146:149], v[170:173], v[38:41]
	v_mfma_f32_16x16x32_bf16 v[38:41], v[150:153], v[174:177], v[38:41]
	v_mfma_f32_16x16x32_bf16 v[34:37], v[154:157], v[170:173], v[34:37]
	v_mfma_f32_16x16x32_bf16 v[34:37], v[158:161], v[174:177], v[34:37]
	v_mfma_f32_16x16x32_bf16 v[22:25], v[146:149], v[178:181], v[22:25]
	v_mfma_f32_16x16x32_bf16 v[22:25], v[150:153], v[182:185], v[22:25]
	v_mfma_f32_16x16x32_bf16 v[18:21], v[154:157], v[178:181], v[18:21]
	v_mfma_f32_16x16x32_bf16 v[18:21], v[158:161], v[182:185], v[18:21]
	s_barrier
	v_mfma_f32_16x16x32_bf16 v[6:9], v[146:149], v[190:193], v[6:9]
	v_mfma_f32_16x16x32_bf16 v[6:9], v[150:153], v[194:197], v[6:9]
	v_mfma_f32_16x16x32_bf16 v[2:5], v[154:157], v[190:193], v[2:5]
	v_mfma_f32_16x16x32_bf16 v[2:5], v[158:161], v[194:197], v[2:5]
	s_setprio 0
	ds_read_b128 v[106:109], v227
	ds_read_b128 v[118:121], v227 offset:1024
	ds_read_b128 v[130:133], v227 offset:2048
	ds_read_b128 v[138:141], v227 offset:3072
	ds_read_b128 v[146:149], v228
	ds_read_b128 v[150:153], v228 offset:1024
	ds_read_b128 v[154:157], v228 offset:2048
	ds_read_b128 v[158:161], v228 offset:3072
	s_mov_b32 m0, s43
	s_add_i32 s78, s75, 0x100000
	ds_read_b128 v[162:165], v226 offset:32768
	ds_read_b128 v[166:169], v226 offset:33792
	ds_read_b128 v[170:173], v226 offset:34816
	ds_read_b128 v[174:177], v226 offset:35840
	ds_read_b128 v[178:181], v226 offset:36864
	ds_read_b128 v[182:185], v226 offset:37888
	ds_read_b128 v[190:193], v226 offset:38912
	ds_read_b128 v[194:197], v226 offset:39936
	buffer_load_dwordx4 v222, s[12:15], s78 offen lds
	s_add_i32 s78, s75, 0x180000
	s_mov_b32 m0, s44
	s_nop 0
	buffer_load_dwordx4 v222, s[12:15], s78 offen lds
	s_waitcnt vmcnt(8)
	s_waitcnt lgkmcnt(0)
	s_setprio 1
	v_mfma_f32_16x16x32_bf16 v[142:145], v[106:109], v[162:165], v[142:145]
	s_barrier
	v_mfma_f32_16x16x32_bf16 v[142:145], v[118:121], v[166:169], v[142:145]
	v_mfma_f32_16x16x32_bf16 v[134:137], v[130:133], v[162:165], v[134:137]
	v_mfma_f32_16x16x32_bf16 v[134:137], v[138:141], v[166:169], v[134:137]
	v_mfma_f32_16x16x32_bf16 v[114:117], v[106:109], v[170:173], v[114:117]
	v_mfma_f32_16x16x32_bf16 v[114:117], v[118:121], v[174:177], v[114:117]
	v_mfma_f32_16x16x32_bf16 v[110:113], v[130:133], v[170:173], v[110:113]
	v_mfma_f32_16x16x32_bf16 v[110:113], v[138:141], v[174:177], v[110:113]
	v_mfma_f32_16x16x32_bf16 v[94:97], v[106:109], v[178:181], v[94:97]
	v_mfma_f32_16x16x32_bf16 v[94:97], v[118:121], v[182:185], v[94:97]
	v_mfma_f32_16x16x32_bf16 v[90:93], v[130:133], v[178:181], v[90:93]
	v_mfma_f32_16x16x32_bf16 v[90:93], v[138:141], v[182:185], v[90:93]
	v_mfma_f32_16x16x32_bf16 v[78:81], v[106:109], v[190:193], v[78:81]
	v_mfma_f32_16x16x32_bf16 v[78:81], v[118:121], v[194:197], v[78:81]
	v_mfma_f32_16x16x32_bf16 v[74:77], v[130:133], v[190:193], v[74:77]
	v_mfma_f32_16x16x32_bf16 v[74:77], v[138:141], v[194:197], v[74:77]
	v_mfma_f32_16x16x32_bf16 v[126:129], v[146:149], v[162:165], v[126:129]
	v_mfma_f32_16x16x32_bf16 v[126:129], v[150:153], v[166:169], v[126:129]
	v_mfma_f32_16x16x32_bf16 v[122:125], v[154:157], v[162:165], v[122:125]
	v_mfma_f32_16x16x32_bf16 v[122:125], v[158:161], v[166:169], v[122:125]
	v_mfma_f32_16x16x32_bf16 v[102:105], v[146:149], v[170:173], v[102:105]
	v_mfma_f32_16x16x32_bf16 v[102:105], v[150:153], v[174:177], v[102:105]
	v_mfma_f32_16x16x32_bf16 v[98:101], v[154:157], v[170:173], v[98:101]
	v_mfma_f32_16x16x32_bf16 v[98:101], v[158:161], v[174:177], v[98:101]
	v_mfma_f32_16x16x32_bf16 v[86:89], v[146:149], v[178:181], v[86:89]
	v_mfma_f32_16x16x32_bf16 v[86:89], v[150:153], v[182:185], v[86:89]
	v_mfma_f32_16x16x32_bf16 v[82:85], v[154:157], v[178:181], v[82:85]
	v_mfma_f32_16x16x32_bf16 v[82:85], v[158:161], v[182:185], v[82:85]
	s_barrier
	v_mfma_f32_16x16x32_bf16 v[70:73], v[146:149], v[190:193], v[70:73]
	v_mfma_f32_16x16x32_bf16 v[70:73], v[150:153], v[194:197], v[70:73]
	v_mfma_f32_16x16x32_bf16 v[66:69], v[154:157], v[190:193], v[66:69]
	v_mfma_f32_16x16x32_bf16 v[66:69], v[158:161], v[194:197], v[66:69]
	s_setprio 0
	s_mov_b32 m0, s48
	s_or_b32 s78, s77, 0x80
	ds_read_b128 v[162:165], v226 offset:49152
	ds_read_b128 v[166:169], v226 offset:50176
	ds_read_b128 v[170:173], v226 offset:51200
	ds_read_b128 v[174:177], v226 offset:52224
	ds_read_b128 v[178:181], v226 offset:53248
	ds_read_b128 v[182:185], v226 offset:54272
	ds_read_b128 v[190:193], v226 offset:55296
	ds_read_b128 v[194:197], v226 offset:56320
	buffer_load_dwordx4 v223, s[16:19], s78 offen lds
	s_add_i32 s78, s77, 0x80080
	s_mov_b32 m0, s49
	s_add_i32 s75, s75, 0x80080
	buffer_load_dwordx4 v223, s[16:19], s78 offen lds
	s_add_i32 s78, s77, 0x100080
	s_mov_b32 m0, s52
	s_add_i32 s77, s77, 0x180080
	buffer_load_dwordx4 v223, s[16:19], s78 offen lds
	s_mov_b32 m0, s53
	s_nop 0
	buffer_load_dwordx4 v223, s[16:19], s77 offen lds
	s_mov_b32 m0, s50
	s_nop 0
	buffer_load_dwordx4 v222, s[12:15], s76 offen lds
	s_mov_b32 m0, s51
	s_nop 0
	buffer_load_dwordx4 v222, s[12:15], s75 offen lds
	s_waitcnt vmcnt(8)
	s_waitcnt lgkmcnt(0)
	s_setprio 1
	v_mfma_f32_16x16x32_bf16 v[62:65], v[106:109], v[162:165], v[62:65]
	s_barrier
	v_mfma_f32_16x16x32_bf16 v[62:65], v[118:121], v[166:169], v[62:65]
	v_mfma_f32_16x16x32_bf16 v[58:61], v[130:133], v[162:165], v[58:61]
	v_mfma_f32_16x16x32_bf16 v[58:61], v[138:141], v[166:169], v[58:61]
	v_mfma_f32_16x16x32_bf16 v[46:49], v[106:109], v[170:173], v[46:49]
	v_mfma_f32_16x16x32_bf16 v[46:49], v[118:121], v[174:177], v[46:49]
	v_mfma_f32_16x16x32_bf16 v[42:45], v[130:133], v[170:173], v[42:45]
	v_mfma_f32_16x16x32_bf16 v[42:45], v[138:141], v[174:177], v[42:45]
	v_mfma_f32_16x16x32_bf16 v[30:33], v[106:109], v[178:181], v[30:33]
	v_mfma_f32_16x16x32_bf16 v[30:33], v[118:121], v[182:185], v[30:33]
	v_mfma_f32_16x16x32_bf16 v[26:29], v[130:133], v[178:181], v[26:29]
	v_mfma_f32_16x16x32_bf16 v[26:29], v[138:141], v[182:185], v[26:29]
	v_mfma_f32_16x16x32_bf16 v[14:17], v[106:109], v[190:193], v[14:17]
	v_mfma_f32_16x16x32_bf16 v[14:17], v[118:121], v[194:197], v[14:17]
	v_mfma_f32_16x16x32_bf16 v[10:13], v[130:133], v[190:193], v[10:13]
	v_mfma_f32_16x16x32_bf16 v[10:13], v[138:141], v[194:197], v[10:13]
	v_mfma_f32_16x16x32_bf16 v[54:57], v[146:149], v[162:165], v[54:57]
	v_mfma_f32_16x16x32_bf16 v[54:57], v[150:153], v[166:169], v[54:57]
	v_mfma_f32_16x16x32_bf16 v[50:53], v[154:157], v[162:165], v[50:53]
	v_mfma_f32_16x16x32_bf16 v[50:53], v[158:161], v[166:169], v[50:53]
	v_mfma_f32_16x16x32_bf16 v[38:41], v[146:149], v[170:173], v[38:41]
	v_mfma_f32_16x16x32_bf16 v[38:41], v[150:153], v[174:177], v[38:41]
	v_mfma_f32_16x16x32_bf16 v[34:37], v[154:157], v[170:173], v[34:37]
	v_mfma_f32_16x16x32_bf16 v[34:37], v[158:161], v[174:177], v[34:37]
	v_mfma_f32_16x16x32_bf16 v[22:25], v[146:149], v[178:181], v[22:25]
	v_mfma_f32_16x16x32_bf16 v[22:25], v[150:153], v[182:185], v[22:25]
	v_mfma_f32_16x16x32_bf16 v[18:21], v[154:157], v[178:181], v[18:21]
	v_mfma_f32_16x16x32_bf16 v[18:21], v[158:161], v[182:185], v[18:21]
	s_barrier
	v_mfma_f32_16x16x32_bf16 v[6:9], v[146:149], v[190:193], v[6:9]
	v_mfma_f32_16x16x32_bf16 v[6:9], v[150:153], v[194:197], v[6:9]
	v_mfma_f32_16x16x32_bf16 v[2:5], v[154:157], v[190:193], v[2:5]
	v_mfma_f32_16x16x32_bf16 v[2:5], v[158:161], v[194:197], v[2:5]
	s_setprio 0
	s_add_i32 s74, s74, 2
	s_addk_i32 s72, 0x100
	s_addk_i32 s73, 0x100
	s_cmp_ge_i32 s74, s3
	s_cbranch_scc0 .LBB0_1290
	s_and_b64 vcc, exec, s[38:39]
	s_cbranch_vccz .LBB0_1293

.LBB0_1382:
	ds_read_b128 v[144:147], v138
	ds_read_b128 v[148:151], v138 offset:1024
	ds_read_b128 v[152:155], v138 offset:2048
	ds_read_b128 v[156:159], v138 offset:3072
	ds_read_b128 v[160:163], v139
	ds_read_b128 v[164:167], v139 offset:1024
	ds_read_b128 v[168:171], v139 offset:2048
	ds_read_b128 v[172:175], v139 offset:3072
	s_add_i32 s14, s74, 0xffe80080
	s_cmp_eq_u32 s61, s76
	s_cselect_b32 s77, s72, s14
	s_cselect_b32 s79, s73, s75
	s_or_b32 s78, s77, 0x80
	s_add_i32 s14, s74, 0xfff80000
	s_mov_b32 m0, s62
	ds_read_b128 v[176:179], v140
	ds_read_b128 v[180:183], v140 offset:1024
	ds_read_b128 v[184:187], v140 offset:2048
	ds_read_b128 v[188:191], v140 offset:3072
	ds_read_b128 v[192:195], v140 offset:4096
	ds_read_b128 v[196:199], v140 offset:5120
	ds_read_b128 v[200:203], v140 offset:6144
	ds_read_b128 v[204:207], v140 offset:7168
	buffer_load_dwordx4 v136, s[16:19], s14 offen lds
	s_mov_b32 m0, s63
	s_nop 0
	buffer_load_dwordx4 v136, s[16:19], s74 offen lds
	s_waitcnt vmcnt(8)
	s_waitcnt lgkmcnt(0)
	s_setprio 1
	v_mfma_f32_16x16x32_bf16 v[118:121], v[144:147], v[176:179], v[118:121]
	s_barrier
	v_mfma_f32_16x16x32_bf16 v[118:121], v[148:151], v[180:183], v[118:121]
	v_mfma_f32_16x16x32_bf16 v[114:117], v[152:155], v[176:179], v[114:117]
	v_mfma_f32_16x16x32_bf16 v[114:117], v[156:159], v[180:183], v[114:117]
	v_mfma_f32_16x16x32_bf16 v[110:113], v[144:147], v[184:187], v[110:113]
	v_mfma_f32_16x16x32_bf16 v[110:113], v[148:151], v[188:191], v[110:113]
	v_mfma_f32_16x16x32_bf16 v[102:105], v[152:155], v[184:187], v[102:105]
	v_mfma_f32_16x16x32_bf16 v[102:105], v[156:159], v[188:191], v[102:105]
	v_mfma_f32_16x16x32_bf16 v[94:97], v[144:147], v[192:195], v[94:97]
	v_mfma_f32_16x16x32_bf16 v[94:97], v[148:151], v[196:199], v[94:97]
	v_mfma_f32_16x16x32_bf16 v[86:89], v[152:155], v[192:195], v[86:89]
	v_mfma_f32_16x16x32_bf16 v[86:89], v[156:159], v[196:199], v[86:89]
	v_mfma_f32_16x16x32_bf16 v[78:81], v[144:147], v[200:203], v[78:81]
	v_mfma_f32_16x16x32_bf16 v[78:81], v[148:151], v[204:207], v[78:81]
	v_mfma_f32_16x16x32_bf16 v[66:69], v[152:155], v[200:203], v[66:69]
	v_mfma_f32_16x16x32_bf16 v[66:69], v[156:159], v[204:207], v[66:69]
	v_mfma_f32_16x16x32_bf16 v[126:129], v[160:163], v[176:179], v[126:129]
	v_mfma_f32_16x16x32_bf16 v[126:129], v[164:167], v[180:183], v[126:129]
	v_mfma_f32_16x16x32_bf16 v[122:125], v[168:171], v[176:179], v[122:125]
	v_mfma_f32_16x16x32_bf16 v[122:125], v[172:175], v[180:183], v[122:125]
	v_mfma_f32_16x16x32_bf16 v[106:109], v[160:163], v[184:187], v[106:109]
	v_mfma_f32_16x16x32_bf16 v[106:109], v[164:167], v[188:191], v[106:109]
	v_mfma_f32_16x16x32_bf16 v[98:101], v[168:171], v[184:187], v[98:101]
	v_mfma_f32_16x16x32_bf16 v[98:101], v[172:175], v[188:191], v[98:101]
	v_mfma_f32_16x16x32_bf16 v[90:93], v[160:163], v[192:195], v[90:93]
	v_mfma_f32_16x16x32_bf16 v[90:93], v[164:167], v[196:199], v[90:93]
	v_mfma_f32_16x16x32_bf16 v[82:85], v[168:171], v[192:195], v[82:85]
	v_mfma_f32_16x16x32_bf16 v[82:85], v[172:175], v[196:199], v[82:85]
	s_barrier
	v_mfma_f32_16x16x32_bf16 v[74:77], v[160:163], v[200:203], v[74:77]
	v_mfma_f32_16x16x32_bf16 v[74:77], v[164:167], v[204:207], v[74:77]
	v_mfma_f32_16x16x32_bf16 v[70:73], v[168:171], v[200:203], v[70:73]
	v_mfma_f32_16x16x32_bf16 v[70:73], v[172:175], v[204:207], v[70:73]
	s_setprio 0
	s_mov_b32 m0, s45
	s_mov_b32 s14, s18
	s_mov_b32 s15, s19
	ds_read_b128 v[176:179], v140 offset:16384
	ds_read_b128 v[180:183], v140 offset:17408
	ds_read_b128 v[184:187], v140 offset:18432
	ds_read_b128 v[188:191], v140 offset:19456
	ds_read_b128 v[192:195], v140 offset:20480
	ds_read_b128 v[196:199], v140 offset:21504
	ds_read_b128 v[200:203], v140 offset:22528
	ds_read_b128 v[204:207], v140 offset:23552
	buffer_load_dwordx4 v137, s[12:15], s79 offen lds
	s_add_i32 s80, s79, 0x80000
	s_mov_b32 m0, s46
	s_nop 0
	buffer_load_dwordx4 v137, s[12:15], s80 offen lds
	s_add_i32 s80, s79, 0x100000
	s_mov_b32 m0, s47
	s_nop 0
	buffer_load_dwordx4 v137, s[12:15], s80 offen lds
	s_add_i32 s80, s79, 0x180000
	s_mov_b32 m0, s48
	s_nop 0
	buffer_load_dwordx4 v137, s[12:15], s80 offen lds
	s_mov_b32 m0, s44
	s_add_i32 s80, s77, 0x80000
	buffer_load_dwordx4 v136, s[16:19], s77 offen lds
	s_mov_b32 m0, s49
	s_nop 0
	buffer_load_dwordx4 v136, s[16:19], s80 offen lds
	s_waitcnt vmcnt(8)
	s_waitcnt lgkmcnt(0)
	s_setprio 1
	v_mfma_f32_16x16x32_bf16 v[62:65], v[144:147], v[176:179], v[62:65]
	s_barrier
	v_mfma_f32_16x16x32_bf16 v[62:65], v[148:151], v[180:183], v[62:65]
	v_mfma_f32_16x16x32_bf16 v[54:57], v[152:155], v[176:179], v[54:57]
	v_mfma_f32_16x16x32_bf16 v[54:57], v[156:159], v[180:183], v[54:57]
	v_mfma_f32_16x16x32_bf16 v[46:49], v[144:147], v[184:187], v[46:49]
	v_mfma_f32_16x16x32_bf16 v[46:49], v[148:151], v[188:191], v[46:49]
	v_mfma_f32_16x16x32_bf16 v[38:41], v[152:155], v[184:187], v[38:41]
	v_mfma_f32_16x16x32_bf16 v[38:41], v[156:159], v[188:191], v[38:41]
	v_mfma_f32_16x16x32_bf16 v[30:33], v[144:147], v[192:195], v[30:33]
	v_mfma_f32_16x16x32_bf16 v[30:33], v[148:151], v[196:199], v[30:33]
	v_mfma_f32_16x16x32_bf16 v[22:25], v[152:155], v[192:195], v[22:25]
	v_mfma_f32_16x16x32_bf16 v[22:25], v[156:159], v[196:199], v[22:25]
	v_mfma_f32_16x16x32_bf16 v[14:17], v[144:147], v[200:203], v[14:17]
	v_mfma_f32_16x16x32_bf16 v[14:17], v[148:151], v[204:207], v[14:17]
	v_mfma_f32_16x16x32_bf16 v[6:9], v[152:155], v[200:203], v[6:9]
	v_mfma_f32_16x16x32_bf16 v[6:9], v[156:159], v[204:207], v[6:9]
	v_mfma_f32_16x16x32_bf16 v[58:61], v[160:163], v[176:179], v[58:61]
	v_mfma_f32_16x16x32_bf16 v[58:61], v[164:167], v[180:183], v[58:61]
	v_mfma_f32_16x16x32_bf16 v[50:53], v[168:171], v[176:179], v[50:53]
	v_mfma_f32_16x16x32_bf16 v[50:53], v[172:175], v[180:183], v[50:53]
	v_mfma_f32_16x16x32_bf16 v[42:45], v[160:163], v[184:187], v[42:45]
	v_mfma_f32_16x16x32_bf16 v[42:45], v[164:167], v[188:191], v[42:45]
	v_mfma_f32_16x16x32_bf16 v[34:37], v[168:171], v[184:187], v[34:37]
	v_mfma_f32_16x16x32_bf16 v[34:37], v[172:175], v[188:191], v[34:37]
	v_mfma_f32_16x16x32_bf16 v[26:29], v[160:163], v[192:195], v[26:29]
	v_mfma_f32_16x16x32_bf16 v[26:29], v[164:167], v[196:199], v[26:29]
	v_mfma_f32_16x16x32_bf16 v[18:21], v[168:171], v[192:195], v[18:21]
	v_mfma_f32_16x16x32_bf16 v[18:21], v[172:175], v[196:199], v[18:21]
	s_barrier
	v_mfma_f32_16x16x32_bf16 v[10:13], v[160:163], v[200:203], v[10:13]
	v_mfma_f32_16x16x32_bf16 v[10:13], v[164:167], v[204:207], v[10:13]
	v_mfma_f32_16x16x32_bf16 v[2:5], v[168:171], v[200:203], v[2:5]
	v_mfma_f32_16x16x32_bf16 v[2:5], v[172:175], v[204:207], v[2:5]
	s_setprio 0
	ds_read_b128 v[144:147], v141
	ds_read_b128 v[148:151], v141 offset:1024
	ds_read_b128 v[152:155], v141 offset:2048
	ds_read_b128 v[156:159], v141 offset:3072
	ds_read_b128 v[160:163], v142
	ds_read_b128 v[164:167], v142 offset:1024
	ds_read_b128 v[168:171], v142 offset:2048
	ds_read_b128 v[172:175], v142 offset:3072
	s_mov_b32 m0, s50
	s_add_i32 s80, s77, 0x100000
	ds_read_b128 v[176:179], v140 offset:32768
	ds_read_b128 v[180:183], v140 offset:33792
	ds_read_b128 v[184:187], v140 offset:34816
	ds_read_b128 v[188:191], v140 offset:35840
	ds_read_b128 v[192:195], v140 offset:36864
	ds_read_b128 v[196:199], v140 offset:37888
	ds_read_b128 v[200:203], v140 offset:38912
	ds_read_b128 v[204:207], v140 offset:39936
	buffer_load_dwordx4 v136, s[16:19], s80 offen lds
	s_add_i32 s80, s77, 0x180000
	s_mov_b32 m0, s51
	s_nop 0
	buffer_load_dwordx4 v136, s[16:19], s80 offen lds
	s_waitcnt vmcnt(8)
	s_waitcnt lgkmcnt(0)
	s_setprio 1
	v_mfma_f32_16x16x32_bf16 v[118:121], v[144:147], v[176:179], v[118:121]
	s_barrier
	v_mfma_f32_16x16x32_bf16 v[118:121], v[148:151], v[180:183], v[118:121]
	v_mfma_f32_16x16x32_bf16 v[114:117], v[152:155], v[176:179], v[114:117]
	v_mfma_f32_16x16x32_bf16 v[114:117], v[156:159], v[180:183], v[114:117]
	v_mfma_f32_16x16x32_bf16 v[110:113], v[144:147], v[184:187], v[110:113]
	v_mfma_f32_16x16x32_bf16 v[110:113], v[148:151], v[188:191], v[110:113]
	v_mfma_f32_16x16x32_bf16 v[102:105], v[152:155], v[184:187], v[102:105]
	v_mfma_f32_16x16x32_bf16 v[102:105], v[156:159], v[188:191], v[102:105]
	v_mfma_f32_16x16x32_bf16 v[94:97], v[144:147], v[192:195], v[94:97]
	v_mfma_f32_16x16x32_bf16 v[94:97], v[148:151], v[196:199], v[94:97]
	v_mfma_f32_16x16x32_bf16 v[86:89], v[152:155], v[192:195], v[86:89]
	v_mfma_f32_16x16x32_bf16 v[86:89], v[156:159], v[196:199], v[86:89]
	v_mfma_f32_16x16x32_bf16 v[78:81], v[144:147], v[200:203], v[78:81]
	v_mfma_f32_16x16x32_bf16 v[78:81], v[148:151], v[204:207], v[78:81]
	v_mfma_f32_16x16x32_bf16 v[66:69], v[152:155], v[200:203], v[66:69]
	v_mfma_f32_16x16x32_bf16 v[66:69], v[156:159], v[204:207], v[66:69]
	v_mfma_f32_16x16x32_bf16 v[126:129], v[160:163], v[176:179], v[126:129]
	v_mfma_f32_16x16x32_bf16 v[126:129], v[164:167], v[180:183], v[126:129]
	v_mfma_f32_16x16x32_bf16 v[122:125], v[168:171], v[176:179], v[122:125]
	v_mfma_f32_16x16x32_bf16 v[122:125], v[172:175], v[180:183], v[122:125]
	v_mfma_f32_16x16x32_bf16 v[106:109], v[160:163], v[184:187], v[106:109]
	v_mfma_f32_16x16x32_bf16 v[106:109], v[164:167], v[188:191], v[106:109]
	v_mfma_f32_16x16x32_bf16 v[98:101], v[168:171], v[184:187], v[98:101]
	v_mfma_f32_16x16x32_bf16 v[98:101], v[172:175], v[188:191], v[98:101]
	v_mfma_f32_16x16x32_bf16 v[90:93], v[160:163], v[192:195], v[90:93]
	v_mfma_f32_16x16x32_bf16 v[90:93], v[164:167], v[196:199], v[90:93]
	v_mfma_f32_16x16x32_bf16 v[82:85], v[168:171], v[192:195], v[82:85]
	v_mfma_f32_16x16x32_bf16 v[82:85], v[172:175], v[196:199], v[82:85]
	s_barrier
	v_mfma_f32_16x16x32_bf16 v[74:77], v[160:163], v[200:203], v[74:77]
	v_mfma_f32_16x16x32_bf16 v[74:77], v[164:167], v[204:207], v[74:77]
	v_mfma_f32_16x16x32_bf16 v[70:73], v[168:171], v[200:203], v[70:73]
	v_mfma_f32_16x16x32_bf16 v[70:73], v[172:175], v[204:207], v[70:73]
	s_setprio 0
	s_mov_b32 m0, s53
	s_or_b32 s80, s79, 0x80
	ds_read_b128 v[176:179], v140 offset:49152
	ds_read_b128 v[180:183], v140 offset:50176
	ds_read_b128 v[184:187], v140 offset:51200
	ds_read_b128 v[188:191], v140 offset:52224
	ds_read_b128 v[192:195], v140 offset:53248
	ds_read_b128 v[196:199], v140 offset:54272
	ds_read_b128 v[200:203], v140 offset:55296
	ds_read_b128 v[204:207], v140 offset:56320
	buffer_load_dwordx4 v137, s[12:15], s80 offen lds
	s_add_i32 s80, s79, 0x80080
	s_mov_b32 m0, s54
	s_add_i32 s77, s77, 0x80080
	buffer_load_dwordx4 v137, s[12:15], s80 offen lds
	s_add_i32 s80, s79, 0x100080
	s_mov_b32 m0, s57
	s_add_i32 s79, s79, 0x180080
	buffer_load_dwordx4 v137, s[12:15], s80 offen lds
	s_mov_b32 m0, s58
	s_nop 0
	buffer_load_dwordx4 v137, s[12:15], s79 offen lds
	s_mov_b32 m0, s55
	s_nop 0
	buffer_load_dwordx4 v136, s[16:19], s78 offen lds
	s_mov_b32 m0, s56
	s_nop 0
	buffer_load_dwordx4 v136, s[16:19], s77 offen lds
	s_waitcnt vmcnt(8)
	s_waitcnt lgkmcnt(0)
	s_setprio 1
	v_mfma_f32_16x16x32_bf16 v[62:65], v[144:147], v[176:179], v[62:65]
	s_barrier
	v_mfma_f32_16x16x32_bf16 v[62:65], v[148:151], v[180:183], v[62:65]
	v_mfma_f32_16x16x32_bf16 v[54:57], v[152:155], v[176:179], v[54:57]
	v_mfma_f32_16x16x32_bf16 v[54:57], v[156:159], v[180:183], v[54:57]
	v_mfma_f32_16x16x32_bf16 v[46:49], v[144:147], v[184:187], v[46:49]
	v_mfma_f32_16x16x32_bf16 v[46:49], v[148:151], v[188:191], v[46:49]
	v_mfma_f32_16x16x32_bf16 v[38:41], v[152:155], v[184:187], v[38:41]
	v_mfma_f32_16x16x32_bf16 v[38:41], v[156:159], v[188:191], v[38:41]
	v_mfma_f32_16x16x32_bf16 v[30:33], v[144:147], v[192:195], v[30:33]
	v_mfma_f32_16x16x32_bf16 v[30:33], v[148:151], v[196:199], v[30:33]
	v_mfma_f32_16x16x32_bf16 v[22:25], v[152:155], v[192:195], v[22:25]
	v_mfma_f32_16x16x32_bf16 v[22:25], v[156:159], v[196:199], v[22:25]
	v_mfma_f32_16x16x32_bf16 v[14:17], v[144:147], v[200:203], v[14:17]
	v_mfma_f32_16x16x32_bf16 v[14:17], v[148:151], v[204:207], v[14:17]
	v_mfma_f32_16x16x32_bf16 v[6:9], v[152:155], v[200:203], v[6:9]
	v_mfma_f32_16x16x32_bf16 v[6:9], v[156:159], v[204:207], v[6:9]
	v_mfma_f32_16x16x32_bf16 v[58:61], v[160:163], v[176:179], v[58:61]
	v_mfma_f32_16x16x32_bf16 v[58:61], v[164:167], v[180:183], v[58:61]
	v_mfma_f32_16x16x32_bf16 v[50:53], v[168:171], v[176:179], v[50:53]
	v_mfma_f32_16x16x32_bf16 v[50:53], v[172:175], v[180:183], v[50:53]
	v_mfma_f32_16x16x32_bf16 v[42:45], v[160:163], v[184:187], v[42:45]
	v_mfma_f32_16x16x32_bf16 v[42:45], v[164:167], v[188:191], v[42:45]
	v_mfma_f32_16x16x32_bf16 v[34:37], v[168:171], v[184:187], v[34:37]
	v_mfma_f32_16x16x32_bf16 v[34:37], v[172:175], v[188:191], v[34:37]
	v_mfma_f32_16x16x32_bf16 v[26:29], v[160:163], v[192:195], v[26:29]
	v_mfma_f32_16x16x32_bf16 v[26:29], v[164:167], v[196:199], v[26:29]
	v_mfma_f32_16x16x32_bf16 v[18:21], v[168:171], v[192:195], v[18:21]
	v_mfma_f32_16x16x32_bf16 v[18:21], v[172:175], v[196:199], v[18:21]
	s_barrier
	v_mfma_f32_16x16x32_bf16 v[10:13], v[160:163], v[200:203], v[10:13]
	v_mfma_f32_16x16x32_bf16 v[10:13], v[164:167], v[204:207], v[10:13]
	v_mfma_f32_16x16x32_bf16 v[2:5], v[168:171], v[200:203], v[2:5]
	v_mfma_f32_16x16x32_bf16 v[2:5], v[172:175], v[204:207], v[2:5]
	s_setprio 0
	s_add_i32 s76, s76, 2
	s_addk_i32 s74, 0x100
	s_addk_i32 s75, 0x100
	s_cmp_ge_i32 s76, s27
	s_cbranch_scc0 .LBB0_1382
	s_and_b64 vcc, exec, s[42:43]
	s_cbranch_vccz .LBB0_1385

.LBB0_1402:
	ds_read_b128 v[146:149], v138
	ds_read_b128 v[150:153], v138 offset:1024
	ds_read_b128 v[154:157], v138 offset:2048
	ds_read_b128 v[158:161], v138 offset:3072
	ds_read_b128 v[162:165], v139
	ds_read_b128 v[166:169], v139 offset:1024
	ds_read_b128 v[170:173], v139 offset:2048
	ds_read_b128 v[174:177], v139 offset:3072
	s_add_i32 s22, s75, 0xffe80080
	s_cmp_eq_u32 s62, s77
	s_cselect_b32 s78, s73, s22
	s_cselect_b32 s80, s74, s76
	s_or_b32 s79, s78, 0x80
	s_add_i32 s22, s75, 0xfff80000
	s_mov_b32 m0, s63
	ds_read_b128 v[178:181], v140
	ds_read_b128 v[182:185], v140 offset:1024
	ds_read_b128 v[186:189], v140 offset:2048
	ds_read_b128 v[190:193], v140 offset:3072
	ds_read_b128 v[194:197], v140 offset:4096
	ds_read_b128 v[198:201], v140 offset:5120
	ds_read_b128 v[202:205], v140 offset:6144
	ds_read_b128 v[206:209], v140 offset:7168
	buffer_load_dwordx4 v136, s[16:19], s22 offen lds
	s_mov_b32 m0, s64
	s_nop 0
	buffer_load_dwordx4 v136, s[16:19], s75 offen lds
	s_waitcnt vmcnt(8)
	s_waitcnt lgkmcnt(0)
	s_setprio 1
	v_mfma_f32_16x16x32_bf16 v[118:121], v[146:149], v[178:181], v[118:121]
	s_barrier
	v_mfma_f32_16x16x32_bf16 v[118:121], v[150:153], v[182:185], v[118:121]
	v_mfma_f32_16x16x32_bf16 v[114:117], v[154:157], v[178:181], v[114:117]
	v_mfma_f32_16x16x32_bf16 v[114:117], v[158:161], v[182:185], v[114:117]
	v_mfma_f32_16x16x32_bf16 v[110:113], v[146:149], v[186:189], v[110:113]
	v_mfma_f32_16x16x32_bf16 v[110:113], v[150:153], v[190:193], v[110:113]
	v_mfma_f32_16x16x32_bf16 v[102:105], v[154:157], v[186:189], v[102:105]
	v_mfma_f32_16x16x32_bf16 v[102:105], v[158:161], v[190:193], v[102:105]
	v_mfma_f32_16x16x32_bf16 v[94:97], v[146:149], v[194:197], v[94:97]
	v_mfma_f32_16x16x32_bf16 v[94:97], v[150:153], v[198:201], v[94:97]
	v_mfma_f32_16x16x32_bf16 v[86:89], v[154:157], v[194:197], v[86:89]
	v_mfma_f32_16x16x32_bf16 v[86:89], v[158:161], v[198:201], v[86:89]
	v_mfma_f32_16x16x32_bf16 v[78:81], v[146:149], v[202:205], v[78:81]
	v_mfma_f32_16x16x32_bf16 v[78:81], v[150:153], v[206:209], v[78:81]
	v_mfma_f32_16x16x32_bf16 v[66:69], v[154:157], v[202:205], v[66:69]
	v_mfma_f32_16x16x32_bf16 v[66:69], v[158:161], v[206:209], v[66:69]
	v_mfma_f32_16x16x32_bf16 v[126:129], v[162:165], v[178:181], v[126:129]
	v_mfma_f32_16x16x32_bf16 v[126:129], v[166:169], v[182:185], v[126:129]
	v_mfma_f32_16x16x32_bf16 v[122:125], v[170:173], v[178:181], v[122:125]
	v_mfma_f32_16x16x32_bf16 v[122:125], v[174:177], v[182:185], v[122:125]
	v_mfma_f32_16x16x32_bf16 v[106:109], v[162:165], v[186:189], v[106:109]
	v_mfma_f32_16x16x32_bf16 v[106:109], v[166:169], v[190:193], v[106:109]
	v_mfma_f32_16x16x32_bf16 v[98:101], v[170:173], v[186:189], v[98:101]
	v_mfma_f32_16x16x32_bf16 v[98:101], v[174:177], v[190:193], v[98:101]
	v_mfma_f32_16x16x32_bf16 v[90:93], v[162:165], v[194:197], v[90:93]
	v_mfma_f32_16x16x32_bf16 v[90:93], v[166:169], v[198:201], v[90:93]
	v_mfma_f32_16x16x32_bf16 v[82:85], v[170:173], v[194:197], v[82:85]
	v_mfma_f32_16x16x32_bf16 v[82:85], v[174:177], v[198:201], v[82:85]
	s_barrier
	v_mfma_f32_16x16x32_bf16 v[74:77], v[162:165], v[202:205], v[74:77]
	v_mfma_f32_16x16x32_bf16 v[74:77], v[166:169], v[206:209], v[74:77]
	v_mfma_f32_16x16x32_bf16 v[70:73], v[170:173], v[202:205], v[70:73]
	v_mfma_f32_16x16x32_bf16 v[70:73], v[174:177], v[206:209], v[70:73]
	s_setprio 0
	s_mov_b32 m0, s31
	s_mov_b32 s22, s18
	s_mov_b32 s23, s19
	ds_read_b128 v[178:181], v140 offset:16384
	ds_read_b128 v[182:185], v140 offset:17408
	ds_read_b128 v[186:189], v140 offset:18432
	ds_read_b128 v[190:193], v140 offset:19456
	ds_read_b128 v[194:197], v140 offset:20480
	ds_read_b128 v[198:201], v140 offset:21504
	ds_read_b128 v[202:205], v140 offset:22528
	ds_read_b128 v[206:209], v140 offset:23552
	buffer_load_dwordx4 v137, s[20:23], s80 offen lds
	s_add_i32 s81, s80, 0x80000
	s_mov_b32 m0, s48
	s_nop 0
	buffer_load_dwordx4 v137, s[20:23], s81 offen lds
	s_add_i32 s81, s80, 0x100000
	s_mov_b32 m0, s49
	s_nop 0
	buffer_load_dwordx4 v137, s[20:23], s81 offen lds
	s_add_i32 s81, s80, 0x180000
	s_mov_b32 m0, s50
	s_nop 0
	buffer_load_dwordx4 v137, s[20:23], s81 offen lds
	s_mov_b32 m0, s30
	s_add_i32 s81, s78, 0x80000
	buffer_load_dwordx4 v136, s[16:19], s78 offen lds
	s_mov_b32 m0, s51
	s_nop 0
	buffer_load_dwordx4 v136, s[16:19], s81 offen lds
	s_waitcnt vmcnt(8)
	s_waitcnt lgkmcnt(0)
	s_setprio 1
	v_mfma_f32_16x16x32_bf16 v[62:65], v[146:149], v[178:181], v[62:65]
	s_barrier
	v_mfma_f32_16x16x32_bf16 v[62:65], v[150:153], v[182:185], v[62:65]
	v_mfma_f32_16x16x32_bf16 v[54:57], v[154:157], v[178:181], v[54:57]
	v_mfma_f32_16x16x32_bf16 v[54:57], v[158:161], v[182:185], v[54:57]
	v_mfma_f32_16x16x32_bf16 v[46:49], v[146:149], v[186:189], v[46:49]
	v_mfma_f32_16x16x32_bf16 v[46:49], v[150:153], v[190:193], v[46:49]
	v_mfma_f32_16x16x32_bf16 v[38:41], v[154:157], v[186:189], v[38:41]
	v_mfma_f32_16x16x32_bf16 v[38:41], v[158:161], v[190:193], v[38:41]
	v_mfma_f32_16x16x32_bf16 v[30:33], v[146:149], v[194:197], v[30:33]
	v_mfma_f32_16x16x32_bf16 v[30:33], v[150:153], v[198:201], v[30:33]
	v_mfma_f32_16x16x32_bf16 v[22:25], v[154:157], v[194:197], v[22:25]
	v_mfma_f32_16x16x32_bf16 v[22:25], v[158:161], v[198:201], v[22:25]
	v_mfma_f32_16x16x32_bf16 v[14:17], v[146:149], v[202:205], v[14:17]
	v_mfma_f32_16x16x32_bf16 v[14:17], v[150:153], v[206:209], v[14:17]
	v_mfma_f32_16x16x32_bf16 v[6:9], v[154:157], v[202:205], v[6:9]
	v_mfma_f32_16x16x32_bf16 v[6:9], v[158:161], v[206:209], v[6:9]
	v_mfma_f32_16x16x32_bf16 v[58:61], v[162:165], v[178:181], v[58:61]
	v_mfma_f32_16x16x32_bf16 v[58:61], v[166:169], v[182:185], v[58:61]
	v_mfma_f32_16x16x32_bf16 v[50:53], v[170:173], v[178:181], v[50:53]
	v_mfma_f32_16x16x32_bf16 v[50:53], v[174:177], v[182:185], v[50:53]
	v_mfma_f32_16x16x32_bf16 v[42:45], v[162:165], v[186:189], v[42:45]
	v_mfma_f32_16x16x32_bf16 v[42:45], v[166:169], v[190:193], v[42:45]
	v_mfma_f32_16x16x32_bf16 v[34:37], v[170:173], v[186:189], v[34:37]
	v_mfma_f32_16x16x32_bf16 v[34:37], v[174:177], v[190:193], v[34:37]
	v_mfma_f32_16x16x32_bf16 v[26:29], v[162:165], v[194:197], v[26:29]
	v_mfma_f32_16x16x32_bf16 v[26:29], v[166:169], v[198:201], v[26:29]
	v_mfma_f32_16x16x32_bf16 v[18:21], v[170:173], v[194:197], v[18:21]
	v_mfma_f32_16x16x32_bf16 v[18:21], v[174:177], v[198:201], v[18:21]
	s_barrier
	v_mfma_f32_16x16x32_bf16 v[10:13], v[162:165], v[202:205], v[10:13]
	v_mfma_f32_16x16x32_bf16 v[10:13], v[166:169], v[206:209], v[10:13]
	v_mfma_f32_16x16x32_bf16 v[2:5], v[170:173], v[202:205], v[2:5]
	v_mfma_f32_16x16x32_bf16 v[2:5], v[174:177], v[206:209], v[2:5]
	s_setprio 0
	ds_read_b128 v[146:149], v141
	ds_read_b128 v[150:153], v141 offset:1024
	ds_read_b128 v[154:157], v141 offset:2048
	ds_read_b128 v[158:161], v141 offset:3072
	ds_read_b128 v[162:165], v142
	ds_read_b128 v[166:169], v142 offset:1024
	ds_read_b128 v[170:173], v142 offset:2048
	ds_read_b128 v[174:177], v142 offset:3072
	s_mov_b32 m0, s52
	s_add_i32 s81, s78, 0x100000
	ds_read_b128 v[178:181], v140 offset:32768
	ds_read_b128 v[182:185], v140 offset:33792
	ds_read_b128 v[186:189], v140 offset:34816
	ds_read_b128 v[190:193], v140 offset:35840
	ds_read_b128 v[194:197], v140 offset:36864
	ds_read_b128 v[198:201], v140 offset:37888
	ds_read_b128 v[202:205], v140 offset:38912
	ds_read_b128 v[206:209], v140 offset:39936
	buffer_load_dwordx4 v136, s[16:19], s81 offen lds
	s_add_i32 s81, s78, 0x180000
	s_mov_b32 m0, s53
	s_nop 0
	buffer_load_dwordx4 v136, s[16:19], s81 offen lds
	s_waitcnt vmcnt(8)
	s_waitcnt lgkmcnt(0)
	s_setprio 1
	v_mfma_f32_16x16x32_bf16 v[118:121], v[146:149], v[178:181], v[118:121]
	s_barrier
	v_mfma_f32_16x16x32_bf16 v[118:121], v[150:153], v[182:185], v[118:121]
	v_mfma_f32_16x16x32_bf16 v[114:117], v[154:157], v[178:181], v[114:117]
	v_mfma_f32_16x16x32_bf16 v[114:117], v[158:161], v[182:185], v[114:117]
	v_mfma_f32_16x16x32_bf16 v[110:113], v[146:149], v[186:189], v[110:113]
	v_mfma_f32_16x16x32_bf16 v[110:113], v[150:153], v[190:193], v[110:113]
	v_mfma_f32_16x16x32_bf16 v[102:105], v[154:157], v[186:189], v[102:105]
	v_mfma_f32_16x16x32_bf16 v[102:105], v[158:161], v[190:193], v[102:105]
	v_mfma_f32_16x16x32_bf16 v[94:97], v[146:149], v[194:197], v[94:97]
	v_mfma_f32_16x16x32_bf16 v[94:97], v[150:153], v[198:201], v[94:97]
	v_mfma_f32_16x16x32_bf16 v[86:89], v[154:157], v[194:197], v[86:89]
	v_mfma_f32_16x16x32_bf16 v[86:89], v[158:161], v[198:201], v[86:89]
	v_mfma_f32_16x16x32_bf16 v[78:81], v[146:149], v[202:205], v[78:81]
	v_mfma_f32_16x16x32_bf16 v[78:81], v[150:153], v[206:209], v[78:81]
	v_mfma_f32_16x16x32_bf16 v[66:69], v[154:157], v[202:205], v[66:69]
	v_mfma_f32_16x16x32_bf16 v[66:69], v[158:161], v[206:209], v[66:69]
	v_mfma_f32_16x16x32_bf16 v[126:129], v[162:165], v[178:181], v[126:129]
	v_mfma_f32_16x16x32_bf16 v[126:129], v[166:169], v[182:185], v[126:129]
	v_mfma_f32_16x16x32_bf16 v[122:125], v[170:173], v[178:181], v[122:125]
	v_mfma_f32_16x16x32_bf16 v[122:125], v[174:177], v[182:185], v[122:125]
	v_mfma_f32_16x16x32_bf16 v[106:109], v[162:165], v[186:189], v[106:109]
	v_mfma_f32_16x16x32_bf16 v[106:109], v[166:169], v[190:193], v[106:109]
	v_mfma_f32_16x16x32_bf16 v[98:101], v[170:173], v[186:189], v[98:101]
	v_mfma_f32_16x16x32_bf16 v[98:101], v[174:177], v[190:193], v[98:101]
	v_mfma_f32_16x16x32_bf16 v[90:93], v[162:165], v[194:197], v[90:93]
	v_mfma_f32_16x16x32_bf16 v[90:93], v[166:169], v[198:201], v[90:93]
	v_mfma_f32_16x16x32_bf16 v[82:85], v[170:173], v[194:197], v[82:85]
	v_mfma_f32_16x16x32_bf16 v[82:85], v[174:177], v[198:201], v[82:85]
	s_barrier
	v_mfma_f32_16x16x32_bf16 v[74:77], v[162:165], v[202:205], v[74:77]
	v_mfma_f32_16x16x32_bf16 v[74:77], v[166:169], v[206:209], v[74:77]
	v_mfma_f32_16x16x32_bf16 v[70:73], v[170:173], v[202:205], v[70:73]
	v_mfma_f32_16x16x32_bf16 v[70:73], v[174:177], v[206:209], v[70:73]
	s_setprio 0
	s_mov_b32 m0, s54
	s_or_b32 s81, s80, 0x80
	ds_read_b128 v[178:181], v140 offset:49152
	ds_read_b128 v[182:185], v140 offset:50176
	ds_read_b128 v[186:189], v140 offset:51200
	ds_read_b128 v[190:193], v140 offset:52224
	ds_read_b128 v[194:197], v140 offset:53248
	ds_read_b128 v[198:201], v140 offset:54272
	ds_read_b128 v[202:205], v140 offset:55296
	ds_read_b128 v[206:209], v140 offset:56320
	buffer_load_dwordx4 v137, s[20:23], s81 offen lds
	s_add_i32 s81, s80, 0x80080
	s_mov_b32 m0, s55
	s_add_i32 s78, s78, 0x80080
	buffer_load_dwordx4 v137, s[20:23], s81 offen lds
	s_add_i32 s81, s80, 0x100080
	s_mov_b32 m0, s58
	s_add_i32 s80, s80, 0x180080
	buffer_load_dwordx4 v137, s[20:23], s81 offen lds
	s_mov_b32 m0, s59
	s_nop 0
	buffer_load_dwordx4 v137, s[20:23], s80 offen lds
	s_mov_b32 m0, s56
	s_nop 0
	buffer_load_dwordx4 v136, s[16:19], s79 offen lds
	s_mov_b32 m0, s57
	s_nop 0
	buffer_load_dwordx4 v136, s[16:19], s78 offen lds
	s_waitcnt vmcnt(8)
	s_waitcnt lgkmcnt(0)
	s_setprio 1
	v_mfma_f32_16x16x32_bf16 v[62:65], v[146:149], v[178:181], v[62:65]
	s_barrier
	v_mfma_f32_16x16x32_bf16 v[62:65], v[150:153], v[182:185], v[62:65]
	v_mfma_f32_16x16x32_bf16 v[54:57], v[154:157], v[178:181], v[54:57]
	v_mfma_f32_16x16x32_bf16 v[54:57], v[158:161], v[182:185], v[54:57]
	v_mfma_f32_16x16x32_bf16 v[46:49], v[146:149], v[186:189], v[46:49]
	v_mfma_f32_16x16x32_bf16 v[46:49], v[150:153], v[190:193], v[46:49]
	v_mfma_f32_16x16x32_bf16 v[38:41], v[154:157], v[186:189], v[38:41]
	v_mfma_f32_16x16x32_bf16 v[38:41], v[158:161], v[190:193], v[38:41]
	v_mfma_f32_16x16x32_bf16 v[30:33], v[146:149], v[194:197], v[30:33]
	v_mfma_f32_16x16x32_bf16 v[30:33], v[150:153], v[198:201], v[30:33]
	v_mfma_f32_16x16x32_bf16 v[22:25], v[154:157], v[194:197], v[22:25]
	v_mfma_f32_16x16x32_bf16 v[22:25], v[158:161], v[198:201], v[22:25]
	v_mfma_f32_16x16x32_bf16 v[14:17], v[146:149], v[202:205], v[14:17]
	v_mfma_f32_16x16x32_bf16 v[14:17], v[150:153], v[206:209], v[14:17]
	v_mfma_f32_16x16x32_bf16 v[6:9], v[154:157], v[202:205], v[6:9]
	v_mfma_f32_16x16x32_bf16 v[6:9], v[158:161], v[206:209], v[6:9]
	v_mfma_f32_16x16x32_bf16 v[58:61], v[162:165], v[178:181], v[58:61]
	v_mfma_f32_16x16x32_bf16 v[58:61], v[166:169], v[182:185], v[58:61]
	v_mfma_f32_16x16x32_bf16 v[50:53], v[170:173], v[178:181], v[50:53]
	v_mfma_f32_16x16x32_bf16 v[50:53], v[174:177], v[182:185], v[50:53]
	v_mfma_f32_16x16x32_bf16 v[42:45], v[162:165], v[186:189], v[42:45]
	v_mfma_f32_16x16x32_bf16 v[42:45], v[166:169], v[190:193], v[42:45]
	v_mfma_f32_16x16x32_bf16 v[34:37], v[170:173], v[186:189], v[34:37]
	v_mfma_f32_16x16x32_bf16 v[34:37], v[174:177], v[190:193], v[34:37]
	v_mfma_f32_16x16x32_bf16 v[26:29], v[162:165], v[194:197], v[26:29]
	v_mfma_f32_16x16x32_bf16 v[26:29], v[166:169], v[198:201], v[26:29]
	v_mfma_f32_16x16x32_bf16 v[18:21], v[170:173], v[194:197], v[18:21]
	v_mfma_f32_16x16x32_bf16 v[18:21], v[174:177], v[198:201], v[18:21]
	s_barrier
	v_mfma_f32_16x16x32_bf16 v[10:13], v[162:165], v[202:205], v[10:13]
	v_mfma_f32_16x16x32_bf16 v[10:13], v[166:169], v[206:209], v[10:13]
	v_mfma_f32_16x16x32_bf16 v[2:5], v[170:173], v[202:205], v[2:5]
	v_mfma_f32_16x16x32_bf16 v[2:5], v[174:177], v[206:209], v[2:5]
	s_setprio 0
	s_add_i32 s77, s77, 2
	s_addk_i32 s75, 0x100
	s_addk_i32 s76, 0x100
	s_cmp_ge_i32 s77, s13
	s_cbranch_scc0 .LBB0_1402
	s_and_b64 vcc, exec, s[46:47]
	s_cbranch_vccz .LBB0_1405

.LBB0_1519:
	ds_read_b128 v[134:137], v208
	ds_read_b128 v[138:141], v208 offset:1024
	ds_read_b128 v[142:145], v208 offset:2048
	ds_read_b128 v[146:149], v208 offset:3072
	ds_read_b128 v[150:153], v209
	ds_read_b128 v[154:157], v209 offset:1024
	ds_read_b128 v[158:161], v209 offset:2048
	ds_read_b128 v[162:165], v209 offset:3072
	s_add_i32 s18, s80, 0xffbf8080
	s_cmp_eq_u32 s65, s82
	s_cselect_b32 s83, s6, s18
	s_cselect_b32 s85, s7, s81
	s_or_b32 s84, s83, 0x80
	s_add_i32 s18, s80, 0xffea8000
	s_mov_b32 m0, s66
	ds_read_b128 v[166:169], v210
	ds_read_b128 v[170:173], v210 offset:1024
	ds_read_b128 v[174:177], v210 offset:2048
	ds_read_b128 v[178:181], v210 offset:3072
	ds_read_b128 v[182:185], v210 offset:4096
	ds_read_b128 v[186:189], v210 offset:5120
	ds_read_b128 v[190:193], v210 offset:6144
	ds_read_b128 v[194:197], v210 offset:7168
	buffer_load_dwordx4 v206, s[12:15], s18 offen lds
	s_mov_b32 m0, s69
	s_nop 0
	buffer_load_dwordx4 v206, s[12:15], s80 offen lds
	s_waitcnt vmcnt(8)
	s_waitcnt lgkmcnt(0)
	s_setprio 1
	v_mfma_f32_16x16x32_bf16 v[126:129], v[134:137], v[166:169], v[126:129]
	s_barrier
	v_mfma_f32_16x16x32_bf16 v[126:129], v[138:141], v[170:173], v[126:129]
	v_mfma_f32_16x16x32_bf16 v[122:125], v[142:145], v[166:169], v[122:125]
	v_mfma_f32_16x16x32_bf16 v[122:125], v[146:149], v[170:173], v[122:125]
	v_mfma_f32_16x16x32_bf16 v[118:121], v[134:137], v[174:177], v[118:121]
	v_mfma_f32_16x16x32_bf16 v[118:121], v[138:141], v[178:181], v[118:121]
	v_mfma_f32_16x16x32_bf16 v[114:117], v[142:145], v[174:177], v[114:117]
	v_mfma_f32_16x16x32_bf16 v[114:117], v[146:149], v[178:181], v[114:117]
	v_mfma_f32_16x16x32_bf16 v[106:109], v[134:137], v[182:185], v[106:109]
	v_mfma_f32_16x16x32_bf16 v[106:109], v[138:141], v[186:189], v[106:109]
	v_mfma_f32_16x16x32_bf16 v[98:101], v[142:145], v[182:185], v[98:101]
	v_mfma_f32_16x16x32_bf16 v[98:101], v[146:149], v[186:189], v[98:101]
	v_mfma_f32_16x16x32_bf16 v[90:93], v[134:137], v[190:193], v[90:93]
	v_mfma_f32_16x16x32_bf16 v[90:93], v[138:141], v[194:197], v[90:93]
	v_mfma_f32_16x16x32_bf16 v[82:85], v[142:145], v[190:193], v[82:85]
	v_mfma_f32_16x16x32_bf16 v[82:85], v[146:149], v[194:197], v[82:85]
	v_mfma_f32_16x16x32_bf16 v[110:113], v[150:153], v[166:169], v[110:113]
	v_mfma_f32_16x16x32_bf16 v[110:113], v[154:157], v[170:173], v[110:113]
	v_mfma_f32_16x16x32_bf16 v[102:105], v[158:161], v[166:169], v[102:105]
	v_mfma_f32_16x16x32_bf16 v[102:105], v[162:165], v[170:173], v[102:105]
	v_mfma_f32_16x16x32_bf16 v[94:97], v[150:153], v[174:177], v[94:97]
	v_mfma_f32_16x16x32_bf16 v[94:97], v[154:157], v[178:181], v[94:97]
	v_mfma_f32_16x16x32_bf16 v[86:89], v[158:161], v[174:177], v[86:89]
	v_mfma_f32_16x16x32_bf16 v[86:89], v[162:165], v[178:181], v[86:89]
	v_mfma_f32_16x16x32_bf16 v[78:81], v[150:153], v[182:185], v[78:81]
	v_mfma_f32_16x16x32_bf16 v[78:81], v[154:157], v[186:189], v[78:81]
	v_mfma_f32_16x16x32_bf16 v[74:77], v[158:161], v[182:185], v[74:77]
	v_mfma_f32_16x16x32_bf16 v[74:77], v[162:165], v[186:189], v[74:77]
	s_barrier
	v_mfma_f32_16x16x32_bf16 v[70:73], v[150:153], v[190:193], v[70:73]
	v_mfma_f32_16x16x32_bf16 v[70:73], v[154:157], v[194:197], v[70:73]
	v_mfma_f32_16x16x32_bf16 v[66:69], v[158:161], v[190:193], v[66:69]
	v_mfma_f32_16x16x32_bf16 v[66:69], v[162:165], v[194:197], v[66:69]
	s_setprio 0
	s_mov_b32 m0, s27
	s_mov_b32 s18, s14
	s_mov_b32 s19, s15
	ds_read_b128 v[166:169], v210 offset:16384
	ds_read_b128 v[170:173], v210 offset:17408
	ds_read_b128 v[174:177], v210 offset:18432
	ds_read_b128 v[178:181], v210 offset:19456
	ds_read_b128 v[182:185], v210 offset:20480
	ds_read_b128 v[186:189], v210 offset:21504
	ds_read_b128 v[190:193], v210 offset:22528
	ds_read_b128 v[194:197], v210 offset:23552
	buffer_load_dwordx4 v207, s[16:19], s85 offen lds
	s_add_i32 s86, s85, 0x158000
	s_mov_b32 m0, s30
	s_nop 0
	buffer_load_dwordx4 v207, s[16:19], s86 offen lds
	s_add_i32 s86, s85, 0x2b0000
	s_mov_b32 m0, s31
	s_nop 0
	buffer_load_dwordx4 v207, s[16:19], s86 offen lds
	s_add_i32 s86, s85, 0x408000
	s_mov_b32 m0, s50
	s_nop 0
	buffer_load_dwordx4 v207, s[16:19], s86 offen lds
	s_mov_b32 m0, s25
	s_add_i32 s86, s83, 0x158000
	buffer_load_dwordx4 v206, s[12:15], s83 offen lds
	s_mov_b32 m0, s51
	s_nop 0
	buffer_load_dwordx4 v206, s[12:15], s86 offen lds
	s_waitcnt vmcnt(8)
	s_waitcnt lgkmcnt(0)
	s_setprio 1
	v_mfma_f32_16x16x32_bf16 v[62:65], v[134:137], v[166:169], v[62:65]
	s_barrier
	v_mfma_f32_16x16x32_bf16 v[62:65], v[138:141], v[170:173], v[62:65]
	v_mfma_f32_16x16x32_bf16 v[58:61], v[142:145], v[166:169], v[58:61]
	v_mfma_f32_16x16x32_bf16 v[58:61], v[146:149], v[170:173], v[58:61]
	v_mfma_f32_16x16x32_bf16 v[54:57], v[134:137], v[174:177], v[54:57]
	v_mfma_f32_16x16x32_bf16 v[54:57], v[138:141], v[178:181], v[54:57]
	v_mfma_f32_16x16x32_bf16 v[50:53], v[142:145], v[174:177], v[50:53]
	v_mfma_f32_16x16x32_bf16 v[50:53], v[146:149], v[178:181], v[50:53]
	v_mfma_f32_16x16x32_bf16 v[42:45], v[134:137], v[182:185], v[42:45]
	v_mfma_f32_16x16x32_bf16 v[42:45], v[138:141], v[186:189], v[42:45]
	v_mfma_f32_16x16x32_bf16 v[34:37], v[142:145], v[182:185], v[34:37]
	v_mfma_f32_16x16x32_bf16 v[34:37], v[146:149], v[186:189], v[34:37]
	v_mfma_f32_16x16x32_bf16 v[26:29], v[134:137], v[190:193], v[26:29]
	v_mfma_f32_16x16x32_bf16 v[26:29], v[138:141], v[194:197], v[26:29]
	v_mfma_f32_16x16x32_bf16 v[18:21], v[142:145], v[190:193], v[18:21]
	v_mfma_f32_16x16x32_bf16 v[18:21], v[146:149], v[194:197], v[18:21]
	v_mfma_f32_16x16x32_bf16 v[46:49], v[150:153], v[166:169], v[46:49]
	v_mfma_f32_16x16x32_bf16 v[46:49], v[154:157], v[170:173], v[46:49]
	v_mfma_f32_16x16x32_bf16 v[38:41], v[158:161], v[166:169], v[38:41]
	v_mfma_f32_16x16x32_bf16 v[38:41], v[162:165], v[170:173], v[38:41]
	v_mfma_f32_16x16x32_bf16 v[30:33], v[150:153], v[174:177], v[30:33]
	v_mfma_f32_16x16x32_bf16 v[30:33], v[154:157], v[178:181], v[30:33]
	v_mfma_f32_16x16x32_bf16 v[22:25], v[158:161], v[174:177], v[22:25]
	v_mfma_f32_16x16x32_bf16 v[22:25], v[162:165], v[178:181], v[22:25]
	v_mfma_f32_16x16x32_bf16 v[14:17], v[150:153], v[182:185], v[14:17]
	v_mfma_f32_16x16x32_bf16 v[14:17], v[154:157], v[186:189], v[14:17]
	v_mfma_f32_16x16x32_bf16 v[10:13], v[158:161], v[182:185], v[10:13]
	v_mfma_f32_16x16x32_bf16 v[10:13], v[162:165], v[186:189], v[10:13]
	s_barrier
	v_mfma_f32_16x16x32_bf16 v[6:9], v[150:153], v[190:193], v[6:9]
	v_mfma_f32_16x16x32_bf16 v[6:9], v[154:157], v[194:197], v[6:9]
	v_mfma_f32_16x16x32_bf16 v[2:5], v[158:161], v[190:193], v[2:5]
	v_mfma_f32_16x16x32_bf16 v[2:5], v[162:165], v[194:197], v[2:5]
	s_setprio 0
	ds_read_b128 v[134:137], v211
	ds_read_b128 v[138:141], v211 offset:1024
	ds_read_b128 v[142:145], v211 offset:2048
	ds_read_b128 v[146:149], v211 offset:3072
	ds_read_b128 v[150:153], v212
	ds_read_b128 v[154:157], v212 offset:1024
	ds_read_b128 v[158:161], v212 offset:2048
	ds_read_b128 v[162:165], v212 offset:3072
	s_mov_b32 m0, s52
	s_add_i32 s86, s83, 0x2b0000
	ds_read_b128 v[166:169], v210 offset:32768
	ds_read_b128 v[170:173], v210 offset:33792
	ds_read_b128 v[174:177], v210 offset:34816
	ds_read_b128 v[178:181], v210 offset:35840
	ds_read_b128 v[182:185], v210 offset:36864
	ds_read_b128 v[186:189], v210 offset:37888
	ds_read_b128 v[190:193], v210 offset:38912
	ds_read_b128 v[194:197], v210 offset:39936
	buffer_load_dwordx4 v206, s[12:15], s86 offen lds
	s_add_i32 s86, s83, 0x408000
	s_mov_b32 m0, s53
	s_nop 0
	buffer_load_dwordx4 v206, s[12:15], s86 offen lds
	s_waitcnt vmcnt(8)
	s_waitcnt lgkmcnt(0)
	s_setprio 1
	v_mfma_f32_16x16x32_bf16 v[126:129], v[134:137], v[166:169], v[126:129]
	s_barrier
	v_mfma_f32_16x16x32_bf16 v[126:129], v[138:141], v[170:173], v[126:129]
	v_mfma_f32_16x16x32_bf16 v[122:125], v[142:145], v[166:169], v[122:125]
	v_mfma_f32_16x16x32_bf16 v[122:125], v[146:149], v[170:173], v[122:125]
	v_mfma_f32_16x16x32_bf16 v[118:121], v[134:137], v[174:177], v[118:121]
	v_mfma_f32_16x16x32_bf16 v[118:121], v[138:141], v[178:181], v[118:121]
	v_mfma_f32_16x16x32_bf16 v[114:117], v[142:145], v[174:177], v[114:117]
	v_mfma_f32_16x16x32_bf16 v[114:117], v[146:149], v[178:181], v[114:117]
	v_mfma_f32_16x16x32_bf16 v[106:109], v[134:137], v[182:185], v[106:109]
	v_mfma_f32_16x16x32_bf16 v[106:109], v[138:141], v[186:189], v[106:109]
	v_mfma_f32_16x16x32_bf16 v[98:101], v[142:145], v[182:185], v[98:101]
	v_mfma_f32_16x16x32_bf16 v[98:101], v[146:149], v[186:189], v[98:101]
	v_mfma_f32_16x16x32_bf16 v[90:93], v[134:137], v[190:193], v[90:93]
	v_mfma_f32_16x16x32_bf16 v[90:93], v[138:141], v[194:197], v[90:93]
	v_mfma_f32_16x16x32_bf16 v[82:85], v[142:145], v[190:193], v[82:85]
	v_mfma_f32_16x16x32_bf16 v[82:85], v[146:149], v[194:197], v[82:85]
	v_mfma_f32_16x16x32_bf16 v[110:113], v[150:153], v[166:169], v[110:113]
	v_mfma_f32_16x16x32_bf16 v[110:113], v[154:157], v[170:173], v[110:113]
	v_mfma_f32_16x16x32_bf16 v[102:105], v[158:161], v[166:169], v[102:105]
	v_mfma_f32_16x16x32_bf16 v[102:105], v[162:165], v[170:173], v[102:105]
	v_mfma_f32_16x16x32_bf16 v[94:97], v[150:153], v[174:177], v[94:97]
	v_mfma_f32_16x16x32_bf16 v[94:97], v[154:157], v[178:181], v[94:97]
	v_mfma_f32_16x16x32_bf16 v[86:89], v[158:161], v[174:177], v[86:89]
	v_mfma_f32_16x16x32_bf16 v[86:89], v[162:165], v[178:181], v[86:89]
	v_mfma_f32_16x16x32_bf16 v[78:81], v[150:153], v[182:185], v[78:81]
	v_mfma_f32_16x16x32_bf16 v[78:81], v[154:157], v[186:189], v[78:81]
	v_mfma_f32_16x16x32_bf16 v[74:77], v[158:161], v[182:185], v[74:77]
	v_mfma_f32_16x16x32_bf16 v[74:77], v[162:165], v[186:189], v[74:77]
	s_barrier
	v_mfma_f32_16x16x32_bf16 v[70:73], v[150:153], v[190:193], v[70:73]
	v_mfma_f32_16x16x32_bf16 v[70:73], v[154:157], v[194:197], v[70:73]
	v_mfma_f32_16x16x32_bf16 v[66:69], v[158:161], v[190:193], v[66:69]
	v_mfma_f32_16x16x32_bf16 v[66:69], v[162:165], v[194:197], v[66:69]
	s_setprio 0
	s_mov_b32 m0, s57
	s_or_b32 s86, s85, 0x80
	ds_read_b128 v[166:169], v210 offset:49152
	ds_read_b128 v[170:173], v210 offset:50176
	ds_read_b128 v[174:177], v210 offset:51200
	ds_read_b128 v[178:181], v210 offset:52224
	ds_read_b128 v[182:185], v210 offset:53248
	ds_read_b128 v[186:189], v210 offset:54272
	ds_read_b128 v[190:193], v210 offset:55296
	ds_read_b128 v[194:197], v210 offset:56320
	buffer_load_dwordx4 v207, s[16:19], s86 offen lds
	s_add_i32 s86, s85, 0x158080
	s_mov_b32 m0, s58
	s_add_i32 s83, s83, 0x158080
	buffer_load_dwordx4 v207, s[16:19], s86 offen lds
	s_add_i32 s86, s85, 0x2b0080
	s_mov_b32 m0, s61
	s_add_i32 s85, s85, 0x408080
	buffer_load_dwordx4 v207, s[16:19], s86 offen lds
	s_mov_b32 m0, s62
	s_nop 0
	buffer_load_dwordx4 v207, s[16:19], s85 offen lds
	s_mov_b32 m0, s59
	s_nop 0
	buffer_load_dwordx4 v206, s[12:15], s84 offen lds
	s_mov_b32 m0, s60
	s_nop 0
	buffer_load_dwordx4 v206, s[12:15], s83 offen lds
	s_waitcnt vmcnt(8)
	s_waitcnt lgkmcnt(0)
	s_setprio 1
	v_mfma_f32_16x16x32_bf16 v[62:65], v[134:137], v[166:169], v[62:65]
	s_barrier
	v_mfma_f32_16x16x32_bf16 v[62:65], v[138:141], v[170:173], v[62:65]
	v_mfma_f32_16x16x32_bf16 v[58:61], v[142:145], v[166:169], v[58:61]
	v_mfma_f32_16x16x32_bf16 v[58:61], v[146:149], v[170:173], v[58:61]
	v_mfma_f32_16x16x32_bf16 v[54:57], v[134:137], v[174:177], v[54:57]
	v_mfma_f32_16x16x32_bf16 v[54:57], v[138:141], v[178:181], v[54:57]
	v_mfma_f32_16x16x32_bf16 v[50:53], v[142:145], v[174:177], v[50:53]
	v_mfma_f32_16x16x32_bf16 v[50:53], v[146:149], v[178:181], v[50:53]
	v_mfma_f32_16x16x32_bf16 v[42:45], v[134:137], v[182:185], v[42:45]
	v_mfma_f32_16x16x32_bf16 v[42:45], v[138:141], v[186:189], v[42:45]
	v_mfma_f32_16x16x32_bf16 v[34:37], v[142:145], v[182:185], v[34:37]
	v_mfma_f32_16x16x32_bf16 v[34:37], v[146:149], v[186:189], v[34:37]
	v_mfma_f32_16x16x32_bf16 v[26:29], v[134:137], v[190:193], v[26:29]
	v_mfma_f32_16x16x32_bf16 v[26:29], v[138:141], v[194:197], v[26:29]
	v_mfma_f32_16x16x32_bf16 v[18:21], v[142:145], v[190:193], v[18:21]
	v_mfma_f32_16x16x32_bf16 v[18:21], v[146:149], v[194:197], v[18:21]
	v_mfma_f32_16x16x32_bf16 v[46:49], v[150:153], v[166:169], v[46:49]
	v_mfma_f32_16x16x32_bf16 v[46:49], v[154:157], v[170:173], v[46:49]
	v_mfma_f32_16x16x32_bf16 v[38:41], v[158:161], v[166:169], v[38:41]
	v_mfma_f32_16x16x32_bf16 v[38:41], v[162:165], v[170:173], v[38:41]
	v_mfma_f32_16x16x32_bf16 v[30:33], v[150:153], v[174:177], v[30:33]
	v_mfma_f32_16x16x32_bf16 v[30:33], v[154:157], v[178:181], v[30:33]
	v_mfma_f32_16x16x32_bf16 v[22:25], v[158:161], v[174:177], v[22:25]
	v_mfma_f32_16x16x32_bf16 v[22:25], v[162:165], v[178:181], v[22:25]
	v_mfma_f32_16x16x32_bf16 v[14:17], v[150:153], v[182:185], v[14:17]
	v_mfma_f32_16x16x32_bf16 v[14:17], v[154:157], v[186:189], v[14:17]
	v_mfma_f32_16x16x32_bf16 v[10:13], v[158:161], v[182:185], v[10:13]
	v_mfma_f32_16x16x32_bf16 v[10:13], v[162:165], v[186:189], v[10:13]
	s_barrier
	v_mfma_f32_16x16x32_bf16 v[6:9], v[150:153], v[190:193], v[6:9]
	v_mfma_f32_16x16x32_bf16 v[6:9], v[154:157], v[194:197], v[6:9]
	v_mfma_f32_16x16x32_bf16 v[2:5], v[158:161], v[190:193], v[2:5]
	v_mfma_f32_16x16x32_bf16 v[2:5], v[162:165], v[194:197], v[2:5]
	s_setprio 0
	s_add_i32 s82, s82, 2
	s_addk_i32 s80, 0x100
	s_addk_i32 s81, 0x100
	s_cmp_ge_i32 s82, s3
	s_cbranch_scc0 .LBB0_1519
	v_pk_mul_f32 v[182:183], v[128:129], 0.5 op_sel_hi:[1,0]
	v_pk_mul_f32 v[184:185], v[126:127], 0.5 op_sel_hi:[1,0]
	v_pk_mul_f32 v[186:187], v[124:125], 0.5 op_sel_hi:[1,0]
	v_pk_mul_f32 v[188:189], v[122:123], 0.5 op_sel_hi:[1,0]
	v_pk_mul_f32 v[196:197], v[112:113], 0.5 op_sel_hi:[1,0]
	v_pk_mul_f32 v[194:195], v[110:111], 0.5 op_sel_hi:[1,0]
	v_pk_mul_f32 v[192:193], v[104:105], 0.5 op_sel_hi:[1,0]
	v_pk_mul_f32 v[190:191], v[102:103], 0.5 op_sel_hi:[1,0]
	v_pk_mul_f32 v[180:181], v[120:121], 0.5 op_sel_hi:[1,0]
	v_pk_mul_f32 v[178:179], v[118:119], 0.5 op_sel_hi:[1,0]
	v_pk_mul_f32 v[176:177], v[116:117], 0.5 op_sel_hi:[1,0]
	v_pk_mul_f32 v[174:175], v[114:115], 0.5 op_sel_hi:[1,0]
	v_pk_mul_f32 v[170:171], v[96:97], 0.5 op_sel_hi:[1,0]
	v_pk_mul_f32 v[168:169], v[94:95], 0.5 op_sel_hi:[1,0]
	v_pk_mul_f32 v[166:167], v[88:89], 0.5 op_sel_hi:[1,0]
	v_pk_mul_f32 v[164:165], v[86:87], 0.5 op_sel_hi:[1,0]
	v_pk_mul_f32 v[162:163], v[108:109], 0.5 op_sel_hi:[1,0]
	v_pk_mul_f32 v[160:161], v[106:107], 0.5 op_sel_hi:[1,0]
	v_pk_mul_f32 v[158:159], v[100:101], 0.5 op_sel_hi:[1,0]
	v_pk_mul_f32 v[156:157], v[98:99], 0.5 op_sel_hi:[1,0]
	v_pk_mul_f32 v[154:155], v[80:81], 0.5 op_sel_hi:[1,0]
	v_pk_mul_f32 v[152:153], v[78:79], 0.5 op_sel_hi:[1,0]
	v_pk_mul_f32 v[150:151], v[76:77], 0.5 op_sel_hi:[1,0]
	v_pk_mul_f32 v[148:149], v[74:75], 0.5 op_sel_hi:[1,0]
	v_pk_mul_f32 v[144:145], v[92:93], 0.5 op_sel_hi:[1,0]
	v_pk_mul_f32 v[142:143], v[90:91], 0.5 op_sel_hi:[1,0]
	v_pk_mul_f32 v[140:141], v[84:85], 0.5 op_sel_hi:[1,0]
	v_pk_mul_f32 v[138:139], v[82:83], 0.5 op_sel_hi:[1,0]
	v_pk_mul_f32 v[136:137], v[72:73], 0.5 op_sel_hi:[1,0]
	v_pk_mul_f32 v[134:135], v[70:71], 0.5 op_sel_hi:[1,0]
	v_pk_mul_f32 v[128:129], v[68:69], 0.5 op_sel_hi:[1,0]
	v_pk_mul_f32 v[126:127], v[66:67], 0.5 op_sel_hi:[1,0]
	v_pk_mul_f32 v[122:123], v[64:65], 0.5 op_sel_hi:[1,0]
	v_pk_mul_f32 v[120:121], v[62:63], 0.5 op_sel_hi:[1,0]
	v_pk_mul_f32 v[118:119], v[60:61], 0.5 op_sel_hi:[1,0]
	v_pk_mul_f32 v[116:117], v[58:59], 0.5 op_sel_hi:[1,0]
	v_pk_mul_f32 v[112:113], v[48:49], 0.5 op_sel_hi:[1,0]
	v_pk_mul_f32 v[110:111], v[46:47], 0.5 op_sel_hi:[1,0]
	v_pk_mul_f32 v[108:109], v[40:41], 0.5 op_sel_hi:[1,0]
	v_pk_mul_f32 v[106:107], v[38:39], 0.5 op_sel_hi:[1,0]
	v_pk_mul_f32 v[104:105], v[56:57], 0.5 op_sel_hi:[1,0]
	v_pk_mul_f32 v[102:103], v[54:55], 0.5 op_sel_hi:[1,0]
	v_pk_mul_f32 v[100:101], v[52:53], 0.5 op_sel_hi:[1,0]
	v_pk_mul_f32 v[98:99], v[50:51], 0.5 op_sel_hi:[1,0]
	v_pk_mul_f32 v[96:97], v[32:33], 0.5 op_sel_hi:[1,0]
	v_pk_mul_f32 v[94:95], v[30:31], 0.5 op_sel_hi:[1,0]
	v_pk_mul_f32 v[92:93], v[24:25], 0.5 op_sel_hi:[1,0]
	v_pk_mul_f32 v[90:91], v[22:23], 0.5 op_sel_hi:[1,0]
	v_pk_mul_f32 v[88:89], v[44:45], 0.5 op_sel_hi:[1,0]
	v_pk_mul_f32 v[86:87], v[42:43], 0.5 op_sel_hi:[1,0]
	v_pk_mul_f32 v[84:85], v[36:37], 0.5 op_sel_hi:[1,0]
	v_pk_mul_f32 v[82:83], v[34:35], 0.5 op_sel_hi:[1,0]
	v_pk_mul_f32 v[80:81], v[16:17], 0.5 op_sel_hi:[1,0]
	v_pk_mul_f32 v[78:79], v[14:15], 0.5 op_sel_hi:[1,0]
	v_pk_mul_f32 v[76:77], v[12:13], 0.5 op_sel_hi:[1,0]
	v_pk_mul_f32 v[74:75], v[10:11], 0.5 op_sel_hi:[1,0]
	v_pk_mul_f32 v[72:73], v[28:29], 0.5 op_sel_hi:[1,0]
	v_pk_mul_f32 v[70:71], v[26:27], 0.5 op_sel_hi:[1,0]
	v_pk_mul_f32 v[68:69], v[20:21], 0.5 op_sel_hi:[1,0]
	v_pk_mul_f32 v[66:67], v[18:19], 0.5 op_sel_hi:[1,0]
	v_pk_mul_f32 v[64:65], v[8:9], 0.5 op_sel_hi:[1,0]
	v_pk_mul_f32 v[62:63], v[6:7], 0.5 op_sel_hi:[1,0]
	v_pk_mul_f32 v[60:61], v[4:5], 0.5 op_sel_hi:[1,0]
	v_pk_mul_f32 v[58:59], v[2:3], 0.5 op_sel_hi:[1,0]
	s_and_b64 vcc, exec, s[40:41]
	s_cbranch_vccz .LBB0_1522
